# speedup vs baseline: 1.0207x; 1.0049x over previous
; #define WAIT_V(n) asm volatile("s_waitcnt vmcnt(" #n ")" ::: "memory")
; #define BAR __builtin_amdgcn_s_barrier()
; template <int EPI>
; __device__ __forceinline__ void phase_gemm(const Params& p, const GemmDesc& d, char* shmc) {
;     ...
; #pragma unroll
;     for (int a = 0; a < 2; ++a)
; #pragma unroll
;       for (int b = 0; b < 2; ++b)
; #pragma unroll
;         for (int m = 0; m < 4; ++m)
; #pragma unroll
;           for (int n = 0; n < 2; ++n) acc[a][b][m][n] = f32x4{0.f, 0.f, 0.f, 0.f};
;     bf16x8 At[4][2], B0[2][2], B1[2][2];
;     if constexpr (EPI == EPI_UP || EPI == EPI_QKV) {
;       if (wid == 0)
;         __builtin_amdgcn_global_load_lds((const unsigned*)(p.rstd + brow + lane * 4), (unsigned*)(shmc + 143360), 16, 0, 0);
;     }
;     STAGE_B(SB(0, 0), 0, 0); STAGE_A(SA(0, 0), 0, 0);
;     STAGE_B(SB(0, 1), 1, 0); STAGE_A(SA(0, 1), 1, 0);
;     if (wr == 1) BAR;
;     WAIT_V(4); BAR;
;     STAGE_B(SB(1, 0), 0, 1); STAGE_A(SA(1, 0), 0, 1); STAGE_B(SB(1, 1), 1, 1);
;     WAIT_V(6); BAR;
.LBB0_295:
	s_or_b64 exec, exec, s[64:65]
	v_mov_b32_e32 v175, v163
	v_lshl_add_u64 v[2:3], s[62:63], 0, v[174:175]
	v_mov_b32_e32 v177, v163
	s_mov_b32 m0, s87
	v_lshl_add_u64 v[4:5], s[62:63], 0, v[176:177]
	v_lshl_add_u64 v[2:3], v[2:3], 0, s[26:27]
	v_lshl_add_u64 v[6:7], s[8:9], 0, v[174:175]
	v_mov_b32_e32 v10, 0
	v_mov_b32_e32 v11, 0
	v_mov_b32_e32 v12, 0
	v_mov_b32_e32 v13, 0
	v_mov_b32_e32 v18, 0
	v_mov_b32_e32 v19, 0
	v_mov_b32_e32 v20, 0
	v_mov_b32_e32 v21, 0
	v_mov_b32_e32 v30, 0
	v_mov_b32_e32 v31, 0
	v_mov_b32_e32 v32, 0
	v_mov_b32_e32 v33, 0
	v_mov_b32_e32 v42, 0
	v_mov_b32_e32 v43, 0
	v_mov_b32_e32 v44, 0
	v_mov_b32_e32 v45, 0
	v_mov_b32_e32 v54, 0
	v_mov_b32_e32 v55, 0
	v_mov_b32_e32 v56, 0
	v_mov_b32_e32 v57, 0
	v_mov_b32_e32 v66, 0
	v_mov_b32_e32 v67, 0
	v_mov_b32_e32 v68, 0
	v_mov_b32_e32 v69, 0
	v_mov_b32_e32 v14, 0
	v_mov_b32_e32 v15, 0
	v_mov_b32_e32 v16, 0
	v_mov_b32_e32 v17, 0
	v_mov_b32_e32 v22, 0
	v_mov_b32_e32 v23, 0
	v_mov_b32_e32 v24, 0
	v_mov_b32_e32 v25, 0
	v_mov_b32_e32 v34, 0
	v_mov_b32_e32 v35, 0
	v_mov_b32_e32 v36, 0
	v_mov_b32_e32 v37, 0
	v_mov_b32_e32 v46, 0
	v_mov_b32_e32 v47, 0
	v_mov_b32_e32 v48, 0
	v_mov_b32_e32 v49, 0
	v_mov_b32_e32 v58, 0
	v_mov_b32_e32 v59, 0
	v_mov_b32_e32 v60, 0
	v_mov_b32_e32 v61, 0
	v_mov_b32_e32 v70, 0
	v_mov_b32_e32 v71, 0
	v_mov_b32_e32 v72, 0
	v_mov_b32_e32 v73, 0
	v_mov_b32_e32 v78, 0
	v_mov_b32_e32 v79, 0
	v_mov_b32_e32 v80, 0
	v_mov_b32_e32 v81, 0
	v_mov_b32_e32 v86, 0
	v_mov_b32_e32 v87, 0
	v_mov_b32_e32 v88, 0
	v_mov_b32_e32 v89, 0
	v_mov_b32_e32 v26, 0
	v_mov_b32_e32 v27, 0
	v_mov_b32_e32 v28, 0
	v_mov_b32_e32 v29, 0
	v_mov_b32_e32 v38, 0
	v_mov_b32_e32 v39, 0
	v_mov_b32_e32 v40, 0
	v_mov_b32_e32 v41, 0
	v_mov_b32_e32 v50, 0
	v_mov_b32_e32 v51, 0
	v_mov_b32_e32 v52, 0
	v_mov_b32_e32 v53, 0
	v_mov_b32_e32 v62, 0
	v_mov_b32_e32 v63, 0
	v_mov_b32_e32 v64, 0
	v_mov_b32_e32 v65, 0
	v_mov_b32_e32 v74, 0
	v_mov_b32_e32 v75, 0
	v_mov_b32_e32 v76, 0
	v_mov_b32_e32 v77, 0
	v_mov_b32_e32 v82, 0
	v_mov_b32_e32 v83, 0
	v_mov_b32_e32 v84, 0
	v_mov_b32_e32 v85, 0
	v_mov_b32_e32 v90, 0
	v_mov_b32_e32 v91, 0
	v_mov_b32_e32 v92, 0
	v_mov_b32_e32 v93, 0
	v_mov_b32_e32 v94, 0
	v_mov_b32_e32 v95, 0
	v_mov_b32_e32 v96, 0
	v_mov_b32_e32 v97, 0
	v_mov_b32_e32 v98, 0
	v_mov_b32_e32 v99, 0
	v_mov_b32_e32 v100, 0
	v_mov_b32_e32 v101, 0
	v_mov_b32_e32 v102, 0
	v_mov_b32_e32 v103, 0
	v_mov_b32_e32 v104, 0
	v_mov_b32_e32 v105, 0
	v_mov_b32_e32 v106, 0
	v_mov_b32_e32 v107, 0
	v_mov_b32_e32 v108, 0
	v_mov_b32_e32 v109, 0
	v_mov_b32_e32 v110, 0
	v_mov_b32_e32 v111, 0
	v_mov_b32_e32 v112, 0
	v_mov_b32_e32 v113, 0
	v_mov_b32_e32 v114, 0
	v_mov_b32_e32 v115, 0
	v_mov_b32_e32 v116, 0
	v_mov_b32_e32 v117, 0
	v_mov_b32_e32 v118, 0
	v_mov_b32_e32 v119, 0
	v_mov_b32_e32 v120, 0
	v_mov_b32_e32 v121, 0
	v_mov_b32_e32 v122, 0
	v_mov_b32_e32 v123, 0
	v_mov_b32_e32 v124, 0
	v_mov_b32_e32 v125, 0
	v_mov_b32_e32 v126, 0
	v_mov_b32_e32 v127, 0
	v_mov_b32_e32 v128, 0
	v_mov_b32_e32 v129, 0
	s_waitcnt vmcnt(2)
	s_barrier
	global_load_lds_dwordx4 v[2:3], off
	v_lshl_add_u64 v[2:3], v[4:5], 0, s[26:27]
	s_mov_b32 m0, s88
	v_lshl_add_u64 v[8:9], s[8:9], 0, v[176:177]
	global_load_lds_dwordx4 v[2:3], off
	v_lshl_add_u64 v[2:3], v[6:7], 0, s[26:27]
	s_mov_b32 m0, s89
	s_add_u32 s62, s62, 0x80080
	global_load_lds_dwordx4 v[2:3], off
	v_lshl_add_u64 v[2:3], v[8:9], 0, s[26:27]
	s_mov_b32 m0, s90
	s_addc_u32 s63, s63, 0
	global_load_lds_dwordx4 v[2:3], off
	s_mov_b32 m0, s91
	v_lshl_add_u64 v[130:131], v[166:167], 0, s[10:11]
	global_load_lds_dwordx4 v174, s[62:63]
	s_mov_b32 m0, s92
	v_lshl_add_u64 v[132:133], v[168:169], 0, s[10:11]
	global_load_lds_dwordx4 v176, s[62:63]
	s_lshl_b32 s10, s35, 11
	s_lshl_b32 s11, s68, 8
	s_or_b32 s10, s10, s11
	s_waitcnt vmcnt(6)
	s_ashr_i32 s11, s10, 31
	s_lshl_b64 s[10:11], s[10:11], 12
	v_mov_b32_e32 v2, 0
	v_lshl_add_u64 v[134:135], v[170:171], 0, s[10:11]
	v_lshl_add_u64 v[136:137], v[172:173], 0, s[10:11]
	s_mov_b32 s35, -2
	s_mov_b64 s[10:11], 0
	v_mov_b32_e32 v3, v2
	v_mov_b32_e32 v4, v2
	v_mov_b32_e32 v5, v2
	v_mov_b32_e32 v6, v2
	v_mov_b32_e32 v7, v2
	v_mov_b32_e32 v8, v2
	v_mov_b32_e32 v9, v2
	s_barrier

; template <int EPI>
; __device__ __forceinline__ void phase_gemm(const Params& p, const GemmDesc& d, char* shmc) {
;     ...
;       float cw[2][4];
; #pragma unroll
;       for (int n = 0; n < 2; ++n) {
;         const int chx = ch0 + ewc * 32 + n * 16 + efr;
;         cw[n][0] = cwp[chx]; cw[n][1] = cwp[DFF + chx]; cw[n][2] = cwp[2 * DFF + chx]; cw[n][3] = cbp[chx];
;       }
;       const float* rsl = reinterpret_cast<const float*>(shmc + 143360);
;       f32x4 rsv[2][4];
; #pragma unroll
;       for (int ai = 0; ai < 2; ++ai)
; #pragma unroll
;         for (int m = 0; m < 4; ++m)
;           rsv[ai][m] = *reinterpret_cast<const f32x4*>(rsl + ai * HALF + ewr * 64 + m * 16 + efq * 4);
; #pragma unroll
;       for (int ai = 0; ai < 2; ++ai)
; #pragma unroll
;         for (int m = 0; m < 4; ++m) {
;           const f32x4 rs4 = rsv[ai][m];
; #pragma unroll
;           for (int n = 0; n < 2; ++n) {
;             acc[ai][0][m][n] *= rs4;
;             acc[ai][1][m][n] *= rs4;
;             const int s = ai * 32 + ewr * 16 + m * 4 + efq;
;             const int col = ewc * 32 + n * 16 + efr;
;             top[s * 144 + col] = acc[ai][0][m][n][0];
;             bot[s * 144 + col] = acc[ai][0][m][n][3];
;           }
;         }
.LBB0_299:
	s_mov_b32 s98, 0x3e8ba43f
	s_or_b64 exec, exec, s[8:9]
	v_mov_b32_e32 v38, v1
	s_movk_i32 s8, 0x60
	v_and_b32_e32 v177, 15, v38
	v_lshrrev_b32_e32 v30, 1, v38
	s_lshl_b32 s62, s34, 7
	v_and_or_b32 v162, v30, s8, v177
	v_or_b32_e32 v200, s62, v162
	v_ashrrev_i32_e32 v201, 31, v200
	v_lshlrev_b64 v[30:31], 2, v[200:201]
	v_lshl_add_u64 v[32:33], s[44:45], 0, v[30:31]
	v_add_co_u32_e32 v34, vcc, 0x5000, v32
	v_lshl_add_u64 v[30:31], s[46:47], 0, v[30:31]
	s_nop 0
	v_addc_co_u32_e32 v35, vcc, 0, v33, vcc
	v_add_co_u32_e32 v36, vcc, 0xb000, v32
	v_ashrrev_i32_e32 v175, 4, v38
	s_nop 0
	v_addc_co_u32_e32 v37, vcc, 0, v33, vcc
	global_load_dword v215, v[32:33], off
	global_load_dword v217, v[34:35], off offset:2048
	global_load_dword v216, v[36:37], off
	global_load_dword v208, v[36:37], off offset:64
	global_load_dword v210, v[34:35], off offset:2112
	global_load_dword v209, v[32:33], off offset:64
	global_load_dword v218, v[30:31], off
	global_load_dword v207, v[30:31], off offset:64
	v_bfe_u32 v178, v38, 8, 1
	v_and_b32_e32 v179, 3, v175
	v_lshlrev_b32_e32 v30, 8, v178
	v_lshlrev_b32_e32 v31, 4, v179
	v_add3_u32 v30, s76, v30, v31
	v_lshl_or_b32 v220, v178, 4, v179
	s_movk_i32 s8, 0x90
	ds_read_b128 v[62:65], v30
	ds_read_b128 v[54:57], v30 offset:64
	ds_read_b128 v[50:53], v30 offset:128
	ds_read_b128 v[46:49], v30 offset:192
	ds_read_b128 v[42:45], v30 offset:512
	ds_read_b128 v[38:41], v30 offset:576
	ds_read_b128 v[34:37], v30 offset:640
	ds_read_b128 v[30:33], v30 offset:704
	v_mad_u32_u24 v178, v220, s8, v162
	v_lshl_add_u32 v211, v178, 2, 0
	s_waitcnt lgkmcnt(0)
	v_pk_mul_f32 v[196:197], v[144:145], v[56:57]
	v_pk_mul_f32 v[198:199], v[142:143], v[54:55]
	v_pk_mul_f32 v[144:145], v[134:135], v[54:55]
	v_add_u32_e32 v134, 0x800, v211
	v_pk_mul_f32 v[190:191], v[128:129], v[52:53]
	v_pk_mul_f32 v[188:189], v[110:111], v[46:47]
	v_pk_mul_f32 v[128:129], v[102:103], v[46:47]
	v_add_u32_e32 v102, 0x1800, v211
	v_pk_mul_f32 v[142:143], v[136:137], v[56:57]
	ds_write2_b32 v134, v198, v144 offset0:64 offset1:80
	v_add_u32_e32 v134, 0x9800, v211
	v_pk_mul_f32 v[192:193], v[126:127], v[50:51]
	v_pk_mul_f32 v[136:137], v[118:119], v[50:51]
	v_add_u32_e32 v118, 0x1000, v211
	v_pk_mul_f32 v[186:187], v[112:113], v[48:49]
	v_pk_mul_f32 v[126:127], v[104:105], v[48:49]
	ds_write2_b32 v102, v188, v128 offset0:192 offset1:208
	v_add_u32_e32 v102, 0xa800, v211
	ds_write2_b32 v134, v197, v143 offset0:64 offset1:80
	v_pk_mul_f32 v[134:135], v[120:121], v[52:53]
	ds_write2_b32 v118, v192, v136 offset0:128 offset1:144
	v_add_u32_e32 v118, 0xa000, v211
	ds_write2_b32 v102, v187, v127 offset0:192 offset1:208
	v_pk_mul_f32 v[184:185], v[154:155], v[42:43]
	v_pk_mul_f32 v[120:121], v[150:151], v[42:43]
	v_add_u32_e32 v102, 0x4800, v211
	ds_write2_b32 v118, v191, v135 offset0:128 offset1:144
	v_pk_mul_f32 v[182:183], v[156:157], v[44:45]
	v_pk_mul_f32 v[118:119], v[152:153], v[44:45]
	ds_write2_b32 v102, v184, v120 offset1:16
	v_add_u32_e32 v102, 0xd800, v211
	v_pk_mul_f32 v[154:155], v[106:107], v[30:31]
	v_pk_mul_f32 v[98:99], v[98:99], v[30:31]
	v_add_u32_e32 v106, 0x6000, v211
	ds_write2_b32 v102, v183, v119 offset1:16
	v_pk_mul_f32 v[180:181], v[138:139], v[38:39]
	v_pk_mul_f32 v[112:113], v[130:131], v[38:39]
	v_add_u32_e32 v102, 0x5000, v211
	v_pk_mul_f32 v[152:153], v[108:109], v[32:33]
	v_pk_mul_f32 v[100:101], v[100:101], v[32:33]
	ds_write2_b32 v106, v154, v98 offset0:192 offset1:208
	v_add_u32_e32 v106, 0xf000, v211
	s_movk_i32 s8, 0x240
	v_pk_mul_f32 v[202:203], v[160:161], v[64:65]
	v_pk_mul_f32 v[194:195], v[158:159], v[62:63]
	v_pk_mul_f32 v[146:147], v[146:147], v[62:63]
	v_pk_mul_f32 v[178:179], v[140:141], v[40:41]
	v_pk_mul_f32 v[110:111], v[132:133], v[40:41]
	ds_write2_b32 v102, v180, v112 offset0:64 offset1:80
	v_add_u32_e32 v102, 0xe000, v211
	v_pk_mul_f32 v[160:161], v[122:123], v[34:35]
	v_pk_mul_f32 v[104:105], v[114:115], v[34:35]
	v_add_u32_e32 v114, 0x5800, v211
	ds_write2_b32 v106, v153, v101 offset0:192 offset1:208
	v_mad_u32_u24 v106, v220, s8, 0
	v_pk_mul_f32 v[158:159], v[148:149], v[64:65]
	ds_write2_b32 v211, v194, v146 offset1:16
	v_add_u32_e32 v148, 0x9000, v211
	ds_write2_b32 v102, v179, v111 offset0:64 offset1:80
	v_pk_mul_f32 v[156:157], v[124:125], v[36:37]
	v_pk_mul_f32 v[102:103], v[116:117], v[36:37]
	ds_write2_b32 v114, v160, v104 offset0:128 offset1:144
	v_add_u32_e32 v114, 0xe800, v211
	v_cmp_eq_u32_e64 s[10:11], 0, v220
	v_cmp_ne_u32_e32 vcc, 0, v220
	v_mov_b32_e32 v213, 0
	v_lshl_add_u32 v211, v162, 2, v106
	v_mov_b32_e32 v224, 0
	ds_write2_b32 v148, v203, v159 offset1:16
	ds_write2_b32 v114, v157, v103 offset0:128 offset1:144
	s_waitcnt vmcnt(0) lgkmcnt(0)
	s_barrier
; __device__ __forceinline__ float erf_f32(float x) {
;   const float ax = fabsf(x);
;   const float t = __frcp_rn(fmaf(0.3275911f, ax, 1.0f));
;   float poly = fmaf(1.061405429f, t, -1.453152027f);
;   poly = fmaf(poly, t, 1.421413741f);
;   poly = fmaf(poly, t, -0.284496736f);
;   poly = fmaf(poly, t, 0.254829592f);
;   const float y = 1.0f - poly * t * __expf(-ax * ax);
; template <int EPI>
; __device__ __forceinline__ void phase_gemm(const Params& p, const GemmDesc& d, char* shmc) {
;     ...
;       float gp[2][4][2], gn[2][4][2];
; #pragma unroll
;       for (int ai = 0; ai < 2; ++ai)
; #pragma unroll
;         for (int m = 0; m < 4; ++m)
; #pragma unroll
;           for (int n = 0; n < 2; ++n) {
;             const int s = ai * 32 + ewr * 16 + m * 4 + efq;
;             const int col = ewc * 32 + n * 16 + efr;
;             gp[ai][m][n] = (s > 0) ? bot[(s - 1) * 144 + col] : 0.f;
;             gn[ai][m][n] = (s < 63) ? top[(s + 1) * 144 + col] : 0.f;
;           }
;       float* edge = p.edge + (size_t)pm * 6 * DFF;
; #pragma unroll
;       for (int n = 0; n < 2; ++n) {
;         const int col = ewc * 32 + n * 16 + efr;
;         const int ch = ch0 + col;
;         const float w0 = cw[n][0], w1 = cw[n][1], w2 = cw[n][2], cb = cw[n][3];
; #pragma unroll
;         for (int ai = 0; ai < 2; ++ai)
; #pragma unroll
;           for (int m = 0; m < 4; ++m) {
;             const int s = ai * 32 + ewr * 16 + m * 4 + efq;
;             const f32x4 g = acc[ai][0][m][n];
;             const f32x4 v = acc[ai][1][m][n];
;             const float c0 = w0 * gp[ai][m][n] + w1 * g[0] + w2 * g[1] + cb;
;             const float c1 = w0 * g[0] + w1 * g[1] + w2 * g[2] + cb;
;             const float c2 = w0 * g[1] + w1 * g[2] + w2 * g[3] + cb;
;             const float c3 = w0 * g[2] + w1 * g[3] + w2 * gn[ai][m][n] + cb;
;             u16* sp = stg + (s * 4) * 136 + col;
;             sp[0] = f2bf(gelu_exact(c0) * v[0]);
;             sp[136] = f2bf(gelu_exact(c1) * v[1]);
;             sp[272] = f2bf(gelu_exact(c2) * v[2]);
;             sp[408] = f2bf(gelu_exact(c3) * v[3]);
;             if (s == 0) {
;               edge[0 * DFF + ch] = c0; edge[1 * DFF + ch] = g[0]; edge[2 * DFF + ch] = v[0];
;             }
;             if (s == 63) {
;               edge[3 * DFF + ch] = c3; edge[4 * DFF + ch] = g[3]; edge[5 * DFF + ch] = v[3];
;             }
;           }
	s_and_saveexec_b64 s[8:9], vcc
	ds_read_b32 v224, v211 offset:36288
	s_or_b64 exec, exec, s[8:9]
	ds_read_b32 v223, v211 offset:576
	s_and_saveexec_b64 s[8:9], vcc
	ds_read_b32 v213, v211 offset:36352
	s_or_b64 exec, exec, s[8:9]
	v_add_u32_e32 v106, 0x9400, v211
	ds_read2_b32 v[150:151], v106 offset0:176 offset1:192
	v_add_u32_e32 v106, 0x800, v211
	ds_read2_b32 v[148:149], v106 offset0:208 offset1:224
	v_add_u32_e32 v106, 0x9e00, v211
	ds_read2_b32 v[140:141], v106 offset0:112 offset1:128
	v_add_u32_e32 v106, 0x1400, v211
	ds_read2_b32 v[138:139], v106 offset0:16 offset1:32
	v_add_u32_e32 v106, 0xa800, v211
	ds_read2_b32 v[132:133], v106 offset0:48 offset1:64
	v_add_u32_e32 v106, 0x1c00, v211
	ds_read2_b32 v[130:131], v106 offset0:80 offset1:96
	v_add_u32_e32 v106, 0xd400, v211
	ds_read2_b32 v[124:125], v106 offset0:112 offset1:128
	v_add_u32_e32 v106, 0x4800, v211
	ds_read2_b32 v[122:123], v106 offset0:144 offset1:160
	v_add_u32_e32 v106, 0xdc00, v211
	ds_read2_b32 v[116:117], v106 offset0:176 offset1:192
	v_add_u32_e32 v106, 0x5000, v211
	ds_read2_b32 v[114:115], v106 offset0:208 offset1:224
	v_add_u32_e32 v106, 0xe600, v211
	ds_read2_b32 v[108:109], v106 offset0:112 offset1:128
	v_add_u32_e32 v106, 0x5c00, v211
	ds_read2_b32 v[106:107], v106 offset0:16 offset1:32
	ds_read_b32 v214, v211 offset:640
	ds_read_b32 v221, v211 offset:61632
	v_cmp_eq_u32_e64 s[8:9], 19, v220
	v_cmp_ne_u32_e32 vcc, 19, v220
	v_add_u32_e32 v222, 0x6300, v211
	v_mov_b32_e32 v211, 0
	v_mov_b32_e32 v219, 0
	s_and_saveexec_b64 s[64:65], vcc
	ds_read_b32 v219, v222 offset:576
	s_or_b64 exec, exec, s[64:65]
	ds_read_b32 v212, v222 offset:36352
	s_and_saveexec_b64 s[64:65], vcc
	ds_read_b32 v211, v222 offset:640
	s_or_b64 exec, exec, s[64:65]
	s_mul_hi_i32 s34, s14, 0x21000
	s_mul_i32 s14, s14, 0x21000
	v_readlane_b32 s72, v246, 15
	v_readlane_b32 s73, v246, 16
	s_add_u32 s64, s72, s14
	s_addc_u32 s65, s73, s34
	v_pk_mul_f32 v[226:227], v[96:97], v[64:65]
	v_pk_mul_f32 v[96:97], v[94:95], v[62:63]
	v_lshl_add_u64 v[94:95], v[200:201], 2, s[64:65]
	s_waitcnt lgkmcnt(14)
	v_mul_f32_e32 v200, v215, v224
	v_fmac_f32_e32 v200, v217, v194
	v_mul_f32_e32 v224, v217, v202
	v_fmac_f32_e32 v200, v216, v195
	v_mul_f32_e32 v201, v217, v195
	v_fmac_f32_e32 v224, v215, v195
	v_add_f32_e32 v200, v218, v200
	v_fmac_f32_e32 v201, v215, v194
	v_fmac_f32_e32 v224, v216, v203
	v_mul_f32_e32 v203, v217, v203
	v_fmac_f32_e32 v201, v216, v202
	v_fmac_f32_e32 v203, v215, v202
	v_mul_f32_e32 v202, 0x3f596d27, v200
	v_fmac_f32_e32 v203, v216, v223
	v_fma_f32 v223, |v202|, s98, 1.0
	v_add_f32_e32 v195, v218, v224
	v_add_f32_e32 v201, v218, v201
	s_add_i32 s14, 0, 0x12000
	v_lshl_add_u32 v222, v162, 1, s14
	v_rcp_f32_e32 v223, v223
	v_mul_f32_e64 v225, |v202|, -|v202|
	v_fmamk_f32 v224, v223, 0x3f87dc22, v206
	v_fmaak_f32 v224, v224, v223, 0x3fb5f0e3
	v_exp_f32_e32 v225, v225
	v_fmaak_f32 v224, v224, v223, 0xbe91a98e
	v_fmaak_f32 v224, v224, v223, 0x3e827906
	v_mul_f32_e32 v223, v223, v224
	v_fma_f32 v202, -v225, v223, 1.0
	v_mul_f32_e32 v223, 0x3f596d27, v201
	s_movk_i32 s34, 0x440
	v_fma_f32 v224, |v223|, s98, 1.0
	v_mad_u32_u24 v228, v220, s34, v222
	v_mul_f32_e32 v229, 0.5, v200
	v_fma_f32 v202, |v229|, v202, v229
	v_mul_f32_e32 v202, v96, v202
	v_cvt_pk_bf16_f32 v202, v202, s0
	ds_write_b16 v228, v202
	v_rcp_f32_e32 v202, v224
	v_mul_f32_e64 v225, |v223|, -|v223|
	v_fmamk_f32 v224, v202, 0x3f87dc22, v206
	v_fmaak_f32 v224, v224, v202, 0x3fb5f0e3
	v_exp_f32_e32 v225, v225
	v_fmaak_f32 v224, v224, v202, 0xbe91a98e
	v_fmaak_f32 v224, v224, v202, 0x3e827906
	v_mul_f32_e32 v202, v202, v224
	v_fma_f32 v202, -v225, v202, 1.0
	v_mul_f32_e32 v201, 0.5, v201
	v_fma_f32 v201, |v201|, v202, v201
	v_mul_f32_e32 v97, v97, v201
	v_mul_f32_e32 v201, 0x3f596d27, v195
	v_fma_f32 v202, |v201|, s98, 1.0
	v_cvt_pk_bf16_f32 v97, v97, s0
	ds_write_b16 v228, v97 offset:272
	v_mul_f32_e32 v97, 0.5, v195
	v_rcp_f32_e32 v195, v202
	v_mul_f32_e64 v223, |v201|, -|v201|
	v_fmamk_f32 v202, v195, 0x3f87dc22, v206
	v_fmaak_f32 v202, v202, v195, 0x3fb5f0e3
	v_exp_f32_e32 v223, v223
	v_fmaak_f32 v202, v202, v195, 0xbe91a98e
	v_fmaak_f32 v202, v202, v195, 0x3e827906
	v_mul_f32_e32 v195, v195, v202
	v_fma_f32 v195, -v223, v195, 1.0
	v_add_f32_e32 v203, v218, v203
	v_fma_f32 v97, |v97|, v195, v97
	v_mul_f32_e32 v195, 0x3f596d27, v203
	v_fma_f32 v201, |v195|, s98, 1.0
	v_mul_f32_e32 v97, v226, v97
	v_cvt_pk_bf16_f32 v97, v97, s0
	ds_write_b16 v228, v97 offset:544
	v_mul_f32_e32 v97, 0.5, v203
	v_rcp_f32_e32 v201, v201
	v_mul_f32_e64 v203, |v195|, -|v195|
	v_fmamk_f32 v202, v201, 0x3f87dc22, v206
	v_fmaak_f32 v202, v202, v201, 0x3fb5f0e3
	v_exp_f32_e32 v203, v203
	v_fmaak_f32 v202, v202, v201, 0xbe91a98e
	v_fmaak_f32 v202, v202, v201, 0x3e827906
	v_mul_f32_e32 v201, v201, v202
	v_fma_f32 v195, -v203, v201, 1.0
	v_fma_f32 v97, |v97|, v195, v97
	v_mul_f32_e32 v97, v227, v97
	v_cvt_pk_bf16_f32 v97, v97, s0
	v_readlane_b32 s74, v246, 17
	v_readlane_b32 s75, v246, 18
	ds_write_b16 v228, v97 offset:816
	s_and_saveexec_b64 s[78:79], s[10:11]
	s_cbranch_execz .LBB0_309
	global_store_dword v[94:95], v200, off
	v_add_co_u32_e32 v200, vcc, 0x5000, v94
	s_nop 1
	v_addc_co_u32_e32 v201, vcc, 0, v95, vcc
	global_store_dword v[200:201], v194, off offset:2048
	v_add_co_u32_e32 v194, vcc, 0xb000, v94
	s_nop 1
	v_addc_co_u32_e32 v195, vcc, 0, v95, vcc
	global_store_dword v[194:195], v96, off
; __device__ __forceinline__ u16 f2bf(float f) { return (u16)(pack2(f, f) & 0xffffu); }
; __device__ __forceinline__ float erf_f32(float x) {
;   const float ax = fabsf(x);
;   const float t = __frcp_rn(fmaf(0.3275911f, ax, 1.0f));
;   float poly = fmaf(1.061405429f, t, -1.453152027f);
;   poly = fmaf(poly, t, 1.421413741f);
;   poly = fmaf(poly, t, -0.284496736f);
;   poly = fmaf(poly, t, 0.254829592f);
;   const float y = 1.0f - poly * t * __expf(-ax * ax);
;   return copysignf(y, x);
; }
; __device__ __forceinline__ float gelu_exact(float x) { return 0.5f * x * (1.0f + erf_f32(x * 0.70710678118654752f)); }
; template <int EPI>
; __device__ __forceinline__ void phase_gemm(const Params& p, const GemmDesc& d, char* shmc) {
;     ...
; #pragma unroll
;       for (int n = 0; n < 2; ++n) {
;         const int col = ewc * 32 + n * 16 + efr;
;         const int ch = ch0 + col;
;         const float w0 = cw[n][0], w1 = cw[n][1], w2 = cw[n][2], cb = cw[n][3];
; #pragma unroll
;         for (int ai = 0; ai < 2; ++ai)
; #pragma unroll
;           for (int m = 0; m < 4; ++m) {
;             const int s = ai * 32 + ewr * 16 + m * 4 + efq;
;             const f32x4 g = acc[ai][0][m][n];
;             const f32x4 v = acc[ai][1][m][n];
;             const float c0 = w0 * gp[ai][m][n] + w1 * g[0] + w2 * g[1] + cb;
;             const float c1 = w0 * g[0] + w1 * g[1] + w2 * g[2] + cb;
;             const float c2 = w0 * g[1] + w1 * g[2] + w2 * g[3] + cb;
;             const float c3 = w0 * g[2] + w1 * g[3] + w2 * gn[ai][m][n] + cb;
;             u16* sp = stg + (s * 4) * 136 + col;
;             sp[0] = f2bf(gelu_exact(c0) * v[0]);
;             sp[136] = f2bf(gelu_exact(c1) * v[1]);
;             sp[272] = f2bf(gelu_exact(c2) * v[2]);
;             sp[408] = f2bf(gelu_exact(c3) * v[3]);
;             if (s == 0) {
;               edge[0 * DFF + ch] = c0; edge[1 * DFF + ch] = g[0]; edge[2 * DFF + ch] = v[0];
;             }
;             if (s == 63) {
;               edge[3 * DFF + ch] = c3; edge[4 * DFF + ch] = g[3]; edge[5 * DFF + ch] = v[3];
;             }
;           }
.LBB0_309:
	s_or_b64 exec, exec, s[78:79]
	v_pk_mul_f32 v[96:97], v[68:69], v[48:49]
	v_pk_mul_f32 v[68:69], v[78:79], v[30:31]
	v_mul_f32_e32 v78, v215, v150
	v_fmac_f32_e32 v78, v217, v198
	v_fmac_f32_e32 v78, v216, v199
	v_add_f32_e32 v79, v218, v78
	v_pk_mul_f32 v[200:201], v[72:73], v[52:53]
	v_pk_mul_f32 v[72:73], v[82:83], v[34:35]
	v_mul_f32_e32 v83, 0x3f596d27, v79
	v_pk_mul_f32 v[202:203], v[70:71], v[50:51]
	v_pk_mul_f32 v[70:71], v[84:85], v[36:37]
	v_fma_f32 v84, |v83|, s98, 1.0
	v_mul_f32_e32 v78, v217, v199
	v_pk_mul_f32 v[224:225], v[76:77], v[56:57]
	v_pk_mul_f32 v[76:77], v[86:87], v[38:39]
	v_fmac_f32_e32 v78, v215, v198
	v_fmac_f32_e32 v78, v216, v196
	v_pk_mul_f32 v[194:195], v[66:67], v[46:47]
	v_pk_mul_f32 v[66:67], v[80:81], v[32:33]
	v_add_f32_e32 v80, v218, v78
	v_mul_f32_e32 v78, v217, v196
	v_fmac_f32_e32 v78, v215, v199
	v_pk_mul_f32 v[226:227], v[74:75], v[54:55]
	v_pk_mul_f32 v[74:75], v[88:89], v[40:41]
	v_fmac_f32_e32 v78, v216, v197
	v_add_f32_e32 v81, v218, v78
	v_mul_f32_e32 v78, v217, v197
	v_fmac_f32_e32 v78, v215, v196
	s_waitcnt lgkmcnt(14)
	v_fmac_f32_e32 v78, v216, v148
	v_rcp_f32_e32 v84, v84
	v_mul_f32_e64 v86, |v83|, -|v83|
	v_fmamk_f32 v85, v84, 0x3f87dc22, v206
	v_fmaak_f32 v85, v85, v84, 0x3fb5f0e3
	v_exp_f32_e32 v86, v86
	v_fmaak_f32 v85, v85, v84, 0xbe91a98e
	v_fmaak_f32 v85, v85, v84, 0x3e827906
	v_mul_f32_e32 v84, v84, v85
	v_fma_f32 v83, -v86, v84, 1.0
	v_mul_f32_e32 v79, 0.5, v79
	v_fma_f32 v79, |v79|, v83, v79
	v_mul_f32_e32 v83, 0x3f596d27, v80
	v_fma_f32 v84, |v83|, s98, 1.0
	v_mul_u32_u24_e32 v220, 0x440, v220
	v_add_f32_e32 v82, v218, v78
	v_add_u32_e32 v78, 0x1100, v220
	v_mul_f32_e32 v79, v226, v79
	v_add_u32_e32 v87, v222, v78
	v_cvt_pk_bf16_f32 v79, v79, s0
	ds_write_b16 v87, v79
	v_mul_f32_e32 v79, 0.5, v80
	v_rcp_f32_e32 v80, v84
	v_mul_f32_e64 v85, |v83|, -|v83|
	v_fmamk_f32 v84, v80, 0x3f87dc22, v206
	v_fmaak_f32 v84, v84, v80, 0x3fb5f0e3
	v_exp_f32_e32 v85, v85
	v_fmaak_f32 v84, v84, v80, 0xbe91a98e
	v_fmaak_f32 v84, v84, v80, 0x3e827906
	v_mul_f32_e32 v80, v80, v84
	v_fma_f32 v80, -v85, v80, 1.0
	v_fma_f32 v79, |v79|, v80, v79
	v_mul_f32_e32 v80, 0x3f596d27, v81
	v_fma_f32 v83, |v80|, s98, 1.0
	v_mul_f32_e32 v79, v227, v79
	v_cvt_pk_bf16_f32 v79, v79, s0
	ds_write_b16 v87, v79 offset:272
	v_mul_f32_e32 v79, 0.5, v81
	v_rcp_f32_e32 v81, v83
	v_mul_f32_e64 v84, |v80|, -|v80|
	v_fmamk_f32 v83, v81, 0x3f87dc22, v206
	v_fmaak_f32 v83, v83, v81, 0x3fb5f0e3
	v_exp_f32_e32 v84, v84
	v_fmaak_f32 v83, v83, v81, 0xbe91a98e
	v_fmaak_f32 v83, v83, v81, 0x3e827906
	v_mul_f32_e32 v81, v81, v83
	v_fma_f32 v80, -v84, v81, 1.0
	v_fma_f32 v79, |v79|, v80, v79
	v_mul_f32_e32 v80, 0x3f596d27, v82
	v_fma_f32 v81, |v80|, s98, 1.0
	v_mul_f32_e32 v79, v224, v79
	v_cvt_pk_bf16_f32 v79, v79, s0
	ds_write_b16 v87, v79 offset:544
	v_mul_f32_e32 v79, 0.5, v82
	v_rcp_f32_e32 v81, v81
	v_mul_f32_e64 v83, |v80|, -|v80|
	v_fmamk_f32 v82, v81, 0x3f87dc22, v206
	v_fmaak_f32 v82, v82, v81, 0x3fb5f0e3
	v_exp_f32_e32 v83, v83
	v_fmaak_f32 v82, v82, v81, 0xbe91a98e
	v_fmaak_f32 v82, v82, v81, 0x3e827906
	v_mul_f32_e32 v81, v81, v82
	v_fma_f32 v80, -v83, v81, 1.0
	v_fma_f32 v79, |v79|, v80, v79
	v_mul_f32_e32 v79, v225, v79
	v_cvt_pk_bf16_f32 v79, v79, s0
	ds_write_b16 v87, v79 offset:816
	v_mul_f32_e32 v79, v215, v140
	v_fmac_f32_e32 v79, v217, v192
	v_fmac_f32_e32 v79, v216, v193
	v_add_f32_e32 v80, v218, v79
	v_mul_f32_e32 v84, 0x3f596d27, v80
	v_mul_f32_e32 v79, v217, v193
	v_fma_f32 v85, |v84|, s98, 1.0
	v_fmac_f32_e32 v79, v215, v192
	v_fmac_f32_e32 v79, v216, v190
	v_add_f32_e32 v81, v218, v79
	v_mul_f32_e32 v79, v217, v190
	v_fmac_f32_e32 v79, v215, v193
	v_fmac_f32_e32 v79, v216, v191
	v_add_f32_e32 v82, v218, v79
	v_mul_f32_e32 v79, v217, v191
	v_fmac_f32_e32 v79, v215, v190
	v_fmac_f32_e32 v79, v216, v138
	v_rcp_f32_e32 v85, v85
	v_mul_f32_e64 v87, |v84|, -|v84|
	v_fmamk_f32 v86, v85, 0x3f87dc22, v206
	v_fmaak_f32 v86, v86, v85, 0x3fb5f0e3
	v_exp_f32_e32 v87, v87
	v_fmaak_f32 v86, v86, v85, 0xbe91a98e
	v_fmaak_f32 v86, v86, v85, 0x3e827906
	v_mul_f32_e32 v85, v85, v86
	v_fma_f32 v84, -v87, v85, 1.0
	v_mul_f32_e32 v80, 0.5, v80
	v_fma_f32 v80, |v80|, v84, v80
	v_mul_f32_e32 v84, 0x3f596d27, v81
	v_fma_f32 v85, |v84|, s98, 1.0
	v_add_f32_e32 v83, v218, v79
	v_add_u32_e32 v79, 0x2200, v220
	v_mul_f32_e32 v80, v202, v80
	v_add_u32_e32 v88, v222, v79
	v_cvt_pk_bf16_f32 v80, v80, s0
	ds_write_b16 v88, v80
	v_mul_f32_e32 v80, 0.5, v81
	v_rcp_f32_e32 v81, v85
	v_mul_f32_e64 v86, |v84|, -|v84|
	v_fmamk_f32 v85, v81, 0x3f87dc22, v206
	v_fmaak_f32 v85, v85, v81, 0x3fb5f0e3
	v_exp_f32_e32 v86, v86
	v_fmaak_f32 v85, v85, v81, 0xbe91a98e
	v_fmaak_f32 v85, v85, v81, 0x3e827906
	v_mul_f32_e32 v81, v81, v85
	v_fma_f32 v81, -v86, v81, 1.0
	v_fma_f32 v80, |v80|, v81, v80
	v_mul_f32_e32 v81, 0x3f596d27, v82
	v_fma_f32 v84, |v81|, s98, 1.0
	v_mul_f32_e32 v80, v203, v80
	v_cvt_pk_bf16_f32 v80, v80, s0
	ds_write_b16 v88, v80 offset:272
	v_mul_f32_e32 v80, 0.5, v82
	v_rcp_f32_e32 v82, v84
	v_mul_f32_e64 v85, |v81|, -|v81|
	v_fmamk_f32 v84, v82, 0x3f87dc22, v206
	v_fmaak_f32 v84, v84, v82, 0x3fb5f0e3
	v_exp_f32_e32 v85, v85
	v_fmaak_f32 v84, v84, v82, 0xbe91a98e
	v_fmaak_f32 v84, v84, v82, 0x3e827906
	v_mul_f32_e32 v82, v82, v84
	v_fma_f32 v81, -v85, v82, 1.0
	v_fma_f32 v80, |v80|, v81, v80
	v_mul_f32_e32 v81, 0x3f596d27, v83
	v_fma_f32 v82, |v81|, s98, 1.0
	v_mul_f32_e32 v80, v200, v80
	v_cvt_pk_bf16_f32 v80, v80, s0
	ds_write_b16 v88, v80 offset:544
	v_mul_f32_e32 v80, 0.5, v83
	v_rcp_f32_e32 v82, v82
	v_mul_f32_e64 v84, |v81|, -|v81|
	v_fmamk_f32 v83, v82, 0x3f87dc22, v206
	v_fmaak_f32 v83, v83, v82, 0x3fb5f0e3
	v_exp_f32_e32 v84, v84
	v_fmaak_f32 v83, v83, v82, 0xbe91a98e
	v_fmaak_f32 v83, v83, v82, 0x3e827906
	v_mul_f32_e32 v82, v82, v83
	v_fma_f32 v81, -v84, v82, 1.0
	v_fma_f32 v80, |v80|, v81, v80
	v_mul_f32_e32 v80, v201, v80
	v_cvt_pk_bf16_f32 v80, v80, s0
	ds_write_b16 v88, v80 offset:816
	v_mul_f32_e32 v80, v215, v132
	v_fmac_f32_e32 v80, v217, v188
	v_fmac_f32_e32 v80, v216, v189
	v_add_f32_e32 v81, v218, v80
	v_mul_f32_e32 v80, v217, v189
	v_fmac_f32_e32 v80, v215, v188
	v_mul_f32_e32 v85, 0x3f596d27, v81
	v_fmac_f32_e32 v80, v216, v186
	v_fma_f32 v86, |v85|, s98, 1.0
	v_add_f32_e32 v82, v218, v80
	v_mul_f32_e32 v80, v217, v186
	v_fmac_f32_e32 v80, v215, v189
	v_fmac_f32_e32 v80, v216, v187
	v_add_f32_e32 v83, v218, v80
	v_mul_f32_e32 v80, v217, v187
	v_fmac_f32_e32 v80, v215, v186
	s_waitcnt lgkmcnt(14)
; __device__ __forceinline__ u16 f2bf(float f) { return (u16)(pack2(f, f) & 0xffffu); }
; __device__ __forceinline__ float erf_f32(float x) {
;   const float ax = fabsf(x);
;   const float t = __frcp_rn(fmaf(0.3275911f, ax, 1.0f));
;   float poly = fmaf(1.061405429f, t, -1.453152027f);
;   poly = fmaf(poly, t, 1.421413741f);
;   poly = fmaf(poly, t, -0.284496736f);
;   poly = fmaf(poly, t, 0.254829592f);
;   const float y = 1.0f - poly * t * __expf(-ax * ax);
;   return copysignf(y, x);
; }
; __device__ __forceinline__ float gelu_exact(float x) { return 0.5f * x * (1.0f + erf_f32(x * 0.70710678118654752f)); }
; template <int EPI>
; __device__ __forceinline__ void phase_gemm(const Params& p, const GemmDesc& d, char* shmc) {
;     ...
; #pragma unroll
;       for (int n = 0; n < 2; ++n) {
;         const int col = ewc * 32 + n * 16 + efr;
;         const int ch = ch0 + col;
;         const float w0 = cw[n][0], w1 = cw[n][1], w2 = cw[n][2], cb = cw[n][3];
; #pragma unroll
;         for (int ai = 0; ai < 2; ++ai)
; #pragma unroll
;           for (int m = 0; m < 4; ++m) {
;             const int s = ai * 32 + ewr * 16 + m * 4 + efq;
;             const f32x4 g = acc[ai][0][m][n];
;             const f32x4 v = acc[ai][1][m][n];
;             const float c0 = w0 * gp[ai][m][n] + w1 * g[0] + w2 * g[1] + cb;
;             const float c1 = w0 * g[0] + w1 * g[1] + w2 * g[2] + cb;
;             const float c2 = w0 * g[1] + w1 * g[2] + w2 * g[3] + cb;
;             const float c3 = w0 * g[2] + w1 * g[3] + w2 * gn[ai][m][n] + cb;
;             u16* sp = stg + (s * 4) * 136 + col;
;             sp[0] = f2bf(gelu_exact(c0) * v[0]);
;             sp[136] = f2bf(gelu_exact(c1) * v[1]);
;             sp[272] = f2bf(gelu_exact(c2) * v[2]);
;             sp[408] = f2bf(gelu_exact(c3) * v[3]);
;             if (s == 0) {
;               edge[0 * DFF + ch] = c0; edge[1 * DFF + ch] = g[0]; edge[2 * DFF + ch] = v[0];
;             }
;             if (s == 63) {
;               edge[3 * DFF + ch] = c3; edge[4 * DFF + ch] = g[3]; edge[5 * DFF + ch] = v[3];
;             }
;           }
	v_fmac_f32_e32 v80, v216, v130
	v_rcp_f32_e32 v86, v86
	v_mul_f32_e64 v88, |v85|, -|v85|
	v_fmamk_f32 v87, v86, 0x3f87dc22, v206
	v_fmaak_f32 v87, v87, v86, 0x3fb5f0e3
	v_exp_f32_e32 v88, v88
	v_fmaak_f32 v87, v87, v86, 0xbe91a98e
	v_fmaak_f32 v87, v87, v86, 0x3e827906
	v_mul_f32_e32 v86, v86, v87
	v_fma_f32 v85, -v88, v86, 1.0
	v_mul_f32_e32 v81, 0.5, v81
	v_fma_f32 v81, |v81|, v85, v81
	v_mul_f32_e32 v85, 0x3f596d27, v82
	v_fma_f32 v86, |v85|, s98, 1.0
	v_add_f32_e32 v84, v218, v80
	v_add_u32_e32 v80, 0x3300, v220
	v_mul_f32_e32 v81, v194, v81
	v_add_u32_e32 v89, v222, v80
	v_cvt_pk_bf16_f32 v81, v81, s0
	ds_write_b16 v89, v81
	v_mul_f32_e32 v81, 0.5, v82
	v_rcp_f32_e32 v82, v86
	v_mul_f32_e64 v87, |v85|, -|v85|
	v_fmamk_f32 v86, v82, 0x3f87dc22, v206
	v_fmaak_f32 v86, v86, v82, 0x3fb5f0e3
	v_exp_f32_e32 v87, v87
	v_fmaak_f32 v86, v86, v82, 0xbe91a98e
	v_fmaak_f32 v86, v86, v82, 0x3e827906
	v_mul_f32_e32 v82, v82, v86
	v_fma_f32 v82, -v87, v82, 1.0
	v_fma_f32 v81, |v81|, v82, v81
	v_mul_f32_e32 v82, 0x3f596d27, v83
	v_fma_f32 v85, |v82|, s98, 1.0
	v_mul_f32_e32 v81, v195, v81
	v_cvt_pk_bf16_f32 v81, v81, s0
	ds_write_b16 v89, v81 offset:272
	v_mul_f32_e32 v81, 0.5, v83
	v_rcp_f32_e32 v83, v85
	v_mul_f32_e64 v86, |v82|, -|v82|
	v_fmamk_f32 v85, v83, 0x3f87dc22, v206
	v_fmaak_f32 v85, v85, v83, 0x3fb5f0e3
	v_exp_f32_e32 v86, v86
	v_fmaak_f32 v85, v85, v83, 0xbe91a98e
	v_fmaak_f32 v85, v85, v83, 0x3e827906
	v_mul_f32_e32 v83, v83, v85
	v_fma_f32 v82, -v86, v83, 1.0
	v_fma_f32 v81, |v81|, v82, v81
	v_mul_f32_e32 v82, 0x3f596d27, v84
	v_fma_f32 v83, |v82|, s98, 1.0
	v_mul_f32_e32 v81, v96, v81
	v_cvt_pk_bf16_f32 v81, v81, s0
	ds_write_b16 v89, v81 offset:544
	v_mul_f32_e32 v81, 0.5, v84
	v_rcp_f32_e32 v83, v83
	v_mul_f32_e64 v85, |v82|, -|v82|
	v_fmamk_f32 v84, v83, 0x3f87dc22, v206
	v_fmaak_f32 v84, v84, v83, 0x3fb5f0e3
	v_exp_f32_e32 v85, v85
	v_fmaak_f32 v84, v84, v83, 0xbe91a98e
	v_fmaak_f32 v84, v84, v83, 0x3e827906
	v_mul_f32_e32 v83, v83, v84
	v_fma_f32 v82, -v85, v83, 1.0
	v_fma_f32 v81, |v81|, v82, v81
	v_mul_f32_e32 v81, v97, v81
	v_cvt_pk_bf16_f32 v81, v81, s0
	ds_write_b16 v89, v81 offset:816
	v_mul_f32_e32 v81, v215, v124
	v_fmac_f32_e32 v81, v217, v184
	v_fmac_f32_e32 v81, v216, v185
	v_add_f32_e32 v82, v218, v81
	v_mul_f32_e32 v86, 0x3f596d27, v82
	v_mul_f32_e32 v81, v217, v185
	v_fma_f32 v87, |v86|, s98, 1.0
	v_fmac_f32_e32 v81, v215, v184
	v_fmac_f32_e32 v81, v216, v182
	v_add_f32_e32 v83, v218, v81
	v_mul_f32_e32 v81, v217, v182
	v_fmac_f32_e32 v81, v215, v185
	v_fmac_f32_e32 v81, v216, v183
	v_add_f32_e32 v84, v218, v81
	v_mul_f32_e32 v81, v217, v183
	v_fmac_f32_e32 v81, v215, v182
	v_fmac_f32_e32 v81, v216, v122
	v_rcp_f32_e32 v87, v87
	v_mul_f32_e64 v89, |v86|, -|v86|
	v_fmamk_f32 v88, v87, 0x3f87dc22, v206
	v_fmaak_f32 v88, v88, v87, 0x3fb5f0e3
	v_exp_f32_e32 v89, v89
	v_fmaak_f32 v88, v88, v87, 0xbe91a98e
	v_fmaak_f32 v88, v88, v87, 0x3e827906
	v_mul_f32_e32 v87, v87, v88
	v_fma_f32 v86, -v89, v87, 1.0
	v_mul_f32_e32 v82, 0.5, v82
	v_fma_f32 v82, |v82|, v86, v82
	v_mul_f32_e32 v86, 0x3f596d27, v83
	v_fma_f32 v87, |v86|, s98, 1.0
	v_pk_mul_f32 v[90:91], v[90:91], v[42:43]
	v_add_f32_e32 v85, v218, v81
	v_add_u32_e32 v81, 0x8800, v220
	v_mul_f32_e32 v82, v90, v82
	v_add_u32_e32 v96, v222, v81
	v_cvt_pk_bf16_f32 v82, v82, s0
	ds_write_b16 v96, v82
	v_mul_f32_e32 v82, 0.5, v83
	v_rcp_f32_e32 v83, v87
	v_mul_f32_e64 v88, |v86|, -|v86|
	v_fmamk_f32 v87, v83, 0x3f87dc22, v206
	v_fmaak_f32 v87, v87, v83, 0x3fb5f0e3
	v_exp_f32_e32 v88, v88
	v_fmaak_f32 v87, v87, v83, 0xbe91a98e
	v_fmaak_f32 v87, v87, v83, 0x3e827906
	v_mul_f32_e32 v83, v83, v87
	v_fma_f32 v83, -v88, v83, 1.0
	v_fma_f32 v82, |v82|, v83, v82
	v_mul_f32_e32 v83, 0x3f596d27, v84
	v_fma_f32 v86, |v83|, s98, 1.0
	v_mul_f32_e32 v82, v91, v82
	v_cvt_pk_bf16_f32 v82, v82, s0
	ds_write_b16 v96, v82 offset:272
	v_mul_f32_e32 v82, 0.5, v84
	v_rcp_f32_e32 v84, v86
	v_mul_f32_e64 v87, |v83|, -|v83|
	v_fmamk_f32 v86, v84, 0x3f87dc22, v206
	v_fmaak_f32 v86, v86, v84, 0x3fb5f0e3
	v_exp_f32_e32 v87, v87
	v_fmaak_f32 v86, v86, v84, 0xbe91a98e
	v_fmaak_f32 v86, v86, v84, 0x3e827906
	v_mul_f32_e32 v84, v84, v86
	v_fma_f32 v83, -v87, v84, 1.0
	v_fma_f32 v82, |v82|, v83, v82
	v_mul_f32_e32 v83, 0x3f596d27, v85
	v_fma_f32 v84, |v83|, s98, 1.0
	v_pk_mul_f32 v[92:93], v[92:93], v[44:45]
	s_nop 0
	v_mul_f32_e32 v82, v92, v82
	v_cvt_pk_bf16_f32 v82, v82, s0
	ds_write_b16 v96, v82 offset:544
	v_mul_f32_e32 v82, 0.5, v85
	v_rcp_f32_e32 v84, v84
	v_mul_f32_e64 v86, |v83|, -|v83|
	v_fmamk_f32 v85, v84, 0x3f87dc22, v206
	v_fmaak_f32 v85, v85, v84, 0x3fb5f0e3
	v_exp_f32_e32 v86, v86
	v_fmaak_f32 v85, v85, v84, 0xbe91a98e
	v_fmaak_f32 v85, v85, v84, 0x3e827906
	v_mul_f32_e32 v84, v84, v85
	v_fma_f32 v83, -v86, v84, 1.0
	v_fma_f32 v82, |v82|, v83, v82
	v_mul_f32_e32 v82, v93, v82
	v_cvt_pk_bf16_f32 v82, v82, s0
	ds_write_b16 v96, v82 offset:816
	v_mul_f32_e32 v82, v215, v116
	v_fmac_f32_e32 v82, v217, v180
	v_fmac_f32_e32 v82, v216, v181
	v_add_f32_e32 v83, v218, v82
	v_mul_f32_e32 v87, 0x3f596d27, v83
	v_fma_f32 v88, |v87|, s98, 1.0
	v_mul_f32_e32 v82, v217, v181
	v_fmac_f32_e32 v82, v215, v180
	v_fmac_f32_e32 v82, v216, v178
	v_rcp_f32_e32 v88, v88
	v_mul_f32_e64 v90, |v87|, -|v87|
	v_fmamk_f32 v89, v88, 0x3f87dc22, v206
	v_fmaak_f32 v89, v89, v88, 0x3fb5f0e3
	v_exp_f32_e32 v90, v90
	v_fmaak_f32 v89, v89, v88, 0xbe91a98e
	v_fmaak_f32 v89, v89, v88, 0x3e827906
	v_mul_f32_e32 v88, v88, v89
	v_fma_f32 v87, -v90, v88, 1.0
	v_mul_f32_e32 v83, 0.5, v83
	v_add_f32_e32 v84, v218, v82
	v_mul_f32_e32 v82, v217, v178
	v_fma_f32 v83, |v83|, v87, v83
	v_fmac_f32_e32 v82, v215, v181
	v_mul_f32_e32 v76, v76, v83
; __device__ __forceinline__ u16 f2bf(float f) { return (u16)(pack2(f, f) & 0xffffu); }
; __device__ __forceinline__ float erf_f32(float x) {
;   const float ax = fabsf(x);
;   const float t = __frcp_rn(fmaf(0.3275911f, ax, 1.0f));
;   float poly = fmaf(1.061405429f, t, -1.453152027f);
;   poly = fmaf(poly, t, 1.421413741f);
;   poly = fmaf(poly, t, -0.284496736f);
;   poly = fmaf(poly, t, 0.254829592f);
;   const float y = 1.0f - poly * t * __expf(-ax * ax);
;   return copysignf(y, x);
; }
; __device__ __forceinline__ float gelu_exact(float x) { return 0.5f * x * (1.0f + erf_f32(x * 0.70710678118654752f)); }
; template <int EPI>
; __device__ __forceinline__ void phase_gemm(const Params& p, const GemmDesc& d, char* shmc) {
;     ...
; #pragma unroll
;       for (int n = 0; n < 2; ++n) {
;         const int col = ewc * 32 + n * 16 + efr;
;         const int ch = ch0 + col;
;         const float w0 = cw[n][0], w1 = cw[n][1], w2 = cw[n][2], cb = cw[n][3];
; #pragma unroll
;         for (int ai = 0; ai < 2; ++ai)
; #pragma unroll
;           for (int m = 0; m < 4; ++m) {
;             const int s = ai * 32 + ewr * 16 + m * 4 + efq;
;             const f32x4 g = acc[ai][0][m][n];
;             const f32x4 v = acc[ai][1][m][n];
;             const float c0 = w0 * gp[ai][m][n] + w1 * g[0] + w2 * g[1] + cb;
;             const float c1 = w0 * g[0] + w1 * g[1] + w2 * g[2] + cb;
;             const float c2 = w0 * g[1] + w1 * g[2] + w2 * g[3] + cb;
;             const float c3 = w0 * g[2] + w1 * g[3] + w2 * gn[ai][m][n] + cb;
;             u16* sp = stg + (s * 4) * 136 + col;
;             sp[0] = f2bf(gelu_exact(c0) * v[0]);
;             sp[136] = f2bf(gelu_exact(c1) * v[1]);
;             sp[272] = f2bf(gelu_exact(c2) * v[2]);
;             sp[408] = f2bf(gelu_exact(c3) * v[3]);
;             if (s == 0) {
;               edge[0 * DFF + ch] = c0; edge[1 * DFF + ch] = g[0]; edge[2 * DFF + ch] = v[0];
;             }
;             if (s == 63) {
;               edge[3 * DFF + ch] = c3; edge[4 * DFF + ch] = g[3]; edge[5 * DFF + ch] = v[3];
;             }
;           }
	v_mul_f32_e32 v83, 0x3f596d27, v84
	v_fmac_f32_e32 v82, v216, v179
	v_fma_f32 v87, |v83|, s98, 1.0
	v_add_f32_e32 v85, v218, v82
	v_mul_f32_e32 v82, v217, v179
	v_fmac_f32_e32 v82, v215, v178
	v_fmac_f32_e32 v82, v216, v114
	v_add_f32_e32 v86, v218, v82
	v_add_u32_e32 v82, 0x9900, v220
	v_add_u32_e32 v91, v222, v82
	v_cvt_pk_bf16_f32 v76, v76, s0
	ds_write_b16 v91, v76
	v_mul_f32_e32 v76, 0.5, v84
	v_rcp_f32_e32 v84, v87
	v_mul_f32_e64 v88, |v83|, -|v83|
	v_fmamk_f32 v87, v84, 0x3f87dc22, v206
	v_fmaak_f32 v87, v87, v84, 0x3fb5f0e3
	v_exp_f32_e32 v88, v88
	v_fmaak_f32 v87, v87, v84, 0xbe91a98e
	v_fmaak_f32 v87, v87, v84, 0x3e827906
	v_mul_f32_e32 v84, v84, v87
	v_fma_f32 v83, -v88, v84, 1.0
	v_fma_f32 v76, |v76|, v83, v76
	v_mul_f32_e32 v76, v77, v76
	v_mul_f32_e32 v77, 0x3f596d27, v85
	v_fma_f32 v83, |v77|, s98, 1.0
	v_cvt_pk_bf16_f32 v76, v76, s0
	ds_write_b16 v91, v76 offset:272
	v_mul_f32_e32 v76, 0.5, v85
	v_rcp_f32_e32 v83, v83
	v_mul_f32_e64 v85, |v77|, -|v77|
	v_fmamk_f32 v84, v83, 0x3f87dc22, v206
	v_fmaak_f32 v84, v84, v83, 0x3fb5f0e3
	v_exp_f32_e32 v85, v85
	v_fmaak_f32 v84, v84, v83, 0xbe91a98e
	v_fmaak_f32 v84, v84, v83, 0x3e827906
	v_mul_f32_e32 v83, v83, v84
	v_fma_f32 v77, -v85, v83, 1.0
	v_fma_f32 v76, |v76|, v77, v76
	v_mul_f32_e32 v74, v74, v76
	v_mul_f32_e32 v76, 0x3f596d27, v86
	v_fma_f32 v77, |v76|, s98, 1.0
	v_cvt_pk_bf16_f32 v74, v74, s0
	ds_write_b16 v91, v74 offset:544
	v_mul_f32_e32 v74, 0.5, v86
	v_rcp_f32_e32 v77, v77
	v_mul_f32_e64 v84, |v76|, -|v76|
	v_fmamk_f32 v83, v77, 0x3f87dc22, v206
	v_fmaak_f32 v83, v83, v77, 0x3fb5f0e3
	v_exp_f32_e32 v84, v84
	v_fmaak_f32 v83, v83, v77, 0xbe91a98e
	v_fmaak_f32 v83, v83, v77, 0x3e827906
	v_mul_f32_e32 v77, v77, v83
	v_fma_f32 v76, -v84, v77, 1.0
	v_fma_f32 v74, |v74|, v76, v74
	v_mul_f32_e32 v74, v75, v74
	v_cvt_pk_bf16_f32 v74, v74, s0
	ds_write_b16 v91, v74 offset:816
	v_mul_f32_e32 v74, v215, v108
	v_fmac_f32_e32 v74, v217, v160
	v_fmac_f32_e32 v74, v216, v161
	v_add_f32_e32 v75, v218, v74
	v_mul_f32_e32 v84, 0x3f596d27, v75
	v_fma_f32 v85, |v84|, s98, 1.0
	v_mul_f32_e32 v74, v217, v161
	v_fmac_f32_e32 v74, v215, v160
	v_fmac_f32_e32 v74, v216, v156
	v_rcp_f32_e32 v85, v85
	v_mul_f32_e64 v87, |v84|, -|v84|
	v_fmamk_f32 v86, v85, 0x3f87dc22, v206
	v_fmaak_f32 v86, v86, v85, 0x3fb5f0e3
	v_exp_f32_e32 v87, v87
	v_fmaak_f32 v86, v86, v85, 0xbe91a98e
	v_fmaak_f32 v86, v86, v85, 0x3e827906
	v_mul_f32_e32 v85, v85, v86
	v_fma_f32 v84, -v87, v85, 1.0
	v_mul_f32_e32 v75, 0.5, v75
	v_add_f32_e32 v76, v218, v74
	v_mul_f32_e32 v74, v217, v156
	v_fma_f32 v75, |v75|, v84, v75
	v_fmac_f32_e32 v74, v215, v161
	v_mul_f32_e32 v72, v72, v75
	v_mul_f32_e32 v75, 0x3f596d27, v76
	v_fmac_f32_e32 v74, v216, v157
	v_fma_f32 v84, |v75|, s98, 1.0
	v_add_f32_e32 v77, v218, v74
	v_mul_f32_e32 v74, v217, v157
	v_fmac_f32_e32 v74, v215, v156
	v_fmac_f32_e32 v74, v216, v106
	v_add_f32_e32 v83, v218, v74
	v_add_u32_e32 v74, 0xaa00, v220
	v_add_u32_e32 v88, v222, v74
	v_cvt_pk_bf16_f32 v72, v72, s0
	ds_write_b16 v88, v72
	v_mul_f32_e32 v72, 0.5, v76
	v_rcp_f32_e32 v76, v84
	v_mul_f32_e64 v85, |v75|, -|v75|
	v_fmamk_f32 v84, v76, 0x3f87dc22, v206
	v_fmaak_f32 v84, v84, v76, 0x3fb5f0e3
	v_exp_f32_e32 v85, v85
	v_fmaak_f32 v84, v84, v76, 0xbe91a98e
	v_fmaak_f32 v84, v84, v76, 0x3e827906
	v_mul_f32_e32 v76, v76, v84
	v_fma_f32 v75, -v85, v76, 1.0
	v_fma_f32 v72, |v72|, v75, v72
	v_mul_f32_e32 v72, v73, v72
	v_mul_f32_e32 v73, 0x3f596d27, v77
	v_fma_f32 v75, |v73|, s98, 1.0
	v_cvt_pk_bf16_f32 v72, v72, s0
	ds_write_b16 v88, v72 offset:272
	v_mul_f32_e32 v72, 0.5, v77
	v_rcp_f32_e32 v75, v75
	v_mul_f32_e64 v77, |v73|, -|v73|
	v_fmamk_f32 v76, v75, 0x3f87dc22, v206
	v_fmaak_f32 v76, v76, v75, 0x3fb5f0e3
	v_exp_f32_e32 v77, v77
	v_fmaak_f32 v76, v76, v75, 0xbe91a98e
	v_fmaak_f32 v76, v76, v75, 0x3e827906
	v_mul_f32_e32 v75, v75, v76
	v_fma_f32 v73, -v77, v75, 1.0
	v_fma_f32 v72, |v72|, v73, v72
	v_mul_f32_e32 v70, v70, v72
	v_mul_f32_e32 v72, 0x3f596d27, v83
	v_fma_f32 v73, |v72|, s98, 1.0
	v_cvt_pk_bf16_f32 v70, v70, s0
	ds_write_b16 v88, v70 offset:544
	v_mul_f32_e32 v70, 0.5, v83
	v_rcp_f32_e32 v73, v73
	v_mul_f32_e64 v76, |v72|, -|v72|
	v_fmamk_f32 v75, v73, 0x3f87dc22, v206
	v_fmaak_f32 v75, v75, v73, 0x3fb5f0e3
	v_exp_f32_e32 v76, v76
	v_fmaak_f32 v75, v75, v73, 0xbe91a98e
	v_fmaak_f32 v75, v75, v73, 0x3e827906
	v_mul_f32_e32 v73, v73, v75
	v_fma_f32 v72, -v76, v73, 1.0
	v_fma_f32 v70, |v70|, v72, v70
	v_mul_f32_e32 v70, v71, v70
	v_cvt_pk_bf16_f32 v70, v70, s0
	ds_write_b16 v88, v70 offset:816
	s_waitcnt lgkmcnt(14)
; __device__ __forceinline__ u16 f2bf(float f) { return (u16)(pack2(f, f) & 0xffffu); }
; __device__ __forceinline__ float erf_f32(float x) {
;   const float ax = fabsf(x);
;   const float t = __frcp_rn(fmaf(0.3275911f, ax, 1.0f));
;   float poly = fmaf(1.061405429f, t, -1.453152027f);
;   poly = fmaf(poly, t, 1.421413741f);
;   poly = fmaf(poly, t, -0.284496736f);
;   poly = fmaf(poly, t, 0.254829592f);
;   const float y = 1.0f - poly * t * __expf(-ax * ax);
;   return copysignf(y, x);
; }
; __device__ __forceinline__ float gelu_exact(float x) { return 0.5f * x * (1.0f + erf_f32(x * 0.70710678118654752f)); }
; template <int EPI>
; __device__ __forceinline__ void phase_gemm(const Params& p, const GemmDesc& d, char* shmc) {
;     ...
; #pragma unroll
;       for (int n = 0; n < 2; ++n) {
;         const int col = ewc * 32 + n * 16 + efr;
;         const int ch = ch0 + col;
;         const float w0 = cw[n][0], w1 = cw[n][1], w2 = cw[n][2], cb = cw[n][3];
; #pragma unroll
;         for (int ai = 0; ai < 2; ++ai)
; #pragma unroll
;           for (int m = 0; m < 4; ++m) {
;             const int s = ai * 32 + ewr * 16 + m * 4 + efq;
;             const f32x4 g = acc[ai][0][m][n];
;             const f32x4 v = acc[ai][1][m][n];
;             const float c0 = w0 * gp[ai][m][n] + w1 * g[0] + w2 * g[1] + cb;
;             const float c1 = w0 * g[0] + w1 * g[1] + w2 * g[2] + cb;
;             const float c2 = w0 * g[1] + w1 * g[2] + w2 * g[3] + cb;
;             const float c3 = w0 * g[2] + w1 * g[3] + w2 * gn[ai][m][n] + cb;
;             u16* sp = stg + (s * 4) * 136 + col;
;             sp[0] = f2bf(gelu_exact(c0) * v[0]);
;             sp[136] = f2bf(gelu_exact(c1) * v[1]);
;             sp[272] = f2bf(gelu_exact(c2) * v[2]);
;             sp[408] = f2bf(gelu_exact(c3) * v[3]);
;             if (s == 0) {
;               edge[0 * DFF + ch] = c0; edge[1 * DFF + ch] = g[0]; edge[2 * DFF + ch] = v[0];
;             }
;             if (s == 63) {
;               edge[3 * DFF + ch] = c3; edge[4 * DFF + ch] = g[3]; edge[5 * DFF + ch] = v[3];
;             }
;           }
	v_mul_f32_e32 v70, v215, v221
	v_fmac_f32_e32 v70, v217, v154
	v_fmac_f32_e32 v70, v216, v155
	v_add_f32_e32 v72, v218, v70
	v_mul_f32_e32 v76, 0x3f596d27, v72
	v_fma_f32 v77, |v76|, s98, 1.0
	v_mul_f32_e32 v70, v217, v155
	v_fmac_f32_e32 v70, v215, v154
	v_fmac_f32_e32 v70, v216, v152
	v_rcp_f32_e32 v77, v77
	v_mul_f32_e64 v84, |v76|, -|v76|
	v_fmamk_f32 v83, v77, 0x3f87dc22, v206
	v_fmaak_f32 v83, v83, v77, 0x3fb5f0e3
	v_exp_f32_e32 v84, v84
	v_fmaak_f32 v83, v83, v77, 0xbe91a98e
	v_fmaak_f32 v83, v83, v77, 0x3e827906
	v_mul_f32_e32 v77, v77, v83
	v_fma_f32 v76, -v84, v77, 1.0
	v_mul_f32_e32 v72, 0.5, v72
	v_add_f32_e32 v73, v218, v70
	v_mul_f32_e32 v70, v217, v152
	v_fma_f32 v72, |v72|, v76, v72
	v_fmac_f32_e32 v70, v215, v155
	v_mul_f32_e32 v68, v68, v72
	v_mul_f32_e32 v72, 0x3f596d27, v73
	v_fmac_f32_e32 v70, v216, v153
	v_fma_f32 v76, |v72|, s98, 1.0
	v_add_f32_e32 v75, v218, v70
	v_mul_f32_e32 v70, v217, v153
	v_fmac_f32_e32 v70, v215, v152
	v_fmac_f32_e32 v70, v216, v219
	v_add_f32_e32 v71, v218, v70
	v_add_u32_e32 v70, 0xbb00, v220
	v_add_u32_e32 v85, v222, v70
	v_cvt_pk_bf16_f32 v68, v68, s0
	ds_write_b16 v85, v68
	v_mul_f32_e32 v68, 0.5, v73
	v_rcp_f32_e32 v73, v76
	v_mul_f32_e64 v77, |v72|, -|v72|
	v_fmamk_f32 v76, v73, 0x3f87dc22, v206
	v_fmaak_f32 v76, v76, v73, 0x3fb5f0e3
	v_exp_f32_e32 v77, v77
	v_fmaak_f32 v76, v76, v73, 0xbe91a98e
	v_fmaak_f32 v76, v76, v73, 0x3e827906
	v_mul_f32_e32 v73, v73, v76
	v_fma_f32 v72, -v77, v73, 1.0
	v_fma_f32 v68, |v68|, v72, v68
	v_mul_f32_e32 v68, v69, v68
	v_mul_f32_e32 v69, 0x3f596d27, v75
	v_fma_f32 v72, |v69|, s98, 1.0
	v_cvt_pk_bf16_f32 v68, v68, s0
	ds_write_b16 v85, v68 offset:272
	v_mul_f32_e32 v68, 0.5, v75
	v_rcp_f32_e32 v72, v72
	v_mul_f32_e64 v75, |v69|, -|v69|
	v_fmamk_f32 v73, v72, 0x3f87dc22, v206
	v_fmaak_f32 v73, v73, v72, 0x3fb5f0e3
	v_exp_f32_e32 v75, v75
	v_fmaak_f32 v73, v73, v72, 0xbe91a98e
	v_fmaak_f32 v73, v73, v72, 0x3e827906
	v_mul_f32_e32 v72, v72, v73
	v_fma_f32 v69, -v75, v72, 1.0
	v_fma_f32 v68, |v68|, v69, v68
	v_mul_f32_e32 v66, v66, v68
	v_mul_f32_e32 v68, 0x3f596d27, v71
	v_fma_f32 v69, |v68|, s98, 1.0
	v_cvt_pk_bf16_f32 v66, v66, s0
	ds_write_b16 v85, v66 offset:544
	v_mul_f32_e32 v66, 0.5, v71
	v_rcp_f32_e32 v69, v69
	v_mul_f32_e64 v73, |v68|, -|v68|
	v_fmamk_f32 v72, v69, 0x3f87dc22, v206
	v_fmaak_f32 v72, v72, v69, 0x3fb5f0e3
	v_exp_f32_e32 v73, v73
	v_fmaak_f32 v72, v72, v69, 0xbe91a98e
	v_fmaak_f32 v72, v72, v69, 0x3e827906
	v_mul_f32_e32 v69, v69, v72
	v_fma_f32 v68, -v73, v69, 1.0
	v_fma_f32 v66, |v66|, v68, v66
	v_mul_f32_e32 v66, v67, v66
	v_cvt_pk_bf16_f32 v66, v66, s0
	ds_write_b16 v85, v66 offset:816
	s_and_saveexec_b64 s[78:79], s[8:9]
	s_cbranch_execz .LBB0_311
	v_add_co_u32_e32 v68, vcc, 0x10000, v94
	s_nop 1
	v_addc_co_u32_e32 v69, vcc, 0, v95, vcc
	global_store_dword v[68:69], v71, off offset:2048
	v_add_co_u32_e32 v68, vcc, 0x16000, v94
	s_nop 1
	v_addc_co_u32_e32 v69, vcc, 0, v95, vcc
	global_store_dword v[68:69], v153, off
	v_add_co_u32_e32 v68, vcc, 0x1b000, v94
	s_nop 1
	v_addc_co_u32_e32 v69, vcc, 0, v95, vcc
	global_store_dword v[68:69], v67, off offset:2048
.LBB0_311:
	s_or_b64 exec, exec, s[78:79]
	v_pk_mul_f32 v[64:65], v[60:61], v[64:65]
	v_pk_mul_f32 v[60:61], v[58:59], v[62:63]
	v_mul_f32_e32 v62, v209, v213
	v_fmac_f32_e32 v62, v210, v146
	v_fmac_f32_e32 v62, v208, v147
	v_add_f32_e32 v63, v207, v62
	v_mul_f32_e32 v71, 0x3f596d27, v63
	v_fma_f32 v72, |v71|, s98, 1.0
	v_mul_f32_e32 v62, v210, v147
	v_fmac_f32_e32 v62, v209, v146
	v_fmac_f32_e32 v62, v208, v158
	v_rcp_f32_e32 v72, v72
	v_mul_f32_e64 v75, |v71|, -|v71|
	v_fmamk_f32 v73, v72, 0x3f87dc22, v206
	v_fmaak_f32 v73, v73, v72, 0x3fb5f0e3
	v_exp_f32_e32 v75, v75
	v_fmaak_f32 v73, v73, v72, 0xbe91a98e
	v_fmaak_f32 v73, v73, v72, 0x3e827906
	v_mul_f32_e32 v72, v72, v73
	v_add_f32_e32 v67, v207, v62
	v_mul_f32_e32 v62, v210, v158
	v_fma_f32 v71, -v75, v72, 1.0
	v_fmac_f32_e32 v62, v209, v147
	v_mul_f32_e32 v72, 0x3f596d27, v67
	v_fmac_f32_e32 v62, v208, v159
	v_fma_f32 v73, |v72|, s98, 1.0
	v_add_f32_e32 v68, v207, v62
	v_mul_f32_e32 v62, v210, v159
	v_mul_f32_e32 v76, 0.5, v63
	v_fmac_f32_e32 v62, v209, v158
	v_fma_f32 v71, |v76|, v71, v76
	v_or_b32_e32 v66, 16, v162
	v_fmac_f32_e32 v62, v208, v214
	v_add_f32_e32 v69, v207, v62
	v_lshlrev_b32_e32 v62, 1, v66
	v_mul_f32_e32 v71, v60, v71
	v_add3_u32 v66, s14, v220, v62
	v_cvt_pk_bf16_f32 v71, v71, s0
	ds_write_b16 v66, v71
	v_rcp_f32_e32 v71, v73
	v_mul_f32_e64 v75, |v72|, -|v72|
	v_fmamk_f32 v73, v71, 0x3f87dc22, v206
	v_fmaak_f32 v73, v73, v71, 0x3fb5f0e3
	v_exp_f32_e32 v75, v75
	v_fmaak_f32 v73, v73, v71, 0xbe91a98e
	v_fmaak_f32 v73, v73, v71, 0x3e827906
	v_mul_f32_e32 v71, v71, v73
	v_fma_f32 v71, -v75, v71, 1.0
	v_mul_f32_e32 v67, 0.5, v67
	v_fma_f32 v67, |v67|, v71, v67
	v_mul_f32_e32 v61, v61, v67
	v_mul_f32_e32 v67, 0x3f596d27, v68
	v_fma_f32 v71, |v67|, s98, 1.0
	v_cvt_pk_bf16_f32 v61, v61, s0
	ds_write_b16 v66, v61 offset:272
	v_mul_f32_e32 v61, 0.5, v68
	v_rcp_f32_e32 v68, v71
	v_mul_f32_e64 v72, |v67|, -|v67|
	v_fmamk_f32 v71, v68, 0x3f87dc22, v206
	v_fmaak_f32 v71, v71, v68, 0x3fb5f0e3
	v_exp_f32_e32 v72, v72
	v_fmaak_f32 v71, v71, v68, 0xbe91a98e
	v_fmaak_f32 v71, v71, v68, 0x3e827906
	v_mul_f32_e32 v68, v68, v71
	v_fma_f32 v67, -v72, v68, 1.0
	v_fma_f32 v61, |v61|, v67, v61
	v_mul_f32_e32 v61, v64, v61
	v_mul_f32_e32 v64, 0x3f596d27, v69
	v_fma_f32 v67, |v64|, s98, 1.0
	v_cvt_pk_bf16_f32 v61, v61, s0
	ds_write_b16 v66, v61 offset:544
	v_mul_f32_e32 v61, 0.5, v69
	v_rcp_f32_e32 v67, v67
	v_mul_f32_e64 v69, |v64|, -|v64|
	v_fmamk_f32 v68, v67, 0x3f87dc22, v206
	v_fmaak_f32 v68, v68, v67, 0x3fb5f0e3
	v_exp_f32_e32 v69, v69
	v_fmaak_f32 v68, v68, v67, 0xbe91a98e
	v_fmaak_f32 v68, v68, v67, 0x3e827906
	v_mul_f32_e32 v67, v67, v68
	v_fma_f32 v64, -v69, v67, 1.0
	s_ashr_i32 s63, s62, 31
	v_lshl_add_u64 v[58:59], v[162:163], 0, s[62:63]
	v_fma_f32 v61, |v61|, v64, v61
	v_lshl_add_u64 v[58:59], v[58:59], 2, s[64:65]
	v_mul_f32_e32 v61, v65, v61
	v_lshl_add_u64 v[58:59], v[58:59], 0, 64
	v_cvt_pk_bf16_f32 v61, v61, s0
	ds_write_b16 v66, v61 offset:816
	s_and_saveexec_b64 s[64:65], s[10:11]
	s_cbranch_execz .LBB0_313
	v_add_co_u32_e32 v64, vcc, 0x5000, v58
	global_store_dword v[58:59], v63, off
	s_nop 0
	v_addc_co_u32_e32 v65, vcc, 0, v59, vcc
	global_store_dword v[64:65], v146, off offset:2048
	v_add_co_u32_e32 v64, vcc, 0xb000, v58
	s_nop 1
	v_addc_co_u32_e32 v65, vcc, 0, v59, vcc
	global_store_dword v[64:65], v60, off
; __device__ __forceinline__ u16 f2bf(float f) { return (u16)(pack2(f, f) & 0xffffu); }
; __device__ __forceinline__ float erf_f32(float x) {
;   const float ax = fabsf(x);
;   const float t = __frcp_rn(fmaf(0.3275911f, ax, 1.0f));
;   float poly = fmaf(1.061405429f, t, -1.453152027f);
;   poly = fmaf(poly, t, 1.421413741f);
;   poly = fmaf(poly, t, -0.284496736f);
;   poly = fmaf(poly, t, 0.254829592f);
;   const float y = 1.0f - poly * t * __expf(-ax * ax);
;   return copysignf(y, x);
; }
; __device__ __forceinline__ float gelu_exact(float x) { return 0.5f * x * (1.0f + erf_f32(x * 0.70710678118654752f)); }
; template <int EPI>
; __device__ __forceinline__ void phase_gemm(const Params& p, const GemmDesc& d, char* shmc) {
;     ...
; #pragma unroll
;       for (int n = 0; n < 2; ++n) {
;         const int col = ewc * 32 + n * 16 + efr;
;         const int ch = ch0 + col;
;         const float w0 = cw[n][0], w1 = cw[n][1], w2 = cw[n][2], cb = cw[n][3];
; #pragma unroll
;         for (int ai = 0; ai < 2; ++ai)
; #pragma unroll
;           for (int m = 0; m < 4; ++m) {
;             const int s = ai * 32 + ewr * 16 + m * 4 + efq;
;             const f32x4 g = acc[ai][0][m][n];
;             const f32x4 v = acc[ai][1][m][n];
;             const float c0 = w0 * gp[ai][m][n] + w1 * g[0] + w2 * g[1] + cb;
;             const float c1 = w0 * g[0] + w1 * g[1] + w2 * g[2] + cb;
;             const float c2 = w0 * g[1] + w1 * g[2] + w2 * g[3] + cb;
;             const float c3 = w0 * g[2] + w1 * g[3] + w2 * gn[ai][m][n] + cb;
;             u16* sp = stg + (s * 4) * 136 + col;
;             sp[0] = f2bf(gelu_exact(c0) * v[0]);
;             sp[136] = f2bf(gelu_exact(c1) * v[1]);
;             sp[272] = f2bf(gelu_exact(c2) * v[2]);
;             sp[408] = f2bf(gelu_exact(c3) * v[3]);
;             if (s == 0) {
;               edge[0 * DFF + ch] = c0; edge[1 * DFF + ch] = g[0]; edge[2 * DFF + ch] = v[0];
;             }
;             if (s == 63) {
;               edge[3 * DFF + ch] = c3; edge[4 * DFF + ch] = g[3]; edge[5 * DFF + ch] = v[3];
;             }
;           }
.LBB0_313:
	s_or_b64 exec, exec, s[64:65]
	v_pk_mul_f32 v[48:49], v[4:5], v[48:49]
	v_pk_mul_f32 v[4:5], v[14:15], v[30:31]
	v_mul_f32_e32 v14, v209, v151
	v_fmac_f32_e32 v14, v210, v144
	v_fmac_f32_e32 v14, v208, v145
	v_add_f32_e32 v14, v207, v14
	v_pk_mul_f32 v[52:53], v[8:9], v[52:53]
	v_pk_mul_f32 v[8:9], v[18:19], v[34:35]
	v_mul_f32_e32 v18, 0x3f596d27, v14
	v_fma_f32 v19, |v18|, s98, 1.0
	v_pk_mul_f32 v[50:51], v[6:7], v[50:51]
	v_pk_mul_f32 v[6:7], v[20:21], v[36:37]
	v_pk_mul_f32 v[56:57], v[12:13], v[56:57]
	v_pk_mul_f32 v[12:13], v[22:23], v[38:39]
	v_pk_mul_f32 v[54:55], v[10:11], v[54:55]
	v_pk_mul_f32 v[10:11], v[24:25], v[40:41]
	v_rcp_f32_e32 v19, v19
	v_mul_f32_e64 v21, |v18|, -|v18|
	v_fmamk_f32 v20, v19, 0x3f87dc22, v206
	v_fmaak_f32 v20, v20, v19, 0x3fb5f0e3
	v_exp_f32_e32 v21, v21
	v_fmaak_f32 v20, v20, v19, 0xbe91a98e
	v_fmaak_f32 v20, v20, v19, 0x3e827906
	v_mul_f32_e32 v15, v210, v145
	v_mul_f32_e32 v19, v19, v20
	v_fmac_f32_e32 v15, v209, v144
	v_fma_f32 v18, -v21, v19, 1.0
	v_fmac_f32_e32 v15, v208, v142
	v_add_f32_e32 v15, v207, v15
	v_mul_f32_e32 v14, 0.5, v14
	v_fma_f32 v14, |v14|, v18, v14
	v_mul_f32_e32 v18, 0x3f596d27, v15
	v_fma_f32 v19, |v18|, s98, 1.0
	v_mul_f32_e32 v14, v54, v14
	v_add3_u32 v22, s14, v78, v62
	v_cvt_pk_bf16_f32 v14, v14, s0
	ds_write_b16 v22, v14
	v_mul_f32_e32 v14, 0.5, v15
	v_rcp_f32_e32 v15, v19
	v_mul_f32_e64 v20, |v18|, -|v18|
	v_fmamk_f32 v19, v15, 0x3f87dc22, v206
	v_fmaak_f32 v19, v19, v15, 0x3fb5f0e3
	v_exp_f32_e32 v20, v20
	v_fmaak_f32 v19, v19, v15, 0xbe91a98e
	v_fmaak_f32 v19, v19, v15, 0x3e827906
	v_pk_mul_f32 v[46:47], v[2:3], v[46:47]
	v_pk_mul_f32 v[2:3], v[16:17], v[32:33]
	v_mul_f32_e32 v16, v210, v142
	v_mul_f32_e32 v15, v15, v19
	v_fmac_f32_e32 v16, v209, v145
	v_fma_f32 v15, -v20, v15, 1.0
	v_fmac_f32_e32 v16, v208, v143
	v_add_f32_e32 v16, v207, v16
	v_fma_f32 v14, |v14|, v15, v14
	v_mul_f32_e32 v15, 0x3f596d27, v16
	v_fma_f32 v18, |v15|, s98, 1.0
	v_mul_f32_e32 v14, v55, v14
	v_cvt_pk_bf16_f32 v14, v14, s0
	ds_write_b16 v22, v14 offset:272
	v_mul_f32_e32 v14, 0.5, v16
	v_rcp_f32_e32 v16, v18
	v_mul_f32_e64 v19, |v15|, -|v15|
	v_fmamk_f32 v18, v16, 0x3f87dc22, v206
	v_fmaak_f32 v18, v18, v16, 0x3fb5f0e3
	v_exp_f32_e32 v19, v19
	v_fmaak_f32 v18, v18, v16, 0xbe91a98e
	v_fmaak_f32 v18, v18, v16, 0x3e827906
	v_mul_f32_e32 v17, v210, v143
	v_mul_f32_e32 v16, v16, v18
	v_fmac_f32_e32 v17, v209, v142
	v_fma_f32 v15, -v19, v16, 1.0
	v_fmac_f32_e32 v17, v208, v149
	v_add_f32_e32 v17, v207, v17
	v_fma_f32 v14, |v14|, v15, v14
	v_mul_f32_e32 v15, 0x3f596d27, v17
	v_fma_f32 v16, |v15|, s98, 1.0
	v_mul_f32_e32 v14, v56, v14
	v_cvt_pk_bf16_f32 v14, v14, s0
	ds_write_b16 v22, v14 offset:544
	v_mul_f32_e32 v14, 0.5, v17
	v_rcp_f32_e32 v16, v16
	v_mul_f32_e64 v18, |v15|, -|v15|
	v_fmamk_f32 v17, v16, 0x3f87dc22, v206
	v_fmaak_f32 v17, v17, v16, 0x3fb5f0e3
	v_exp_f32_e32 v18, v18
	v_fmaak_f32 v17, v17, v16, 0xbe91a98e
	v_fmaak_f32 v17, v17, v16, 0x3e827906
	v_mul_f32_e32 v16, v16, v17
	v_fma_f32 v15, -v18, v16, 1.0
	v_fma_f32 v14, |v14|, v15, v14
	v_mul_f32_e32 v14, v57, v14
	v_cvt_pk_bf16_f32 v14, v14, s0
	ds_write_b16 v22, v14 offset:816
	v_mul_f32_e32 v14, v209, v141
	v_fmac_f32_e32 v14, v210, v136
	v_fmac_f32_e32 v14, v208, v137
	v_add_f32_e32 v14, v207, v14
	v_mul_f32_e32 v18, 0x3f596d27, v14
	v_fma_f32 v19, |v18|, s98, 1.0
	v_mul_f32_e32 v15, v210, v137
	v_fmac_f32_e32 v15, v209, v136
	v_fmac_f32_e32 v15, v208, v134
	v_rcp_f32_e32 v19, v19
	v_mul_f32_e64 v21, |v18|, -|v18|
	v_fmamk_f32 v20, v19, 0x3f87dc22, v206
	v_fmaak_f32 v20, v20, v19, 0x3fb5f0e3
	v_exp_f32_e32 v21, v21
	v_fmaak_f32 v20, v20, v19, 0xbe91a98e
	v_fmaak_f32 v20, v20, v19, 0x3e827906
	v_mul_f32_e32 v19, v19, v20
	v_fma_f32 v18, -v21, v19, 1.0
	v_add_f32_e32 v15, v207, v15
	v_mul_f32_e32 v14, 0.5, v14
	v_fma_f32 v14, |v14|, v18, v14
	v_mul_f32_e32 v18, 0x3f596d27, v15
	v_fma_f32 v19, |v18|, s98, 1.0
	v_mul_f32_e32 v14, v50, v14
	v_add3_u32 v22, s14, v79, v62
	v_cvt_pk_bf16_f32 v14, v14, s0
	ds_write_b16 v22, v14
	v_mul_f32_e32 v14, 0.5, v15
	v_rcp_f32_e32 v15, v19
	v_mul_f32_e64 v20, |v18|, -|v18|
	v_fmamk_f32 v19, v15, 0x3f87dc22, v206
	v_fmaak_f32 v19, v19, v15, 0x3fb5f0e3
	v_exp_f32_e32 v20, v20
	v_fmaak_f32 v19, v19, v15, 0xbe91a98e
	v_fmaak_f32 v19, v19, v15, 0x3e827906
	v_mul_f32_e32 v16, v210, v134
	v_mul_f32_e32 v15, v15, v19
	v_fmac_f32_e32 v16, v209, v137
	v_fma_f32 v15, -v20, v15, 1.0
	v_fmac_f32_e32 v16, v208, v135
	v_add_f32_e32 v16, v207, v16
	v_fma_f32 v14, |v14|, v15, v14
	v_mul_f32_e32 v15, 0x3f596d27, v16
	v_fma_f32 v18, |v15|, s98, 1.0
	v_mul_f32_e32 v14, v51, v14
	v_cvt_pk_bf16_f32 v14, v14, s0
	ds_write_b16 v22, v14 offset:272
	v_mul_f32_e32 v14, 0.5, v16
	v_rcp_f32_e32 v16, v18
	v_mul_f32_e64 v19, |v15|, -|v15|
	v_fmamk_f32 v18, v16, 0x3f87dc22, v206
	v_fmaak_f32 v18, v18, v16, 0x3fb5f0e3
	v_exp_f32_e32 v19, v19
	v_fmaak_f32 v18, v18, v16, 0xbe91a98e
	v_fmaak_f32 v18, v18, v16, 0x3e827906
	v_mul_f32_e32 v17, v210, v135
	v_mul_f32_e32 v16, v16, v18
	v_fmac_f32_e32 v17, v209, v134
	v_fma_f32 v15, -v19, v16, 1.0
	v_fmac_f32_e32 v17, v208, v139
	v_add_f32_e32 v17, v207, v17
	v_fma_f32 v14, |v14|, v15, v14
	v_mul_f32_e32 v15, 0x3f596d27, v17
	v_fma_f32 v16, |v15|, s98, 1.0
	v_mul_f32_e32 v14, v52, v14
	v_cvt_pk_bf16_f32 v14, v14, s0
	ds_write_b16 v22, v14 offset:544
	v_mul_f32_e32 v14, 0.5, v17
	v_rcp_f32_e32 v16, v16
	v_mul_f32_e64 v18, |v15|, -|v15|
	v_fmamk_f32 v17, v16, 0x3f87dc22, v206
	v_fmaak_f32 v17, v17, v16, 0x3fb5f0e3
	v_exp_f32_e32 v18, v18
	v_fmaak_f32 v17, v17, v16, 0xbe91a98e
	v_fmaak_f32 v17, v17, v16, 0x3e827906
	v_mul_f32_e32 v16, v16, v17
	v_fma_f32 v15, -v18, v16, 1.0
; __device__ __forceinline__ u16 f2bf(float f) { return (u16)(pack2(f, f) & 0xffffu); }
; __device__ __forceinline__ float erf_f32(float x) {
;   const float ax = fabsf(x);
;   const float t = __frcp_rn(fmaf(0.3275911f, ax, 1.0f));
;   float poly = fmaf(1.061405429f, t, -1.453152027f);
;   poly = fmaf(poly, t, 1.421413741f);
;   poly = fmaf(poly, t, -0.284496736f);
;   poly = fmaf(poly, t, 0.254829592f);
;   const float y = 1.0f - poly * t * __expf(-ax * ax);
;   return copysignf(y, x);
; }
; __device__ __forceinline__ float gelu_exact(float x) { return 0.5f * x * (1.0f + erf_f32(x * 0.70710678118654752f)); }
; template <int EPI>
; __device__ __forceinline__ void phase_gemm(const Params& p, const GemmDesc& d, char* shmc) {
;     ...
; #pragma unroll
;       for (int n = 0; n < 2; ++n) {
;         const int col = ewc * 32 + n * 16 + efr;
;         const int ch = ch0 + col;
;         const float w0 = cw[n][0], w1 = cw[n][1], w2 = cw[n][2], cb = cw[n][3];
; #pragma unroll
;         for (int ai = 0; ai < 2; ++ai)
; #pragma unroll
;           for (int m = 0; m < 4; ++m) {
;             const int s = ai * 32 + ewr * 16 + m * 4 + efq;
;             const f32x4 g = acc[ai][0][m][n];
;             const f32x4 v = acc[ai][1][m][n];
;             const float c0 = w0 * gp[ai][m][n] + w1 * g[0] + w2 * g[1] + cb;
;             const float c1 = w0 * g[0] + w1 * g[1] + w2 * g[2] + cb;
;             const float c2 = w0 * g[1] + w1 * g[2] + w2 * g[3] + cb;
;             const float c3 = w0 * g[2] + w1 * g[3] + w2 * gn[ai][m][n] + cb;
;             u16* sp = stg + (s * 4) * 136 + col;
;             sp[0] = f2bf(gelu_exact(c0) * v[0]);
;             sp[136] = f2bf(gelu_exact(c1) * v[1]);
;             sp[272] = f2bf(gelu_exact(c2) * v[2]);
;             sp[408] = f2bf(gelu_exact(c3) * v[3]);
;             if (s == 0) {
;               edge[0 * DFF + ch] = c0; edge[1 * DFF + ch] = g[0]; edge[2 * DFF + ch] = v[0];
;             }
;             if (s == 63) {
;               edge[3 * DFF + ch] = c3; edge[4 * DFF + ch] = g[3]; edge[5 * DFF + ch] = v[3];
;             }
;           }
	v_fma_f32 v14, |v14|, v15, v14
	v_mul_f32_e32 v14, v53, v14
	v_cvt_pk_bf16_f32 v14, v14, s0
	ds_write_b16 v22, v14 offset:816
	v_mul_f32_e32 v14, v209, v133
	v_fmac_f32_e32 v14, v210, v128
	v_fmac_f32_e32 v14, v208, v129
	v_add_f32_e32 v14, v207, v14
	v_mul_f32_e32 v18, 0x3f596d27, v14
	v_fma_f32 v19, |v18|, s98, 1.0
	v_mul_f32_e32 v15, v210, v129
	v_fmac_f32_e32 v15, v209, v128
	v_fmac_f32_e32 v15, v208, v126
	v_rcp_f32_e32 v19, v19
	v_mul_f32_e64 v21, |v18|, -|v18|
	v_fmamk_f32 v20, v19, 0x3f87dc22, v206
	v_fmaak_f32 v20, v20, v19, 0x3fb5f0e3
	v_exp_f32_e32 v21, v21
	v_fmaak_f32 v20, v20, v19, 0xbe91a98e
	v_fmaak_f32 v20, v20, v19, 0x3e827906
	v_mul_f32_e32 v19, v19, v20
	v_fma_f32 v18, -v21, v19, 1.0
	v_add_f32_e32 v15, v207, v15
	v_mul_f32_e32 v14, 0.5, v14
	v_fma_f32 v14, |v14|, v18, v14
	v_mul_f32_e32 v18, 0x3f596d27, v15
	v_fma_f32 v19, |v18|, s98, 1.0
	v_mul_f32_e32 v14, v46, v14
	v_add3_u32 v22, s14, v80, v62
	v_cvt_pk_bf16_f32 v14, v14, s0
	ds_write_b16 v22, v14
	v_mul_f32_e32 v14, 0.5, v15
	v_rcp_f32_e32 v15, v19
	v_mul_f32_e64 v20, |v18|, -|v18|
	v_fmamk_f32 v19, v15, 0x3f87dc22, v206
	v_fmaak_f32 v19, v19, v15, 0x3fb5f0e3
	v_exp_f32_e32 v20, v20
	v_fmaak_f32 v19, v19, v15, 0xbe91a98e
	v_fmaak_f32 v19, v19, v15, 0x3e827906
	v_mul_f32_e32 v16, v210, v126
	v_mul_f32_e32 v15, v15, v19
	v_fmac_f32_e32 v16, v209, v129
	v_fma_f32 v15, -v20, v15, 1.0
	v_fmac_f32_e32 v16, v208, v127
	v_add_f32_e32 v16, v207, v16
	v_fma_f32 v14, |v14|, v15, v14
	v_mul_f32_e32 v15, 0x3f596d27, v16
	v_fma_f32 v18, |v15|, s98, 1.0
	v_mul_f32_e32 v14, v47, v14
	v_cvt_pk_bf16_f32 v14, v14, s0
	ds_write_b16 v22, v14 offset:272
	v_mul_f32_e32 v14, 0.5, v16
	v_rcp_f32_e32 v16, v18
	v_mul_f32_e64 v19, |v15|, -|v15|
	v_fmamk_f32 v18, v16, 0x3f87dc22, v206
	v_fmaak_f32 v18, v18, v16, 0x3fb5f0e3
	v_exp_f32_e32 v19, v19
	v_fmaak_f32 v18, v18, v16, 0xbe91a98e
	v_fmaak_f32 v18, v18, v16, 0x3e827906
	v_mul_f32_e32 v17, v210, v127
	v_mul_f32_e32 v16, v16, v18
	v_fmac_f32_e32 v17, v209, v126
	v_fma_f32 v15, -v19, v16, 1.0
	v_fmac_f32_e32 v17, v208, v131
	v_add_f32_e32 v17, v207, v17
	v_fma_f32 v14, |v14|, v15, v14
	v_mul_f32_e32 v15, 0x3f596d27, v17
	v_fma_f32 v16, |v15|, s98, 1.0
	v_mul_f32_e32 v14, v48, v14
	v_cvt_pk_bf16_f32 v14, v14, s0
	ds_write_b16 v22, v14 offset:544
	v_mul_f32_e32 v14, 0.5, v17
	v_rcp_f32_e32 v16, v16
	v_mul_f32_e64 v18, |v15|, -|v15|
	v_fmamk_f32 v17, v16, 0x3f87dc22, v206
	v_fmaak_f32 v17, v17, v16, 0x3fb5f0e3
	v_exp_f32_e32 v18, v18
	v_fmaak_f32 v17, v17, v16, 0xbe91a98e
	v_fmaak_f32 v17, v17, v16, 0x3e827906
	v_mul_f32_e32 v16, v16, v17
	v_fma_f32 v15, -v18, v16, 1.0
	v_fma_f32 v14, |v14|, v15, v14
	v_mul_f32_e32 v14, v49, v14
	v_cvt_pk_bf16_f32 v14, v14, s0
	ds_write_b16 v22, v14 offset:816
	v_mul_f32_e32 v14, v209, v125
	v_fmac_f32_e32 v14, v210, v120
	v_fmac_f32_e32 v14, v208, v121
	v_add_f32_e32 v14, v207, v14
	v_mul_f32_e32 v18, 0x3f596d27, v14
	v_fma_f32 v19, |v18|, s98, 1.0
	v_mul_f32_e32 v15, v210, v121
	v_fmac_f32_e32 v15, v209, v120
	v_fmac_f32_e32 v15, v208, v118
	v_rcp_f32_e32 v19, v19
	v_mul_f32_e64 v21, |v18|, -|v18|
	v_fmamk_f32 v20, v19, 0x3f87dc22, v206
	v_fmaak_f32 v20, v20, v19, 0x3fb5f0e3
	v_exp_f32_e32 v21, v21
	v_fmaak_f32 v20, v20, v19, 0xbe91a98e
	v_fmaak_f32 v20, v20, v19, 0x3e827906
	v_mul_f32_e32 v19, v19, v20
	v_fma_f32 v18, -v21, v19, 1.0
	v_add_f32_e32 v15, v207, v15
	v_mul_f32_e32 v14, 0.5, v14
	v_fma_f32 v14, |v14|, v18, v14
	v_mul_f32_e32 v18, 0x3f596d27, v15
	v_fma_f32 v19, |v18|, s98, 1.0
	v_pk_mul_f32 v[26:27], v[26:27], v[42:43]
	v_add3_u32 v22, s14, v81, v62
	v_mul_f32_e32 v14, v26, v14
	v_cvt_pk_bf16_f32 v14, v14, s0
	ds_write_b16 v22, v14
	v_mul_f32_e32 v14, 0.5, v15
	v_rcp_f32_e32 v15, v19
	v_mul_f32_e64 v20, |v18|, -|v18|
	v_fmamk_f32 v19, v15, 0x3f87dc22, v206
	v_fmaak_f32 v19, v19, v15, 0x3fb5f0e3
	v_exp_f32_e32 v20, v20
	v_fmaak_f32 v19, v19, v15, 0xbe91a98e
	v_fmaak_f32 v19, v19, v15, 0x3e827906
	v_mul_f32_e32 v16, v210, v118
	v_mul_f32_e32 v15, v15, v19
	v_fmac_f32_e32 v16, v209, v121
	v_fma_f32 v15, -v20, v15, 1.0
	v_fmac_f32_e32 v16, v208, v119
	v_add_f32_e32 v16, v207, v16
	v_fma_f32 v14, |v14|, v15, v14
	v_mul_f32_e32 v15, 0x3f596d27, v16
	v_fma_f32 v18, |v15|, s98, 1.0
	v_mul_f32_e32 v14, v27, v14
	v_cvt_pk_bf16_f32 v14, v14, s0
	ds_write_b16 v22, v14 offset:272
	v_mul_f32_e32 v14, 0.5, v16
	v_rcp_f32_e32 v16, v18
	v_mul_f32_e64 v19, |v15|, -|v15|
	v_fmamk_f32 v18, v16, 0x3f87dc22, v206
	v_fmaak_f32 v18, v18, v16, 0x3fb5f0e3
	v_exp_f32_e32 v19, v19
	v_fmaak_f32 v18, v18, v16, 0xbe91a98e
	v_fmaak_f32 v18, v18, v16, 0x3e827906
	v_mul_f32_e32 v17, v210, v119
	v_mul_f32_e32 v16, v16, v18
	v_fmac_f32_e32 v17, v209, v118
	v_fma_f32 v15, -v19, v16, 1.0
	v_fmac_f32_e32 v17, v208, v123
	v_add_f32_e32 v17, v207, v17
	v_fma_f32 v14, |v14|, v15, v14
	v_mul_f32_e32 v15, 0x3f596d27, v17
	v_fma_f32 v16, |v15|, s98, 1.0
	v_pk_mul_f32 v[28:29], v[28:29], v[44:45]
	s_nop 0
	v_mul_f32_e32 v14, v28, v14
	v_cvt_pk_bf16_f32 v14, v14, s0
	ds_write_b16 v22, v14 offset:544
	v_mul_f32_e32 v14, 0.5, v17
	v_rcp_f32_e32 v16, v16
	v_mul_f32_e64 v18, |v15|, -|v15|
	v_fmamk_f32 v17, v16, 0x3f87dc22, v206
	v_fmaak_f32 v17, v17, v16, 0x3fb5f0e3
	v_exp_f32_e32 v18, v18
	v_fmaak_f32 v17, v17, v16, 0xbe91a98e
	v_fmaak_f32 v17, v17, v16, 0x3e827906
	v_mul_f32_e32 v16, v16, v17
	v_fma_f32 v15, -v18, v16, 1.0
	v_fma_f32 v14, |v14|, v15, v14
	v_mul_f32_e32 v14, v29, v14
	v_cvt_pk_bf16_f32 v14, v14, s0
	ds_write_b16 v22, v14 offset:816
	v_mul_f32_e32 v14, v209, v117
	v_fmac_f32_e32 v14, v210, v112
	v_fmac_f32_e32 v14, v208, v113
	v_add_f32_e32 v14, v207, v14
	v_mul_f32_e32 v18, 0x3f596d27, v14
	v_fma_f32 v19, |v18|, s98, 1.0
; __device__ __forceinline__ u16 f2bf(float f) { return (u16)(pack2(f, f) & 0xffffu); }
; __device__ __forceinline__ float erf_f32(float x) {
;   const float ax = fabsf(x);
;   const float t = __frcp_rn(fmaf(0.3275911f, ax, 1.0f));
;   float poly = fmaf(1.061405429f, t, -1.453152027f);
;   poly = fmaf(poly, t, 1.421413741f);
;   poly = fmaf(poly, t, -0.284496736f);
;   poly = fmaf(poly, t, 0.254829592f);
;   const float y = 1.0f - poly * t * __expf(-ax * ax);
;   return copysignf(y, x);
; }
; __device__ __forceinline__ float gelu_exact(float x) { return 0.5f * x * (1.0f + erf_f32(x * 0.70710678118654752f)); }
; template <int EPI>
; __device__ __forceinline__ void phase_gemm(const Params& p, const GemmDesc& d, char* shmc) {
;     ...
; #pragma unroll
;       for (int n = 0; n < 2; ++n) {
;         const int col = ewc * 32 + n * 16 + efr;
;         const int ch = ch0 + col;
;         const float w0 = cw[n][0], w1 = cw[n][1], w2 = cw[n][2], cb = cw[n][3];
; #pragma unroll
;         for (int ai = 0; ai < 2; ++ai)
; #pragma unroll
;           for (int m = 0; m < 4; ++m) {
;             const int s = ai * 32 + ewr * 16 + m * 4 + efq;
;             const f32x4 g = acc[ai][0][m][n];
;             const f32x4 v = acc[ai][1][m][n];
;             const float c0 = w0 * gp[ai][m][n] + w1 * g[0] + w2 * g[1] + cb;
;             const float c1 = w0 * g[0] + w1 * g[1] + w2 * g[2] + cb;
;             const float c2 = w0 * g[1] + w1 * g[2] + w2 * g[3] + cb;
;             const float c3 = w0 * g[2] + w1 * g[3] + w2 * gn[ai][m][n] + cb;
;             u16* sp = stg + (s * 4) * 136 + col;
;             sp[0] = f2bf(gelu_exact(c0) * v[0]);
;             sp[136] = f2bf(gelu_exact(c1) * v[1]);
;             sp[272] = f2bf(gelu_exact(c2) * v[2]);
;             sp[408] = f2bf(gelu_exact(c3) * v[3]);
;             if (s == 0) {
;               edge[0 * DFF + ch] = c0; edge[1 * DFF + ch] = g[0]; edge[2 * DFF + ch] = v[0];
;             }
;             if (s == 63) {
;               edge[3 * DFF + ch] = c3; edge[4 * DFF + ch] = g[3]; edge[5 * DFF + ch] = v[3];
;             }
;           }
	v_mul_f32_e32 v15, v210, v113
	v_fmac_f32_e32 v15, v209, v112
	v_fmac_f32_e32 v15, v208, v110
	v_rcp_f32_e32 v19, v19
	v_mul_f32_e64 v21, |v18|, -|v18|
	v_fmamk_f32 v20, v19, 0x3f87dc22, v206
	v_fmaak_f32 v20, v20, v19, 0x3fb5f0e3
	v_exp_f32_e32 v21, v21
	v_fmaak_f32 v20, v20, v19, 0xbe91a98e
	v_fmaak_f32 v20, v20, v19, 0x3e827906
	v_mul_f32_e32 v19, v19, v20
	v_fma_f32 v18, -v21, v19, 1.0
	v_mul_f32_e32 v14, 0.5, v14
	v_add_f32_e32 v15, v207, v15
	v_fma_f32 v14, |v14|, v18, v14
	v_mul_f32_e32 v12, v12, v14
	v_mul_f32_e32 v14, 0x3f596d27, v15
	v_fma_f32 v18, |v14|, s98, 1.0
	v_add3_u32 v22, s14, v82, v62
	v_cvt_pk_bf16_f32 v12, v12, s0
	ds_write_b16 v22, v12
	v_mul_f32_e32 v12, 0.5, v15
	v_rcp_f32_e32 v15, v18
	v_mul_f32_e64 v19, |v14|, -|v14|
	v_fmamk_f32 v18, v15, 0x3f87dc22, v206
	v_fmaak_f32 v18, v18, v15, 0x3fb5f0e3
	v_exp_f32_e32 v19, v19
	v_fmaak_f32 v18, v18, v15, 0xbe91a98e
	v_fmaak_f32 v18, v18, v15, 0x3e827906
	v_mul_f32_e32 v15, v15, v18
	v_mul_f32_e32 v16, v210, v110
	v_fma_f32 v14, -v19, v15, 1.0
	v_fmac_f32_e32 v16, v209, v113
	v_fmac_f32_e32 v16, v208, v111
	v_add_f32_e32 v16, v207, v16
	v_fma_f32 v12, |v12|, v14, v12
	v_mul_f32_e32 v12, v13, v12
	v_mul_f32_e32 v13, 0x3f596d27, v16
	v_fma_f32 v14, |v13|, s98, 1.0
	v_cvt_pk_bf16_f32 v12, v12, s0
	ds_write_b16 v22, v12 offset:272
	v_mul_f32_e32 v12, 0.5, v16
	v_rcp_f32_e32 v14, v14
	v_mul_f32_e64 v16, |v13|, -|v13|
	v_fmamk_f32 v15, v14, 0x3f87dc22, v206
	v_fmaak_f32 v15, v15, v14, 0x3fb5f0e3
	v_exp_f32_e32 v16, v16
	v_fmaak_f32 v15, v15, v14, 0xbe91a98e
	v_fmaak_f32 v15, v15, v14, 0x3e827906
	v_mul_f32_e32 v14, v14, v15
	v_mul_f32_e32 v17, v210, v111
	v_fma_f32 v13, -v16, v14, 1.0
	v_fmac_f32_e32 v17, v209, v110
	v_fmac_f32_e32 v17, v208, v115
	v_add_f32_e32 v17, v207, v17
	v_fma_f32 v12, |v12|, v13, v12
	v_mul_f32_e32 v10, v10, v12
	v_mul_f32_e32 v12, 0x3f596d27, v17
	v_fma_f32 v13, |v12|, s98, 1.0
	v_cvt_pk_bf16_f32 v10, v10, s0
	ds_write_b16 v22, v10 offset:544
	v_mul_f32_e32 v10, 0.5, v17
	v_rcp_f32_e32 v13, v13
	v_mul_f32_e64 v15, |v12|, -|v12|
	v_fmamk_f32 v14, v13, 0x3f87dc22, v206
	v_fmaak_f32 v14, v14, v13, 0x3fb5f0e3
	v_exp_f32_e32 v15, v15
	v_fmaak_f32 v14, v14, v13, 0xbe91a98e
	v_fmaak_f32 v14, v14, v13, 0x3e827906
	v_mul_f32_e32 v13, v13, v14
	v_fma_f32 v12, -v15, v13, 1.0
	v_fma_f32 v10, |v10|, v12, v10
	v_mul_f32_e32 v10, v11, v10
	v_cvt_pk_bf16_f32 v10, v10, s0
	ds_write_b16 v22, v10 offset:816
	v_mul_f32_e32 v10, v209, v109
	v_fmac_f32_e32 v10, v210, v104
	v_fmac_f32_e32 v10, v208, v105
	v_add_f32_e32 v10, v207, v10
	v_mul_f32_e32 v14, 0x3f596d27, v10
	v_fma_f32 v15, |v14|, s98, 1.0
	v_mul_f32_e32 v11, v210, v105
	v_fmac_f32_e32 v11, v209, v104
	v_fmac_f32_e32 v11, v208, v102
	v_rcp_f32_e32 v15, v15
	v_mul_f32_e64 v17, |v14|, -|v14|
	v_fmamk_f32 v16, v15, 0x3f87dc22, v206
	v_fmaak_f32 v16, v16, v15, 0x3fb5f0e3
	v_exp_f32_e32 v17, v17
	v_fmaak_f32 v16, v16, v15, 0xbe91a98e
	v_fmaak_f32 v16, v16, v15, 0x3e827906
	v_mul_f32_e32 v15, v15, v16
	v_fma_f32 v14, -v17, v15, 1.0
	v_mul_f32_e32 v10, 0.5, v10
	v_add_f32_e32 v11, v207, v11
	v_fma_f32 v10, |v10|, v14, v10
	v_mul_f32_e32 v8, v8, v10
	v_mul_f32_e32 v10, 0x3f596d27, v11
	v_fma_f32 v14, |v10|, s98, 1.0
	v_add3_u32 v18, s14, v74, v62
	v_cvt_pk_bf16_f32 v8, v8, s0
	ds_write_b16 v18, v8
	v_mul_f32_e32 v8, 0.5, v11
	v_rcp_f32_e32 v11, v14
	v_mul_f32_e64 v15, |v10|, -|v10|
	v_fmamk_f32 v14, v11, 0x3f87dc22, v206
	v_fmaak_f32 v14, v14, v11, 0x3fb5f0e3
	v_exp_f32_e32 v15, v15
	v_fmaak_f32 v14, v14, v11, 0xbe91a98e
	v_fmaak_f32 v14, v14, v11, 0x3e827906
	v_mul_f32_e32 v11, v11, v14
	v_mul_f32_e32 v12, v210, v102
	v_fma_f32 v10, -v15, v11, 1.0
	v_fmac_f32_e32 v12, v209, v105
	v_fmac_f32_e32 v12, v208, v103
	v_add_f32_e32 v12, v207, v12
	v_fma_f32 v8, |v8|, v10, v8
	v_mul_f32_e32 v8, v9, v8
	v_mul_f32_e32 v9, 0x3f596d27, v12
	v_fma_f32 v10, |v9|, s98, 1.0
	v_cvt_pk_bf16_f32 v8, v8, s0
	ds_write_b16 v18, v8 offset:272
	v_mul_f32_e32 v8, 0.5, v12
	v_rcp_f32_e32 v10, v10
; __device__ __forceinline__ u16 f2bf(float f) { return (u16)(pack2(f, f) & 0xffffu); }
; __device__ __forceinline__ float erf_f32(float x) {
;   const float ax = fabsf(x);
;   const float t = __frcp_rn(fmaf(0.3275911f, ax, 1.0f));
;   float poly = fmaf(1.061405429f, t, -1.453152027f);
;   poly = fmaf(poly, t, 1.421413741f);
;   poly = fmaf(poly, t, -0.284496736f);
;   poly = fmaf(poly, t, 0.254829592f);
;   const float y = 1.0f - poly * t * __expf(-ax * ax);
;   return copysignf(y, x);
; }
; __device__ __forceinline__ float gelu_exact(float x) { return 0.5f * x * (1.0f + erf_f32(x * 0.70710678118654752f)); }
; template <int EPI>
; __device__ __forceinline__ void phase_gemm(const Params& p, const GemmDesc& d, char* shmc) {
;     ...
; #pragma unroll
;       for (int n = 0; n < 2; ++n) {
;         const int col = ewc * 32 + n * 16 + efr;
;         const int ch = ch0 + col;
;         const float w0 = cw[n][0], w1 = cw[n][1], w2 = cw[n][2], cb = cw[n][3];
; #pragma unroll
;         for (int ai = 0; ai < 2; ++ai)
; #pragma unroll
;           for (int m = 0; m < 4; ++m) {
;             const int s = ai * 32 + ewr * 16 + m * 4 + efq;
;             const f32x4 g = acc[ai][0][m][n];
;             const f32x4 v = acc[ai][1][m][n];
;             const float c0 = w0 * gp[ai][m][n] + w1 * g[0] + w2 * g[1] + cb;
;             const float c1 = w0 * g[0] + w1 * g[1] + w2 * g[2] + cb;
;             const float c2 = w0 * g[1] + w1 * g[2] + w2 * g[3] + cb;
;             const float c3 = w0 * g[2] + w1 * g[3] + w2 * gn[ai][m][n] + cb;
;             u16* sp = stg + (s * 4) * 136 + col;
;             sp[0] = f2bf(gelu_exact(c0) * v[0]);
;             sp[136] = f2bf(gelu_exact(c1) * v[1]);
;             sp[272] = f2bf(gelu_exact(c2) * v[2]);
;             sp[408] = f2bf(gelu_exact(c3) * v[3]);
;             if (s == 0) {
;               edge[0 * DFF + ch] = c0; edge[1 * DFF + ch] = g[0]; edge[2 * DFF + ch] = v[0];
;             }
;             if (s == 63) {
;               edge[3 * DFF + ch] = c3; edge[4 * DFF + ch] = g[3]; edge[5 * DFF + ch] = v[3];
;             }
;           }
	v_mul_f32_e64 v12, |v9|, -|v9|
	v_fmamk_f32 v11, v10, 0x3f87dc22, v206
	v_fmaak_f32 v11, v11, v10, 0x3fb5f0e3
	v_exp_f32_e32 v12, v12
	v_fmaak_f32 v11, v11, v10, 0xbe91a98e
	v_fmaak_f32 v11, v11, v10, 0x3e827906
	v_mul_f32_e32 v10, v10, v11
	v_mul_f32_e32 v13, v210, v103
	v_fma_f32 v9, -v12, v10, 1.0
	v_fmac_f32_e32 v13, v209, v102
	v_fmac_f32_e32 v13, v208, v107
	v_add_f32_e32 v13, v207, v13
	v_fma_f32 v8, |v8|, v9, v8
	v_mul_f32_e32 v6, v6, v8
	v_mul_f32_e32 v8, 0x3f596d27, v13
	v_fma_f32 v9, |v8|, s98, 1.0
	v_cvt_pk_bf16_f32 v6, v6, s0
	ds_write_b16 v18, v6 offset:544
	v_mul_f32_e32 v6, 0.5, v13
	v_rcp_f32_e32 v9, v9
	v_mul_f32_e64 v11, |v8|, -|v8|
	v_fmamk_f32 v10, v9, 0x3f87dc22, v206
	v_fmaak_f32 v10, v10, v9, 0x3fb5f0e3
	v_exp_f32_e32 v11, v11
	v_fmaak_f32 v10, v10, v9, 0xbe91a98e
	v_fmaak_f32 v10, v10, v9, 0x3e827906
	v_mul_f32_e32 v9, v9, v10
	v_fma_f32 v8, -v11, v9, 1.0
	v_fma_f32 v6, |v6|, v8, v6
	v_mul_f32_e32 v6, v7, v6
	v_cvt_pk_bf16_f32 v6, v6, s0
	ds_write_b16 v18, v6 offset:816
	v_mul_f32_e32 v6, v209, v212
	v_fmac_f32_e32 v6, v210, v98
	v_fmac_f32_e32 v6, v208, v99
	v_add_f32_e32 v7, v207, v6
	v_mul_f32_e32 v10, 0x3f596d27, v7
	v_fma_f32 v11, |v10|, s98, 1.0
	v_mul_f32_e32 v6, v210, v99
	v_fmac_f32_e32 v6, v209, v98
	v_fmac_f32_e32 v6, v208, v100
	v_rcp_f32_e32 v11, v11
	v_mul_f32_e64 v13, |v10|, -|v10|
	v_fmamk_f32 v12, v11, 0x3f87dc22, v206
	v_fmaak_f32 v12, v12, v11, 0x3fb5f0e3
	v_exp_f32_e32 v13, v13
	v_fmaak_f32 v12, v12, v11, 0xbe91a98e
	v_fmaak_f32 v12, v12, v11, 0x3e827906
	v_mul_f32_e32 v11, v11, v12
	v_fma_f32 v10, -v13, v11, 1.0
	v_mul_f32_e32 v7, 0.5, v7
	v_add_f32_e32 v8, v207, v6
	v_fma_f32 v7, |v7|, v10, v7
	v_mul_f32_e32 v4, v4, v7
	v_mul_f32_e32 v7, 0x3f596d27, v8
	v_fma_f32 v10, |v7|, s98, 1.0
	v_add3_u32 v14, s14, v70, v62
	v_cvt_pk_bf16_f32 v4, v4, s0
	ds_write_b16 v14, v4
	v_mul_f32_e32 v4, 0.5, v8
	v_rcp_f32_e32 v8, v10
	v_mul_f32_e64 v11, |v7|, -|v7|
	v_fmamk_f32 v10, v8, 0x3f87dc22, v206
	v_fmaak_f32 v10, v10, v8, 0x3fb5f0e3
	v_exp_f32_e32 v11, v11
	v_fmaak_f32 v10, v10, v8, 0xbe91a98e
	v_fmaak_f32 v10, v10, v8, 0x3e827906
	v_mul_f32_e32 v8, v8, v10
	v_mul_f32_e32 v6, v210, v100
	v_fma_f32 v7, -v11, v8, 1.0
	v_fmac_f32_e32 v6, v209, v99
	v_fmac_f32_e32 v6, v208, v101
	v_add_f32_e32 v9, v207, v6
	v_fma_f32 v4, |v4|, v7, v4
	v_mul_f32_e32 v4, v5, v4
	v_mul_f32_e32 v5, 0x3f596d27, v9
	v_fma_f32 v7, |v5|, s98, 1.0
	v_cvt_pk_bf16_f32 v4, v4, s0
	ds_write_b16 v14, v4 offset:272
	v_mul_f32_e32 v4, 0.5, v9
	v_rcp_f32_e32 v7, v7
	v_mul_f32_e64 v9, |v5|, -|v5|
	v_fmamk_f32 v8, v7, 0x3f87dc22, v206
	v_fmaak_f32 v8, v8, v7, 0x3fb5f0e3
	v_exp_f32_e32 v9, v9
	v_fmaak_f32 v8, v8, v7, 0xbe91a98e
	v_fmaak_f32 v8, v8, v7, 0x3e827906
	v_mul_f32_e32 v7, v7, v8
	v_mul_f32_e32 v6, v210, v101
	v_fma_f32 v5, -v9, v7, 1.0
	v_fmac_f32_e32 v6, v209, v100
	v_fmac_f32_e32 v6, v208, v211
	v_add_f32_e32 v6, v207, v6
	v_fma_f32 v4, |v4|, v5, v4
	v_mul_f32_e32 v2, v2, v4
	v_mul_f32_e32 v4, 0x3f596d27, v6
	v_fma_f32 v5, |v4|, s98, 1.0
	v_cvt_pk_bf16_f32 v2, v2, s0
	ds_write_b16 v14, v2 offset:544
	v_mul_f32_e32 v2, 0.5, v6
	v_rcp_f32_e32 v5, v5
	v_mul_f32_e64 v8, |v4|, -|v4|
	v_fmamk_f32 v7, v5, 0x3f87dc22, v206
	v_fmaak_f32 v7, v7, v5, 0x3fb5f0e3
	v_exp_f32_e32 v8, v8
	v_fmaak_f32 v7, v7, v5, 0xbe91a98e
	v_fmaak_f32 v7, v7, v5, 0x3e827906
	v_mul_f32_e32 v5, v5, v7
	v_fma_f32 v4, -v8, v5, 1.0
	v_fma_f32 v2, |v2|, v4, v2
	v_mul_f32_e32 v2, v3, v2
	v_cvt_pk_bf16_f32 v2, v2, s0
	ds_write_b16 v14, v2 offset:816
	s_and_saveexec_b64 s[10:11], s[8:9]
	s_cbranch_execz .LBB0_289
	v_add_co_u32_e32 v4, vcc, 0x10000, v58
	s_nop 1
	v_addc_co_u32_e32 v5, vcc, 0, v59, vcc
	global_store_dword v[4:5], v6, off offset:2048
	v_add_co_u32_e32 v4, vcc, 0x16000, v58
	s_nop 1
	v_addc_co_u32_e32 v5, vcc, 0, v59, vcc
	global_store_dword v[4:5], v101, off
	v_add_co_u32_e32 v4, vcc, 0x1b000, v58
	s_nop 1
	v_addc_co_u32_e32 v5, vcc, 0, v59, vcc
	global_store_dword v[4:5], v3, off offset:2048
	s_branch .LBB0_289

; #define WAIT_V(n) asm volatile("s_waitcnt vmcnt(" #n ")" ::: "memory")
; #define BAR __builtin_amdgcn_s_barrier()
; template <int EPI>
; __device__ __forceinline__ void phase_gemm(const Params& p, const GemmDesc& d, char* shmc) {
;     ...
; #pragma unroll
;     for (int a = 0; a < 2; ++a)
; #pragma unroll
;       for (int b = 0; b < 2; ++b)
; #pragma unroll
;         for (int m = 0; m < 4; ++m)
; #pragma unroll
;           for (int n = 0; n < 2; ++n) acc[a][b][m][n] = f32x4{0.f, 0.f, 0.f, 0.f};
;     bf16x8 At[4][2], B0[2][2], B1[2][2];
;     if constexpr (EPI == EPI_UP || EPI == EPI_QKV) {
;       if (wid == 0)
;         __builtin_amdgcn_global_load_lds((const unsigned*)(p.rstd + brow + lane * 4), (unsigned*)(shmc + 143360), 16, 0, 0);
;     }
;     STAGE_B(SB(0, 0), 0, 0); STAGE_A(SA(0, 0), 0, 0);
;     STAGE_B(SB(0, 1), 1, 0); STAGE_A(SA(0, 1), 1, 0);
;     if (wr == 1) BAR;
;     WAIT_V(4); BAR;
;     STAGE_B(SB(1, 0), 0, 1); STAGE_A(SA(1, 0), 0, 1); STAGE_B(SB(1, 1), 1, 1);
;     WAIT_V(6); BAR;
.LBB0_454:
	s_or_b64 exec, exec, s[56:57]
	v_mov_b32_e32 v141, v131
	s_waitcnt lgkmcnt(0)
	v_lshl_add_u64 v[2:3], s[54:55], 0, v[140:141]
	v_mov_b32_e32 v143, v131
	s_mov_b32 m0, s62
	v_lshl_add_u64 v[4:5], s[54:55], 0, v[142:143]
	v_lshl_add_u64 v[2:3], v[2:3], 0, s[8:9]
	v_lshl_add_u64 v[6:7], s[48:49], 0, v[140:141]
	v_mov_b32_e32 v10, 0
	v_mov_b32_e32 v11, 0
	v_mov_b32_e32 v12, 0
	v_mov_b32_e32 v13, 0
	v_mov_b32_e32 v14, 0
	v_mov_b32_e32 v15, 0
	v_mov_b32_e32 v16, 0
	v_mov_b32_e32 v17, 0
	v_mov_b32_e32 v18, 0
	v_mov_b32_e32 v19, 0
	v_mov_b32_e32 v20, 0
	v_mov_b32_e32 v21, 0
	v_mov_b32_e32 v22, 0
	v_mov_b32_e32 v23, 0
	v_mov_b32_e32 v24, 0
	v_mov_b32_e32 v25, 0
	v_mov_b32_e32 v26, 0
	v_mov_b32_e32 v27, 0
	v_mov_b32_e32 v28, 0
	v_mov_b32_e32 v29, 0
	v_mov_b32_e32 v30, 0
	v_mov_b32_e32 v31, 0
	v_mov_b32_e32 v32, 0
	v_mov_b32_e32 v33, 0
	v_mov_b32_e32 v34, 0
	v_mov_b32_e32 v35, 0
	v_mov_b32_e32 v36, 0
	v_mov_b32_e32 v37, 0
	v_mov_b32_e32 v38, 0
	v_mov_b32_e32 v39, 0
	v_mov_b32_e32 v40, 0
	v_mov_b32_e32 v41, 0
	v_mov_b32_e32 v42, 0
	v_mov_b32_e32 v43, 0
	v_mov_b32_e32 v44, 0
	v_mov_b32_e32 v45, 0
	v_mov_b32_e32 v46, 0
	v_mov_b32_e32 v47, 0
	v_mov_b32_e32 v48, 0
	v_mov_b32_e32 v49, 0
	v_mov_b32_e32 v50, 0
	v_mov_b32_e32 v51, 0
	v_mov_b32_e32 v52, 0
	v_mov_b32_e32 v53, 0
	v_mov_b32_e32 v54, 0
	v_mov_b32_e32 v55, 0
	v_mov_b32_e32 v56, 0
	v_mov_b32_e32 v57, 0
	v_mov_b32_e32 v70, 0
	v_mov_b32_e32 v71, 0
	v_mov_b32_e32 v72, 0
	v_mov_b32_e32 v73, 0
	v_mov_b32_e32 v86, 0
	v_mov_b32_e32 v87, 0
	v_mov_b32_e32 v88, 0
	v_mov_b32_e32 v89, 0
	v_mov_b32_e32 v98, 0
	v_mov_b32_e32 v99, 0
	v_mov_b32_e32 v100, 0
	v_mov_b32_e32 v101, 0
	v_mov_b32_e32 v102, 0
	v_mov_b32_e32 v103, 0
	v_mov_b32_e32 v104, 0
	v_mov_b32_e32 v105, 0
	v_mov_b32_e32 v106, 0
	v_mov_b32_e32 v107, 0
	v_mov_b32_e32 v108, 0
	v_mov_b32_e32 v109, 0
	v_mov_b32_e32 v110, 0
	v_mov_b32_e32 v111, 0
	v_mov_b32_e32 v112, 0
	v_mov_b32_e32 v113, 0
	v_mov_b32_e32 v114, 0
	v_mov_b32_e32 v115, 0
	v_mov_b32_e32 v116, 0
	v_mov_b32_e32 v117, 0
	v_mov_b32_e32 v118, 0
	v_mov_b32_e32 v119, 0
	v_mov_b32_e32 v120, 0
	v_mov_b32_e32 v121, 0
	v_mov_b32_e32 v122, 0
	v_mov_b32_e32 v123, 0
	v_mov_b32_e32 v124, 0
	v_mov_b32_e32 v125, 0
	v_mov_b32_e32 v126, 0
	v_mov_b32_e32 v127, 0
	v_mov_b32_e32 v128, 0
	v_mov_b32_e32 v129, 0
	v_mov_b32_e32 v58, 0
	v_mov_b32_e32 v59, 0
	v_mov_b32_e32 v60, 0
	v_mov_b32_e32 v61, 0
	v_mov_b32_e32 v62, 0
	v_mov_b32_e32 v63, 0
	v_mov_b32_e32 v64, 0
	v_mov_b32_e32 v65, 0
	v_mov_b32_e32 v66, 0
	v_mov_b32_e32 v67, 0
	v_mov_b32_e32 v68, 0
	v_mov_b32_e32 v69, 0
	v_mov_b32_e32 v74, 0
	v_mov_b32_e32 v75, 0
	v_mov_b32_e32 v76, 0
	v_mov_b32_e32 v77, 0
	v_mov_b32_e32 v78, 0
	v_mov_b32_e32 v79, 0
	v_mov_b32_e32 v80, 0
	v_mov_b32_e32 v81, 0
	v_mov_b32_e32 v82, 0
	v_mov_b32_e32 v83, 0
	v_mov_b32_e32 v84, 0
	v_mov_b32_e32 v85, 0
	v_mov_b32_e32 v90, 0
	v_mov_b32_e32 v91, 0
	v_mov_b32_e32 v92, 0
	v_mov_b32_e32 v93, 0
	v_mov_b32_e32 v94, 0
	v_mov_b32_e32 v95, 0
	v_mov_b32_e32 v96, 0
	v_mov_b32_e32 v97, 0
	s_waitcnt vmcnt(2)
	s_barrier
	global_load_lds_dwordx4 v[2:3], off
	v_lshl_add_u64 v[2:3], v[4:5], 0, s[8:9]
	s_mov_b32 m0, s63
	v_lshl_add_u64 v[8:9], s[48:49], 0, v[142:143]
	global_load_lds_dwordx4 v[2:3], off
	v_lshl_add_u64 v[2:3], v[6:7], 0, s[8:9]
	s_mov_b32 m0, s64
	s_add_u32 s54, s54, 0x160080
	global_load_lds_dwordx4 v[2:3], off
	v_lshl_add_u64 v[2:3], v[8:9], 0, s[8:9]
	s_mov_b32 m0, s65
	s_addc_u32 s55, s55, 0
	global_load_lds_dwordx4 v[2:3], off
	s_mov_b32 m0, s68
	s_add_i32 s79, s79, s80
	global_load_lds_dwordx4 v140, s[54:55]
	s_mov_b32 m0, s69
	v_lshl_add_u64 v[144:145], v[132:133], 0, s[52:53]
	global_load_lds_dwordx4 v142, s[54:55]
	s_waitcnt vmcnt(6)
	v_lshl_add_u64 v[146:147], v[134:135], 0, s[52:53]
	v_mad_i64_i32 v[148:149], s[52:53], s79, v154, v[136:137]
	v_mad_i64_i32 v[150:151], s[52:53], s79, v154, v[138:139]
	v_mov_b32_e32 v2, 0
	s_mov_b32 s54, -2
	s_mov_b64 s[52:53], 0
	v_mov_b32_e32 v3, v2
	v_mov_b32_e32 v4, v2
	v_mov_b32_e32 v5, v2
	v_mov_b32_e32 v6, v2
	v_mov_b32_e32 v7, v2
	v_mov_b32_e32 v8, v2
	v_mov_b32_e32 v9, v2
	s_barrier

; #define WAIT_V(n) asm volatile("s_waitcnt vmcnt(" #n ")" ::: "memory")
; #define BAR __builtin_amdgcn_s_barrier()
; template <int EPI>
; __device__ __forceinline__ void phase_gemm(const Params& p, const GemmDesc& d, char* shmc) {
;     ...
;     f32x4 acc[2][2][4][2];
; #pragma unroll
;     for (int a = 0; a < 2; ++a)
; #pragma unroll
;       for (int b = 0; b < 2; ++b)
; #pragma unroll
;         for (int m = 0; m < 4; ++m)
; #pragma unroll
;           for (int n = 0; n < 2; ++n) acc[a][b][m][n] = f32x4{0.f, 0.f, 0.f, 0.f};
;     bf16x8 At[4][2], B0[2][2], B1[2][2];
;     if constexpr (EPI == EPI_UP || EPI == EPI_QKV) {
;       if (wid == 0)
;         __builtin_amdgcn_global_load_lds((const unsigned*)(p.rstd + brow + lane * 4), (unsigned*)(shmc + 143360), 16, 0, 0);
;     }
;     STAGE_B(SB(0, 0), 0, 0); STAGE_A(SA(0, 0), 0, 0);
;     STAGE_B(SB(0, 1), 1, 0); STAGE_A(SA(0, 1), 1, 0);
;     if (wr == 1) BAR;
;     WAIT_V(4); BAR;
;     STAGE_B(SB(1, 0), 0, 1); STAGE_A(SA(1, 0), 0, 1); STAGE_B(SB(1, 1), 1, 1);
;     WAIT_V(6); BAR;
.LBB0_597:
	s_or_b64 exec, exec, s[78:79]
	v_lshl_add_u64 v[2:3], s[64:65], 0, v[162:163]
	v_mov_b32_e32 v175, v163
	s_add_i32 s61, s68, 0x18000
	v_lshl_add_u64 v[4:5], s[64:65], 0, v[174:175]
	v_lshl_add_u64 v[2:3], v[2:3], 0, s[10:11]
	s_mov_b32 m0, s61
	s_add_i32 s78, s68, 0x1a000
	v_lshl_add_u64 v[6:7], s[8:9], 0, v[162:163]
	v_mov_b32_e32 v10, 0
	v_mov_b32_e32 v11, 0
	v_mov_b32_e32 v12, 0
	v_mov_b32_e32 v13, 0
	v_mov_b32_e32 v14, 0
	v_mov_b32_e32 v15, 0
	v_mov_b32_e32 v16, 0
	v_mov_b32_e32 v17, 0
	v_mov_b32_e32 v18, 0
	v_mov_b32_e32 v19, 0
	v_mov_b32_e32 v20, 0
	v_mov_b32_e32 v21, 0
	v_mov_b32_e32 v22, 0
	v_mov_b32_e32 v23, 0
	v_mov_b32_e32 v24, 0
	v_mov_b32_e32 v25, 0
	v_mov_b32_e32 v26, 0
	v_mov_b32_e32 v27, 0
	v_mov_b32_e32 v28, 0
	v_mov_b32_e32 v29, 0
	v_mov_b32_e32 v30, 0
	v_mov_b32_e32 v31, 0
	v_mov_b32_e32 v32, 0
	v_mov_b32_e32 v33, 0
	v_mov_b32_e32 v34, 0
	v_mov_b32_e32 v35, 0
	v_mov_b32_e32 v36, 0
	v_mov_b32_e32 v37, 0
	v_mov_b32_e32 v38, 0
	v_mov_b32_e32 v39, 0
	v_mov_b32_e32 v40, 0
	v_mov_b32_e32 v41, 0
	v_mov_b32_e32 v42, 0
	v_mov_b32_e32 v43, 0
	v_mov_b32_e32 v44, 0
	v_mov_b32_e32 v45, 0
	v_mov_b32_e32 v50, 0
	v_mov_b32_e32 v51, 0
	v_mov_b32_e32 v52, 0
	v_mov_b32_e32 v53, 0
	v_mov_b32_e32 v94, 0
	v_mov_b32_e32 v95, 0
	v_mov_b32_e32 v96, 0
	v_mov_b32_e32 v97, 0
	v_mov_b32_e32 v102, 0
	v_mov_b32_e32 v103, 0
	v_mov_b32_e32 v104, 0
	v_mov_b32_e32 v105, 0
	v_mov_b32_e32 v106, 0
	v_mov_b32_e32 v107, 0
	v_mov_b32_e32 v108, 0
	v_mov_b32_e32 v109, 0
	v_mov_b32_e32 v110, 0
	v_mov_b32_e32 v111, 0
	v_mov_b32_e32 v112, 0
	v_mov_b32_e32 v113, 0
	v_mov_b32_e32 v114, 0
	v_mov_b32_e32 v115, 0
	v_mov_b32_e32 v116, 0
	v_mov_b32_e32 v117, 0
	v_mov_b32_e32 v118, 0
	v_mov_b32_e32 v119, 0
	v_mov_b32_e32 v120, 0
	v_mov_b32_e32 v121, 0
	v_mov_b32_e32 v122, 0
	v_mov_b32_e32 v123, 0
	v_mov_b32_e32 v124, 0
	v_mov_b32_e32 v125, 0
	v_mov_b32_e32 v126, 0
	v_mov_b32_e32 v127, 0
	v_mov_b32_e32 v128, 0
	v_mov_b32_e32 v129, 0
	v_mov_b32_e32 v46, 0
	v_mov_b32_e32 v47, 0
	v_mov_b32_e32 v48, 0
	v_mov_b32_e32 v49, 0
	v_mov_b32_e32 v54, 0
	v_mov_b32_e32 v55, 0
	v_mov_b32_e32 v56, 0
	v_mov_b32_e32 v57, 0
	v_mov_b32_e32 v58, 0
	v_mov_b32_e32 v59, 0
	v_mov_b32_e32 v60, 0
	v_mov_b32_e32 v61, 0
	v_mov_b32_e32 v62, 0
	v_mov_b32_e32 v63, 0
	v_mov_b32_e32 v64, 0
	v_mov_b32_e32 v65, 0
	v_mov_b32_e32 v66, 0
	v_mov_b32_e32 v67, 0
	v_mov_b32_e32 v68, 0
	v_mov_b32_e32 v69, 0
	v_mov_b32_e32 v70, 0
	v_mov_b32_e32 v71, 0
	v_mov_b32_e32 v72, 0
	v_mov_b32_e32 v73, 0
	v_mov_b32_e32 v74, 0
	v_mov_b32_e32 v75, 0
	v_mov_b32_e32 v76, 0
	v_mov_b32_e32 v77, 0
	v_mov_b32_e32 v78, 0
	v_mov_b32_e32 v79, 0
	v_mov_b32_e32 v80, 0
	v_mov_b32_e32 v81, 0
	v_mov_b32_e32 v82, 0
	v_mov_b32_e32 v83, 0
	v_mov_b32_e32 v84, 0
	v_mov_b32_e32 v85, 0
	v_mov_b32_e32 v86, 0
	v_mov_b32_e32 v87, 0
	v_mov_b32_e32 v88, 0
	v_mov_b32_e32 v89, 0
	v_mov_b32_e32 v90, 0
	v_mov_b32_e32 v91, 0
	v_mov_b32_e32 v92, 0
	v_mov_b32_e32 v93, 0
	v_mov_b32_e32 v98, 0
	v_mov_b32_e32 v99, 0
	v_mov_b32_e32 v100, 0
	v_mov_b32_e32 v101, 0
	s_waitcnt vmcnt(2)
	s_barrier
	global_load_lds_dwordx4 v[2:3], off
	v_lshl_add_u64 v[2:3], v[4:5], 0, s[10:11]
	s_mov_b32 m0, s78
	s_add_i32 s79, s68, 0x8000
	s_add_i32 s86, s68, 0xa000
	v_lshl_add_u64 v[8:9], s[8:9], 0, v[174:175]
	global_load_lds_dwordx4 v[2:3], off
	v_lshl_add_u64 v[2:3], v[6:7], 0, s[10:11]
	s_mov_b32 m0, s79
	s_add_u32 s72, s64, 0x80080
	global_load_lds_dwordx4 v[2:3], off
	v_lshl_add_u64 v[2:3], v[8:9], 0, s[10:11]
	s_mov_b32 m0, s86
	s_addc_u32 s73, s65, 0
	s_add_i32 s64, s68, 0x1c000
	global_load_lds_dwordx4 v[2:3], off
	s_mov_b32 m0, s64
	s_add_i32 s65, s68, 0x1e000
	global_load_lds_dwordx4 v162, s[72:73]
	s_mov_b32 m0, s65
	v_lshl_add_u64 v[130:131], v[166:167], 0, s[62:63]
	global_load_lds_dwordx4 v174, s[72:73]
	v_lshl_add_u64 v[132:133], v[168:169], 0, s[62:63]
	s_lshl_b32 s62, s87, 11
	s_lshl_b32 s63, s88, 8
	s_or_b32 s62, s62, s63
	s_waitcnt vmcnt(6)
	s_ashr_i32 s63, s62, 31
	s_lshl_b64 s[62:63], s[62:63], 12
	v_mov_b32_e32 v2, 0
	v_lshl_add_u64 v[134:135], v[170:171], 0, s[62:63]
	v_lshl_add_u64 v[136:137], v[172:173], 0, s[62:63]
	s_mov_b32 s87, -2
	s_mov_b64 s[62:63], 0
	v_mov_b32_e32 v3, v2
	v_mov_b32_e32 v4, v2
	v_mov_b32_e32 v5, v2
	v_mov_b32_e32 v6, v2
	v_mov_b32_e32 v7, v2
	v_mov_b32_e32 v8, v2
	v_mov_b32_e32 v9, v2
	s_barrier

; #define WAIT_V(n) asm volatile("s_waitcnt vmcnt(" #n ")" ::: "memory")
; #define BAR __builtin_amdgcn_s_barrier()
; template <int EPI>
; __device__ __forceinline__ void phase_gemm(const Params& p, const GemmDesc& d, char* shmc) {
;     ...
;     f32x4 acc[2][2][4][2];
; #pragma unroll
;     for (int a = 0; a < 2; ++a)
; #pragma unroll
;       for (int b = 0; b < 2; ++b)
; #pragma unroll
;         for (int m = 0; m < 4; ++m)
; #pragma unroll
;           for (int n = 0; n < 2; ++n) acc[a][b][m][n] = f32x4{0.f, 0.f, 0.f, 0.f};
;     bf16x8 At[4][2], B0[2][2], B1[2][2];
;     if constexpr (EPI == EPI_UP || EPI == EPI_QKV) {
;       if (wid == 0)
;         __builtin_amdgcn_global_load_lds((const unsigned*)(p.rstd + brow + lane * 4), (unsigned*)(shmc + 143360), 16, 0, 0);
;     }
;     STAGE_B(SB(0, 0), 0, 0); STAGE_A(SA(0, 0), 0, 0);
;     STAGE_B(SB(0, 1), 1, 0); STAGE_A(SA(0, 1), 1, 0);
;     if (wr == 1) BAR;
;     WAIT_V(4); BAR;
;     STAGE_B(SB(1, 0), 0, 1); STAGE_A(SA(1, 0), 0, 1); STAGE_B(SB(1, 1), 1, 1);
;     WAIT_V(6); BAR;
.LBB0_1009:
	s_or_b64 exec, exec, s[62:63]
	v_mov_b32_e32 v141, v131
	s_waitcnt lgkmcnt(0)
	v_lshl_add_u64 v[2:3], s[60:61], 0, v[140:141]
	v_mov_b32_e32 v143, v131
	s_mov_b32 m0, s70
	v_lshl_add_u64 v[4:5], s[60:61], 0, v[142:143]
	v_lshl_add_u64 v[2:3], v[2:3], 0, s[8:9]
	v_lshl_add_u64 v[6:7], s[56:57], 0, v[140:141]
	v_mov_b32_e32 v10, 0
	v_mov_b32_e32 v11, 0
	v_mov_b32_e32 v12, 0
	v_mov_b32_e32 v13, 0
	v_mov_b32_e32 v14, 0
	v_mov_b32_e32 v15, 0
	v_mov_b32_e32 v16, 0
	v_mov_b32_e32 v17, 0
	v_mov_b32_e32 v18, 0
	v_mov_b32_e32 v19, 0
	v_mov_b32_e32 v20, 0
	v_mov_b32_e32 v21, 0
	v_mov_b32_e32 v22, 0
	v_mov_b32_e32 v23, 0
	v_mov_b32_e32 v24, 0
	v_mov_b32_e32 v25, 0
	v_mov_b32_e32 v26, 0
	v_mov_b32_e32 v27, 0
	v_mov_b32_e32 v28, 0
	v_mov_b32_e32 v29, 0
	v_mov_b32_e32 v30, 0
	v_mov_b32_e32 v31, 0
	v_mov_b32_e32 v32, 0
	v_mov_b32_e32 v33, 0
	v_mov_b32_e32 v34, 0
	v_mov_b32_e32 v35, 0
	v_mov_b32_e32 v36, 0
	v_mov_b32_e32 v37, 0
	v_mov_b32_e32 v38, 0
	v_mov_b32_e32 v39, 0
	v_mov_b32_e32 v40, 0
	v_mov_b32_e32 v41, 0
	v_mov_b32_e32 v42, 0
	v_mov_b32_e32 v43, 0
	v_mov_b32_e32 v44, 0
	v_mov_b32_e32 v45, 0
	v_mov_b32_e32 v46, 0
	v_mov_b32_e32 v47, 0
	v_mov_b32_e32 v48, 0
	v_mov_b32_e32 v49, 0
	v_mov_b32_e32 v50, 0
	v_mov_b32_e32 v51, 0
	v_mov_b32_e32 v52, 0
	v_mov_b32_e32 v53, 0
	v_mov_b32_e32 v54, 0
	v_mov_b32_e32 v55, 0
	v_mov_b32_e32 v56, 0
	v_mov_b32_e32 v57, 0
	v_mov_b32_e32 v70, 0
	v_mov_b32_e32 v71, 0
	v_mov_b32_e32 v72, 0
	v_mov_b32_e32 v73, 0
	v_mov_b32_e32 v86, 0
	v_mov_b32_e32 v87, 0
	v_mov_b32_e32 v88, 0
	v_mov_b32_e32 v89, 0
	v_mov_b32_e32 v98, 0
	v_mov_b32_e32 v99, 0
	v_mov_b32_e32 v100, 0
	v_mov_b32_e32 v101, 0
	v_mov_b32_e32 v102, 0
	v_mov_b32_e32 v103, 0
	v_mov_b32_e32 v104, 0
	v_mov_b32_e32 v105, 0
	v_mov_b32_e32 v106, 0
	v_mov_b32_e32 v107, 0
	v_mov_b32_e32 v108, 0
	v_mov_b32_e32 v109, 0
	v_mov_b32_e32 v110, 0
	v_mov_b32_e32 v111, 0
	v_mov_b32_e32 v112, 0
	v_mov_b32_e32 v113, 0
	v_mov_b32_e32 v114, 0
	v_mov_b32_e32 v115, 0
	v_mov_b32_e32 v116, 0
	v_mov_b32_e32 v117, 0
	v_mov_b32_e32 v118, 0
	v_mov_b32_e32 v119, 0
	v_mov_b32_e32 v120, 0
	v_mov_b32_e32 v121, 0
	v_mov_b32_e32 v122, 0
	v_mov_b32_e32 v123, 0
	v_mov_b32_e32 v124, 0
	v_mov_b32_e32 v125, 0
	v_mov_b32_e32 v126, 0
	v_mov_b32_e32 v127, 0
	v_mov_b32_e32 v128, 0
	v_mov_b32_e32 v129, 0
	v_mov_b32_e32 v58, 0
	v_mov_b32_e32 v59, 0
	v_mov_b32_e32 v60, 0
	v_mov_b32_e32 v61, 0
	v_mov_b32_e32 v62, 0
	v_mov_b32_e32 v63, 0
	v_mov_b32_e32 v64, 0
	v_mov_b32_e32 v65, 0
	v_mov_b32_e32 v66, 0
	v_mov_b32_e32 v67, 0
	v_mov_b32_e32 v68, 0
	v_mov_b32_e32 v69, 0
	v_mov_b32_e32 v74, 0
	v_mov_b32_e32 v75, 0
	v_mov_b32_e32 v76, 0
	v_mov_b32_e32 v77, 0
	v_mov_b32_e32 v78, 0
	v_mov_b32_e32 v79, 0
	v_mov_b32_e32 v80, 0
	v_mov_b32_e32 v81, 0
	v_mov_b32_e32 v82, 0
	v_mov_b32_e32 v83, 0
	v_mov_b32_e32 v84, 0
	v_mov_b32_e32 v85, 0
	v_mov_b32_e32 v90, 0
	v_mov_b32_e32 v91, 0
	v_mov_b32_e32 v92, 0
	v_mov_b32_e32 v93, 0
	v_mov_b32_e32 v94, 0
	v_mov_b32_e32 v95, 0
	v_mov_b32_e32 v96, 0
	v_mov_b32_e32 v97, 0
	s_waitcnt vmcnt(2)
	s_barrier
	global_load_lds_dwordx4 v[2:3], off
	v_lshl_add_u64 v[2:3], v[4:5], 0, s[8:9]
	s_mov_b32 m0, s71
	v_lshl_add_u64 v[8:9], s[56:57], 0, v[142:143]
	global_load_lds_dwordx4 v[2:3], off
	v_lshl_add_u64 v[2:3], v[6:7], 0, s[8:9]
	s_mov_b32 m0, s76
	s_add_u32 s60, s60, 0x80080
	global_load_lds_dwordx4 v[2:3], off
	v_lshl_add_u64 v[2:3], v[8:9], 0, s[8:9]
	s_mov_b32 m0, s77
	s_addc_u32 s61, s61, 0
	global_load_lds_dwordx4 v[2:3], off
	s_mov_b32 m0, s78
	v_lshl_add_u64 v[144:145], v[132:133], 0, s[58:59]
	global_load_lds_dwordx4 v140, s[60:61]
	s_mov_b32 m0, s79
	v_lshl_add_u64 v[146:147], v[134:135], 0, s[58:59]
	global_load_lds_dwordx4 v142, s[60:61]
	s_add_i32 s58, s83, s84
	s_waitcnt vmcnt(6)
	s_ashr_i32 s59, s58, 31
	s_lshl_b64 s[58:59], s[58:59], 12
	v_mov_b32_e32 v2, 0
	v_lshl_add_u64 v[148:149], v[136:137], 0, s[58:59]
	v_lshl_add_u64 v[150:151], v[138:139], 0, s[58:59]
	s_mov_b32 s53, -2
	s_mov_b64 s[58:59], 0
	v_mov_b32_e32 v3, v2
	v_mov_b32_e32 v4, v2
	v_mov_b32_e32 v5, v2
	v_mov_b32_e32 v6, v2
	v_mov_b32_e32 v7, v2
	v_mov_b32_e32 v8, v2
	v_mov_b32_e32 v9, v2
	s_barrier

; #define WAIT_V(n) asm volatile("s_waitcnt vmcnt(" #n ")" ::: "memory")
; #define BAR __builtin_amdgcn_s_barrier()
; template <int EPI>
; __device__ __forceinline__ void phase_gemm(const Params& p, const GemmDesc& d, char* shmc) {
;     ...
;     f32x4 acc[2][2][4][2];
; #pragma unroll
;     for (int a = 0; a < 2; ++a)
; #pragma unroll
;       for (int b = 0; b < 2; ++b)
; #pragma unroll
;         for (int m = 0; m < 4; ++m)
; #pragma unroll
;           for (int n = 0; n < 2; ++n) acc[a][b][m][n] = f32x4{0.f, 0.f, 0.f, 0.f};
;     bf16x8 At[4][2], B0[2][2], B1[2][2];
;     if constexpr (EPI == EPI_UP || EPI == EPI_QKV) {
;       if (wid == 0)
;         __builtin_amdgcn_global_load_lds((const unsigned*)(p.rstd + brow + lane * 4), (unsigned*)(shmc + 143360), 16, 0, 0);
;     }
;     STAGE_B(SB(0, 0), 0, 0); STAGE_A(SA(0, 0), 0, 0);
;     STAGE_B(SB(0, 1), 1, 0); STAGE_A(SA(0, 1), 1, 0);
;     if (wr == 1) BAR;
;     WAIT_V(4); BAR;
;     STAGE_B(SB(1, 0), 0, 1); STAGE_A(SA(1, 0), 0, 1); STAGE_B(SB(1, 1), 1, 1);
;     WAIT_V(6); BAR;
.LBB0_1152:
	s_or_b64 exec, exec, s[56:57]
	v_mov_b32_e32 v175, v163
	v_lshl_add_u64 v[2:3], s[54:55], 0, v[174:175]
	v_mov_b32_e32 v177, v163
	s_add_i32 s35, s64, 0x18000
	v_lshl_add_u64 v[4:5], s[54:55], 0, v[176:177]
	v_lshl_add_u64 v[2:3], v[2:3], 0, s[18:19]
	s_mov_b32 m0, s35
	s_add_i32 s53, s64, 0x1a000
	v_lshl_add_u64 v[6:7], s[8:9], 0, v[174:175]
	v_mov_b32_e32 v10, 0
	v_mov_b32_e32 v11, 0
	v_mov_b32_e32 v12, 0
	v_mov_b32_e32 v13, 0
	v_mov_b32_e32 v18, 0
	v_mov_b32_e32 v19, 0
	v_mov_b32_e32 v20, 0
	v_mov_b32_e32 v21, 0
	v_mov_b32_e32 v30, 0
	v_mov_b32_e32 v31, 0
	v_mov_b32_e32 v32, 0
	v_mov_b32_e32 v33, 0
	v_mov_b32_e32 v42, 0
	v_mov_b32_e32 v43, 0
	v_mov_b32_e32 v44, 0
	v_mov_b32_e32 v45, 0
	v_mov_b32_e32 v54, 0
	v_mov_b32_e32 v55, 0
	v_mov_b32_e32 v56, 0
	v_mov_b32_e32 v57, 0
	v_mov_b32_e32 v66, 0
	v_mov_b32_e32 v67, 0
	v_mov_b32_e32 v68, 0
	v_mov_b32_e32 v69, 0
	v_mov_b32_e32 v14, 0
	v_mov_b32_e32 v15, 0
	v_mov_b32_e32 v16, 0
	v_mov_b32_e32 v17, 0
	v_mov_b32_e32 v22, 0
	v_mov_b32_e32 v23, 0
	v_mov_b32_e32 v24, 0
	v_mov_b32_e32 v25, 0
	v_mov_b32_e32 v34, 0
	v_mov_b32_e32 v35, 0
	v_mov_b32_e32 v36, 0
	v_mov_b32_e32 v37, 0
	v_mov_b32_e32 v46, 0
	v_mov_b32_e32 v47, 0
	v_mov_b32_e32 v48, 0
	v_mov_b32_e32 v49, 0
	v_mov_b32_e32 v58, 0
	v_mov_b32_e32 v59, 0
	v_mov_b32_e32 v60, 0
	v_mov_b32_e32 v61, 0
	v_mov_b32_e32 v70, 0
	v_mov_b32_e32 v71, 0
	v_mov_b32_e32 v72, 0
	v_mov_b32_e32 v73, 0
	v_mov_b32_e32 v78, 0
	v_mov_b32_e32 v79, 0
	v_mov_b32_e32 v80, 0
	v_mov_b32_e32 v81, 0
	v_mov_b32_e32 v86, 0
	v_mov_b32_e32 v87, 0
	v_mov_b32_e32 v88, 0
	v_mov_b32_e32 v89, 0
	v_mov_b32_e32 v26, 0
	v_mov_b32_e32 v27, 0
	v_mov_b32_e32 v28, 0
	v_mov_b32_e32 v29, 0
	v_mov_b32_e32 v38, 0
	v_mov_b32_e32 v39, 0
	v_mov_b32_e32 v40, 0
	v_mov_b32_e32 v41, 0
	v_mov_b32_e32 v50, 0
	v_mov_b32_e32 v51, 0
	v_mov_b32_e32 v52, 0
	v_mov_b32_e32 v53, 0
	v_mov_b32_e32 v62, 0
	v_mov_b32_e32 v63, 0
	v_mov_b32_e32 v64, 0
	v_mov_b32_e32 v65, 0
	v_mov_b32_e32 v74, 0
	v_mov_b32_e32 v75, 0
	v_mov_b32_e32 v76, 0
	v_mov_b32_e32 v77, 0
	v_mov_b32_e32 v82, 0
	v_mov_b32_e32 v83, 0
	v_mov_b32_e32 v84, 0
	v_mov_b32_e32 v85, 0
	v_mov_b32_e32 v90, 0
	v_mov_b32_e32 v91, 0
	v_mov_b32_e32 v92, 0
	v_mov_b32_e32 v93, 0
	v_mov_b32_e32 v94, 0
	v_mov_b32_e32 v95, 0
	v_mov_b32_e32 v96, 0
	v_mov_b32_e32 v97, 0
	v_mov_b32_e32 v98, 0
	v_mov_b32_e32 v99, 0
	v_mov_b32_e32 v100, 0
	v_mov_b32_e32 v101, 0
	v_mov_b32_e32 v102, 0
	v_mov_b32_e32 v103, 0
	v_mov_b32_e32 v104, 0
	v_mov_b32_e32 v105, 0
	v_mov_b32_e32 v106, 0
	v_mov_b32_e32 v107, 0
	v_mov_b32_e32 v108, 0
	v_mov_b32_e32 v109, 0
	v_mov_b32_e32 v110, 0
	v_mov_b32_e32 v111, 0
	v_mov_b32_e32 v112, 0
	v_mov_b32_e32 v113, 0
	v_mov_b32_e32 v114, 0
	v_mov_b32_e32 v115, 0
	v_mov_b32_e32 v116, 0
	v_mov_b32_e32 v117, 0
	v_mov_b32_e32 v118, 0
	v_mov_b32_e32 v119, 0
	v_mov_b32_e32 v120, 0
	v_mov_b32_e32 v121, 0
	v_mov_b32_e32 v122, 0
	v_mov_b32_e32 v123, 0
	v_mov_b32_e32 v124, 0
	v_mov_b32_e32 v125, 0
	v_mov_b32_e32 v126, 0
	v_mov_b32_e32 v127, 0
	v_mov_b32_e32 v128, 0
	v_mov_b32_e32 v129, 0
	s_waitcnt vmcnt(2)
	s_barrier
	global_load_lds_dwordx4 v[2:3], off
	v_lshl_add_u64 v[2:3], v[4:5], 0, s[18:19]
	s_mov_b32 m0, s53
	s_add_i32 s56, s64, 0x8000
	s_add_i32 s57, s64, 0xa000
	v_lshl_add_u64 v[8:9], s[8:9], 0, v[176:177]
	global_load_lds_dwordx4 v[2:3], off
	v_lshl_add_u64 v[2:3], v[6:7], 0, s[18:19]
	s_mov_b32 m0, s56
	s_add_u32 s68, s54, 0x80080
	global_load_lds_dwordx4 v[2:3], off
	v_lshl_add_u64 v[2:3], v[8:9], 0, s[18:19]
	s_mov_b32 m0, s57
	s_addc_u32 s69, s55, 0
	s_add_i32 s54, s64, 0x1c000
	global_load_lds_dwordx4 v[2:3], off
	s_mov_b32 m0, s54
	s_add_i32 s55, s64, 0x1e000
	global_load_lds_dwordx4 v174, s[68:69]
	s_mov_b32 m0, s55
	v_lshl_add_u64 v[130:131], v[166:167], 0, s[10:11]
	global_load_lds_dwordx4 v176, s[68:69]
	v_lshl_add_u64 v[132:133], v[168:169], 0, s[10:11]
	s_lshl_b32 s10, s58, 11
	s_lshl_b32 s11, s59, 8
	s_or_b32 s10, s10, s11
	s_waitcnt vmcnt(6)
	s_ashr_i32 s11, s10, 31
	s_lshl_b64 s[10:11], s[10:11], 12
	v_mov_b32_e32 v2, 0
	v_lshl_add_u64 v[134:135], v[170:171], 0, s[10:11]
	v_lshl_add_u64 v[136:137], v[172:173], 0, s[10:11]
	s_mov_b32 s58, -2
	s_mov_b64 s[10:11], 0
	v_mov_b32_e32 v3, v2
	v_mov_b32_e32 v4, v2
	v_mov_b32_e32 v5, v2
	v_mov_b32_e32 v6, v2
	v_mov_b32_e32 v7, v2
	v_mov_b32_e32 v8, v2
	v_mov_b32_e32 v9, v2
	s_barrier

; template <int EPI>
; __device__ __forceinline__ void phase_gemm(const Params& p, const GemmDesc& d, char* shmc) {
;     ...
;       const int ch0 = pn * 128;
;       const float* cwp = p.conv_w + (size_t)d.layer * 3 * DFF;
;       const float* cbp = p.conv_b + (size_t)d.layer * DFF;
;       float cw[2][4];
; #pragma unroll
;       for (int n = 0; n < 2; ++n) {
;         const int chx = ch0 + ewc * 32 + n * 16 + efr;
;         cw[n][0] = cwp[chx]; cw[n][1] = cwp[DFF + chx]; cw[n][2] = cwp[2 * DFF + chx]; cw[n][3] = cbp[chx];
;       }
;       const float* rsl = reinterpret_cast<const float*>(shmc + 143360);
;       f32x4 rsv[2][4];
; #pragma unroll
;       for (int ai = 0; ai < 2; ++ai)
; #pragma unroll
;         for (int m = 0; m < 4; ++m)
;           rsv[ai][m] = *reinterpret_cast<const f32x4*>(rsl + ai * HALF + ewr * 64 + m * 16 + efq * 4);
; #pragma unroll
;       for (int ai = 0; ai < 2; ++ai)
; #pragma unroll
;         for (int m = 0; m < 4; ++m) {
;           const f32x4 rs4 = rsv[ai][m];
; #pragma unroll
;           for (int n = 0; n < 2; ++n) {
;             acc[ai][0][m][n] *= rs4;
;             acc[ai][1][m][n] *= rs4;
;             const int s = ai * 32 + ewr * 16 + m * 4 + efq;
;             const int col = ewc * 32 + n * 16 + efr;
;             top[s * 144 + col] = acc[ai][0][m][n][0];
;             bot[s * 144 + col] = acc[ai][0][m][n][3];
;           }
;         }
;       __syncthreads();
.LBB0_1156:
	s_mov_b32 s98, 0x3e8ba43f
	s_or_b64 exec, exec, s[8:9]
	v_mov_b32_e32 v38, v1
	s_lshl_b32 s54, s34, 7
	v_and_b32_e32 v177, 15, v38
	v_lshrrev_b32_e32 v30, 1, v38
	v_and_or_b32 v162, v30, s79, v177
	v_or_b32_e32 v200, s54, v162
	v_ashrrev_i32_e32 v201, 31, v200
	v_lshlrev_b64 v[30:31], 2, v[200:201]
	v_lshl_add_u64 v[32:33], s[22:23], 0, v[30:31]
	v_add_co_u32_e32 v34, vcc, 0x5000, v32
	v_lshl_add_u64 v[30:31], s[24:25], 0, v[30:31]
	s_nop 0
	v_addc_co_u32_e32 v35, vcc, 0, v33, vcc
	v_add_co_u32_e32 v36, vcc, 0xb000, v32
	v_ashrrev_i32_e32 v175, 4, v38
	s_nop 0
	v_addc_co_u32_e32 v37, vcc, 0, v33, vcc
	global_load_dword v215, v[32:33], off
	global_load_dword v217, v[34:35], off offset:2048
	global_load_dword v216, v[36:37], off
	global_load_dword v218, v[30:31], off
	v_or_b32_e32 v30, 16, v200
	v_ashrrev_i32_e32 v31, 31, v30
	v_lshlrev_b64 v[30:31], 2, v[30:31]
	v_lshl_add_u64 v[32:33], s[22:23], 0, v[30:31]
	v_add_co_u32_e32 v34, vcc, s80, v32
	v_lshl_add_u64 v[30:31], s[24:25], 0, v[30:31]
	s_nop 0
	v_addc_co_u32_e32 v35, vcc, 0, v33, vcc
	v_add_co_u32_e32 v36, vcc, s81, v32
	v_bfe_u32 v178, v38, 8, 1
	s_nop 0
	v_addc_co_u32_e32 v37, vcc, 0, v33, vcc
	global_load_dword v208, v[32:33], off
	global_load_dword v210, v[34:35], off offset:2048
	global_load_dword v209, v[36:37], off
	global_load_dword v207, v[30:31], off
	v_and_b32_e32 v179, 3, v175
	v_lshlrev_b32_e32 v30, 8, v178
	v_lshlrev_b32_e32 v31, 4, v179
	v_add3_u32 v30, s63, v30, v31
	v_lshl_or_b32 v220, v178, 4, v179
	ds_read_b128 v[62:65], v30
	ds_read_b128 v[54:57], v30 offset:64
	ds_read_b128 v[50:53], v30 offset:128
	ds_read_b128 v[46:49], v30 offset:192
	ds_read_b128 v[42:45], v30 offset:512
	ds_read_b128 v[38:41], v30 offset:576
	ds_read_b128 v[34:37], v30 offset:640
	ds_read_b128 v[30:33], v30 offset:704
	v_mad_u32_u24 v178, v220, s82, v162
	v_lshl_add_u32 v211, v178, 2, 0
	s_waitcnt lgkmcnt(0)
	v_pk_mul_f32 v[196:197], v[144:145], v[56:57]
	v_pk_mul_f32 v[198:199], v[142:143], v[54:55]
	v_pk_mul_f32 v[144:145], v[134:135], v[54:55]
	v_add_u32_e32 v134, 0x800, v211
	v_pk_mul_f32 v[190:191], v[128:129], v[52:53]
	v_pk_mul_f32 v[188:189], v[110:111], v[46:47]
	v_pk_mul_f32 v[128:129], v[102:103], v[46:47]
	v_add_u32_e32 v102, 0x1800, v211
	v_pk_mul_f32 v[142:143], v[136:137], v[56:57]
	ds_write2_b32 v134, v198, v144 offset0:64 offset1:80
	v_add_u32_e32 v134, 0x9800, v211
	v_pk_mul_f32 v[192:193], v[126:127], v[50:51]
	v_pk_mul_f32 v[136:137], v[118:119], v[50:51]
	v_add_u32_e32 v118, 0x1000, v211
	v_pk_mul_f32 v[186:187], v[112:113], v[48:49]
	v_pk_mul_f32 v[126:127], v[104:105], v[48:49]
	ds_write2_b32 v102, v188, v128 offset0:192 offset1:208
	v_add_u32_e32 v102, 0xa800, v211
	ds_write2_b32 v134, v197, v143 offset0:64 offset1:80
	v_pk_mul_f32 v[134:135], v[120:121], v[52:53]
	ds_write2_b32 v118, v192, v136 offset0:128 offset1:144
	v_add_u32_e32 v118, 0xa000, v211
	ds_write2_b32 v102, v187, v127 offset0:192 offset1:208
	v_pk_mul_f32 v[184:185], v[154:155], v[42:43]
	v_pk_mul_f32 v[120:121], v[150:151], v[42:43]
	v_add_u32_e32 v102, 0x4800, v211
	ds_write2_b32 v118, v191, v135 offset0:128 offset1:144
	v_pk_mul_f32 v[182:183], v[156:157], v[44:45]
	v_pk_mul_f32 v[118:119], v[152:153], v[44:45]
	ds_write2_b32 v102, v184, v120 offset1:16
	v_add_u32_e32 v102, 0xd800, v211
	v_pk_mul_f32 v[154:155], v[106:107], v[30:31]
	v_pk_mul_f32 v[98:99], v[98:99], v[30:31]
	v_add_u32_e32 v106, 0x6000, v211
	ds_write2_b32 v102, v183, v119 offset1:16
	v_pk_mul_f32 v[180:181], v[138:139], v[38:39]
	v_pk_mul_f32 v[112:113], v[130:131], v[38:39]
	v_add_u32_e32 v102, 0x5000, v211
	v_pk_mul_f32 v[152:153], v[108:109], v[32:33]
	v_pk_mul_f32 v[100:101], v[100:101], v[32:33]
	ds_write2_b32 v106, v154, v98 offset0:192 offset1:208
	v_add_u32_e32 v106, 0xf000, v211
	v_pk_mul_f32 v[202:203], v[160:161], v[64:65]
	v_pk_mul_f32 v[194:195], v[158:159], v[62:63]
	v_pk_mul_f32 v[146:147], v[146:147], v[62:63]
	v_pk_mul_f32 v[178:179], v[140:141], v[40:41]
	v_pk_mul_f32 v[110:111], v[132:133], v[40:41]
	ds_write2_b32 v102, v180, v112 offset0:64 offset1:80
	v_add_u32_e32 v102, 0xe000, v211
	v_pk_mul_f32 v[160:161], v[122:123], v[34:35]
	v_pk_mul_f32 v[104:105], v[114:115], v[34:35]
	v_add_u32_e32 v114, 0x5800, v211
	ds_write2_b32 v106, v153, v101 offset0:192 offset1:208
	v_mad_u32_u24 v106, v220, s83, 0
	v_pk_mul_f32 v[158:159], v[148:149], v[64:65]
	ds_write2_b32 v211, v194, v146 offset1:16
	v_add_u32_e32 v148, 0x9000, v211
	ds_write2_b32 v102, v179, v111 offset0:64 offset1:80
	v_pk_mul_f32 v[156:157], v[124:125], v[36:37]
	v_pk_mul_f32 v[102:103], v[116:117], v[36:37]
	ds_write2_b32 v114, v160, v104 offset0:128 offset1:144
	v_add_u32_e32 v114, 0xe800, v211
	v_cmp_eq_u32_e64 s[10:11], 0, v220
	v_cmp_ne_u32_e32 vcc, 0, v220
	v_mov_b32_e32 v213, 0
	v_lshl_add_u32 v211, v162, 2, v106
	v_mov_b32_e32 v224, 0
	ds_write2_b32 v148, v203, v159 offset1:16
	ds_write2_b32 v114, v157, v103 offset0:128 offset1:144
	s_waitcnt vmcnt(0) lgkmcnt(0)
	s_barrier
; __device__ __forceinline__ float erf_f32(float x) {
;   const float ax = fabsf(x);
;   const float t = __frcp_rn(fmaf(0.3275911f, ax, 1.0f));
;   float poly = fmaf(1.061405429f, t, -1.453152027f);
;   poly = fmaf(poly, t, 1.421413741f);
;   poly = fmaf(poly, t, -0.284496736f);
;   poly = fmaf(poly, t, 0.254829592f);
;   const float y = 1.0f - poly * t * __expf(-ax * ax);
; template <int EPI>
; __device__ __forceinline__ void phase_gemm(const Params& p, const GemmDesc& d, char* shmc) {
;     ...
;       float gp[2][4][2], gn[2][4][2];
; #pragma unroll
;       for (int ai = 0; ai < 2; ++ai)
; #pragma unroll
;         for (int m = 0; m < 4; ++m)
; #pragma unroll
;           for (int n = 0; n < 2; ++n) {
;             const int s = ai * 32 + ewr * 16 + m * 4 + efq;
;             const int col = ewc * 32 + n * 16 + efr;
;             gp[ai][m][n] = (s > 0) ? bot[(s - 1) * 144 + col] : 0.f;
;             gn[ai][m][n] = (s < 63) ? top[(s + 1) * 144 + col] : 0.f;
;           }
;       float* edge = p.edge + (size_t)pm * 6 * DFF;
; #pragma unroll
;       for (int n = 0; n < 2; ++n) {
;         const int col = ewc * 32 + n * 16 + efr;
;         const int ch = ch0 + col;
;         const float w0 = cw[n][0], w1 = cw[n][1], w2 = cw[n][2], cb = cw[n][3];
; #pragma unroll
;         for (int ai = 0; ai < 2; ++ai)
; #pragma unroll
;           for (int m = 0; m < 4; ++m) {
;             const int s = ai * 32 + ewr * 16 + m * 4 + efq;
;             const f32x4 g = acc[ai][0][m][n];
;             const f32x4 v = acc[ai][1][m][n];
;             const float c0 = w0 * gp[ai][m][n] + w1 * g[0] + w2 * g[1] + cb;
;             const float c1 = w0 * g[0] + w1 * g[1] + w2 * g[2] + cb;
;             const float c2 = w0 * g[1] + w1 * g[2] + w2 * g[3] + cb;
;             const float c3 = w0 * g[2] + w1 * g[3] + w2 * gn[ai][m][n] + cb;
;             u16* sp = stg + (s * 4) * 136 + col;
;             sp[0] = f2bf(gelu_exact(c0) * v[0]);
;             sp[136] = f2bf(gelu_exact(c1) * v[1]);
;             sp[272] = f2bf(gelu_exact(c2) * v[2]);
;             sp[408] = f2bf(gelu_exact(c3) * v[3]);
;             if (s == 0) {
;               edge[0 * DFF + ch] = c0; edge[1 * DFF + ch] = g[0]; edge[2 * DFF + ch] = v[0];
;             }
;             if (s == 63) {
;               edge[3 * DFF + ch] = c3; edge[4 * DFF + ch] = g[3]; edge[5 * DFF + ch] = v[3];
;             }
;           }
	s_and_saveexec_b64 s[8:9], vcc
	ds_read_b32 v224, v211 offset:36288
	s_or_b64 exec, exec, s[8:9]
	ds_read_b32 v223, v211 offset:576
	s_and_saveexec_b64 s[8:9], vcc
	ds_read_b32 v213, v211 offset:36352
	s_or_b64 exec, exec, s[8:9]
	v_add_u32_e32 v106, 0x9400, v211
	ds_read2_b32 v[150:151], v106 offset0:176 offset1:192
	v_add_u32_e32 v106, 0x800, v211
	ds_read2_b32 v[148:149], v106 offset0:208 offset1:224
	v_add_u32_e32 v106, 0x9e00, v211
	ds_read2_b32 v[140:141], v106 offset0:112 offset1:128
	v_add_u32_e32 v106, 0x1400, v211
	ds_read2_b32 v[138:139], v106 offset0:16 offset1:32
	v_add_u32_e32 v106, 0xa800, v211
	ds_read2_b32 v[132:133], v106 offset0:48 offset1:64
	v_add_u32_e32 v106, 0x1c00, v211
	ds_read2_b32 v[130:131], v106 offset0:80 offset1:96
	v_add_u32_e32 v106, 0xd400, v211
	ds_read2_b32 v[124:125], v106 offset0:112 offset1:128
	v_add_u32_e32 v106, 0x4800, v211
	ds_read2_b32 v[122:123], v106 offset0:144 offset1:160
	v_add_u32_e32 v106, 0xdc00, v211
	ds_read2_b32 v[116:117], v106 offset0:176 offset1:192
	v_add_u32_e32 v106, 0x5000, v211
	ds_read2_b32 v[114:115], v106 offset0:208 offset1:224
	v_add_u32_e32 v106, 0xe600, v211
	ds_read2_b32 v[108:109], v106 offset0:112 offset1:128
	v_add_u32_e32 v106, 0x5c00, v211
	ds_read2_b32 v[106:107], v106 offset0:16 offset1:32
	ds_read_b32 v214, v211 offset:640
	ds_read_b32 v221, v211 offset:61632
	v_cmp_eq_u32_e64 s[8:9], 19, v220
	v_cmp_ne_u32_e32 vcc, 19, v220
	v_add_u32_e32 v222, 0x6300, v211
	v_mov_b32_e32 v211, 0
	v_mov_b32_e32 v219, 0
	s_and_saveexec_b64 s[56:57], vcc
	ds_read_b32 v219, v222 offset:576
	s_or_b64 exec, exec, s[56:57]
	ds_read_b32 v212, v222 offset:36352
	s_and_saveexec_b64 s[56:57], vcc
	ds_read_b32 v211, v222 offset:640
	s_or_b64 exec, exec, s[56:57]
	s_mul_hi_i32 s34, s14, 0x21000
	s_mul_i32 s14, s14, 0x21000
	v_readlane_b32 s56, v246, 15
	v_readlane_b32 s57, v246, 16
	s_add_u32 s56, s56, s14
	s_addc_u32 s57, s57, s34
	v_pk_mul_f32 v[226:227], v[96:97], v[64:65]
	v_pk_mul_f32 v[96:97], v[94:95], v[62:63]
	v_lshl_add_u64 v[94:95], v[200:201], 2, s[56:57]
	s_waitcnt lgkmcnt(14)
	v_mul_f32_e32 v200, v215, v224
	v_fmac_f32_e32 v200, v217, v194
	v_mul_f32_e32 v224, v217, v202
	v_fmac_f32_e32 v200, v216, v195
	v_mul_f32_e32 v201, v217, v195
	v_fmac_f32_e32 v224, v215, v195
	v_add_f32_e32 v200, v218, v200
	v_fmac_f32_e32 v201, v215, v194
	v_fmac_f32_e32 v224, v216, v203
	v_mul_f32_e32 v203, v217, v203
	v_fmac_f32_e32 v201, v216, v202
	v_fmac_f32_e32 v203, v215, v202
	v_mul_f32_e32 v202, 0x3f596d27, v200
	v_fmac_f32_e32 v203, v216, v223
	v_fma_f32 v223, |v202|, s98, 1.0
	v_add_f32_e32 v195, v218, v224
	v_add_f32_e32 v201, v218, v201
	v_mul_f32_e32 v229, 0.5, v200
	s_add_i32 s14, 0, 0x12000
	v_rcp_f32_e32 v223, v223
	v_mul_f32_e64 v225, |v202|, -|v202|
	v_fmamk_f32 v224, v223, 0x3f87dc22, v206
	v_fmaak_f32 v224, v224, v223, 0x3fb5f0e3
	v_exp_f32_e32 v225, v225
	v_fmaak_f32 v224, v224, v223, 0xbe91a98e
	v_fmaak_f32 v224, v224, v223, 0x3e827906
	v_mul_f32_e32 v223, v223, v224
	v_fma_f32 v202, -v225, v223, 1.0
	v_mul_f32_e32 v223, 0x3f596d27, v201
	v_fma_f32 v224, |v223|, s98, 1.0
	v_fma_f32 v202, |v229|, v202, v229
	v_lshl_add_u32 v222, v162, 1, s14
	v_mul_f32_e32 v202, v96, v202
	v_mad_u32_u24 v228, v220, s84, v222
	v_cvt_pk_bf16_f32 v202, v202, s0
	ds_write_b16 v228, v202
	v_rcp_f32_e32 v202, v224
	v_mul_f32_e64 v225, |v223|, -|v223|
	v_fmamk_f32 v224, v202, 0x3f87dc22, v206
	v_fmaak_f32 v224, v224, v202, 0x3fb5f0e3
	v_exp_f32_e32 v225, v225
	v_fmaak_f32 v224, v224, v202, 0xbe91a98e
	v_fmaak_f32 v224, v224, v202, 0x3e827906
	v_mul_f32_e32 v202, v202, v224
	v_fma_f32 v202, -v225, v202, 1.0
	v_mul_f32_e32 v201, 0.5, v201
	v_fma_f32 v201, |v201|, v202, v201
	v_mul_f32_e32 v97, v97, v201
	v_mul_f32_e32 v201, 0x3f596d27, v195
	v_fma_f32 v202, |v201|, s98, 1.0
	v_cvt_pk_bf16_f32 v97, v97, s0
	ds_write_b16 v228, v97 offset:272
	v_mul_f32_e32 v97, 0.5, v195
	v_rcp_f32_e32 v195, v202
	v_mul_f32_e64 v223, |v201|, -|v201|
	v_fmamk_f32 v202, v195, 0x3f87dc22, v206
	v_fmaak_f32 v202, v202, v195, 0x3fb5f0e3
	v_exp_f32_e32 v223, v223
	v_fmaak_f32 v202, v202, v195, 0xbe91a98e
	v_fmaak_f32 v202, v202, v195, 0x3e827906
	v_mul_f32_e32 v195, v195, v202
	v_fma_f32 v195, -v223, v195, 1.0
	v_add_f32_e32 v203, v218, v203
	v_fma_f32 v97, |v97|, v195, v97
	v_mul_f32_e32 v195, 0x3f596d27, v203
	v_fma_f32 v201, |v195|, s98, 1.0
	v_mul_f32_e32 v97, v226, v97
	v_cvt_pk_bf16_f32 v97, v97, s0
	ds_write_b16 v228, v97 offset:544
	v_mul_f32_e32 v97, 0.5, v203
	v_rcp_f32_e32 v201, v201
	v_mul_f32_e64 v203, |v195|, -|v195|
	v_fmamk_f32 v202, v201, 0x3f87dc22, v206
	v_fmaak_f32 v202, v202, v201, 0x3fb5f0e3
	v_exp_f32_e32 v203, v203
	v_fmaak_f32 v202, v202, v201, 0xbe91a98e
	v_fmaak_f32 v202, v202, v201, 0x3e827906
	v_mul_f32_e32 v201, v201, v202
	v_fma_f32 v195, -v203, v201, 1.0
	v_fma_f32 v97, |v97|, v195, v97
	v_mul_f32_e32 v97, v227, v97
	v_readlane_b32 s58, v246, 17
	v_readlane_b32 s59, v246, 18
	v_cvt_pk_bf16_f32 v97, v97, s0
	ds_write_b16 v228, v97 offset:816
	s_and_saveexec_b64 s[58:59], s[10:11]
	s_cbranch_execz .LBB0_1166
	global_store_dword v[94:95], v200, off
	v_add_co_u32_e32 v200, vcc, 0x5000, v94
	s_nop 1
	v_addc_co_u32_e32 v201, vcc, 0, v95, vcc
	global_store_dword v[200:201], v194, off offset:2048
	v_add_co_u32_e32 v194, vcc, 0xb000, v94
	s_nop 1
	v_addc_co_u32_e32 v195, vcc, 0, v95, vcc
	global_store_dword v[194:195], v96, off
; __device__ __forceinline__ u16 f2bf(float f) { return (u16)(pack2(f, f) & 0xffffu); }
; __device__ __forceinline__ float erf_f32(float x) {
;   const float ax = fabsf(x);
;   const float t = __frcp_rn(fmaf(0.3275911f, ax, 1.0f));
;   float poly = fmaf(1.061405429f, t, -1.453152027f);
;   poly = fmaf(poly, t, 1.421413741f);
;   poly = fmaf(poly, t, -0.284496736f);
;   poly = fmaf(poly, t, 0.254829592f);
;   const float y = 1.0f - poly * t * __expf(-ax * ax);
;   return copysignf(y, x);
; }
; __device__ __forceinline__ float gelu_exact(float x) { return 0.5f * x * (1.0f + erf_f32(x * 0.70710678118654752f)); }
; template <int EPI>
; __device__ __forceinline__ void phase_gemm(const Params& p, const GemmDesc& d, char* shmc) {
;     ...
; #pragma unroll
;       for (int n = 0; n < 2; ++n) {
;         const int col = ewc * 32 + n * 16 + efr;
;         const int ch = ch0 + col;
;         const float w0 = cw[n][0], w1 = cw[n][1], w2 = cw[n][2], cb = cw[n][3];
; #pragma unroll
;         for (int ai = 0; ai < 2; ++ai)
; #pragma unroll
;           for (int m = 0; m < 4; ++m) {
;             const int s = ai * 32 + ewr * 16 + m * 4 + efq;
;             const f32x4 g = acc[ai][0][m][n];
;             const f32x4 v = acc[ai][1][m][n];
;             const float c0 = w0 * gp[ai][m][n] + w1 * g[0] + w2 * g[1] + cb;
;             const float c1 = w0 * g[0] + w1 * g[1] + w2 * g[2] + cb;
;             const float c2 = w0 * g[1] + w1 * g[2] + w2 * g[3] + cb;
;             const float c3 = w0 * g[2] + w1 * g[3] + w2 * gn[ai][m][n] + cb;
;             u16* sp = stg + (s * 4) * 136 + col;
;             sp[0] = f2bf(gelu_exact(c0) * v[0]);
;             sp[136] = f2bf(gelu_exact(c1) * v[1]);
;             sp[272] = f2bf(gelu_exact(c2) * v[2]);
;             sp[408] = f2bf(gelu_exact(c3) * v[3]);
;             if (s == 0) {
;               edge[0 * DFF + ch] = c0; edge[1 * DFF + ch] = g[0]; edge[2 * DFF + ch] = v[0];
;             }
;             if (s == 63) {
;               edge[3 * DFF + ch] = c3; edge[4 * DFF + ch] = g[3]; edge[5 * DFF + ch] = v[3];
;             }
;           }
.LBB0_1166:
	s_or_b64 exec, exec, s[58:59]
	v_pk_mul_f32 v[96:97], v[68:69], v[48:49]
	v_pk_mul_f32 v[68:69], v[78:79], v[30:31]
	v_mul_f32_e32 v78, v215, v150
	v_fmac_f32_e32 v78, v217, v198
	v_fmac_f32_e32 v78, v216, v199
	v_add_f32_e32 v79, v218, v78
	v_pk_mul_f32 v[200:201], v[72:73], v[52:53]
	v_pk_mul_f32 v[72:73], v[82:83], v[34:35]
	v_mul_f32_e32 v83, 0x3f596d27, v79
	v_pk_mul_f32 v[202:203], v[70:71], v[50:51]
	v_pk_mul_f32 v[70:71], v[84:85], v[36:37]
	v_fma_f32 v84, |v83|, s98, 1.0
	v_mul_f32_e32 v78, v217, v199
	v_pk_mul_f32 v[224:225], v[76:77], v[56:57]
	v_pk_mul_f32 v[76:77], v[86:87], v[38:39]
	v_fmac_f32_e32 v78, v215, v198
	v_fmac_f32_e32 v78, v216, v196
	v_pk_mul_f32 v[194:195], v[66:67], v[46:47]
	v_pk_mul_f32 v[66:67], v[80:81], v[32:33]
	v_add_f32_e32 v80, v218, v78
	v_mul_f32_e32 v78, v217, v196
	v_fmac_f32_e32 v78, v215, v199
	v_pk_mul_f32 v[226:227], v[74:75], v[54:55]
	v_pk_mul_f32 v[74:75], v[88:89], v[40:41]
	v_fmac_f32_e32 v78, v216, v197
	v_add_f32_e32 v81, v218, v78
	v_mul_f32_e32 v78, v217, v197
	v_fmac_f32_e32 v78, v215, v196
	s_waitcnt lgkmcnt(14)
	v_fmac_f32_e32 v78, v216, v148
	v_rcp_f32_e32 v84, v84
	v_mul_f32_e64 v86, |v83|, -|v83|
	v_fmamk_f32 v85, v84, 0x3f87dc22, v206
	v_fmaak_f32 v85, v85, v84, 0x3fb5f0e3
	v_exp_f32_e32 v86, v86
	v_fmaak_f32 v85, v85, v84, 0xbe91a98e
	v_fmaak_f32 v85, v85, v84, 0x3e827906
	v_mul_f32_e32 v84, v84, v85
	v_fma_f32 v83, -v86, v84, 1.0
	v_mul_f32_e32 v79, 0.5, v79
	v_fma_f32 v79, |v79|, v83, v79
	v_mul_f32_e32 v83, 0x3f596d27, v80
	v_fma_f32 v84, |v83|, s98, 1.0
	v_mul_u32_u24_e32 v220, 0x440, v220
	v_add_f32_e32 v82, v218, v78
	v_add_u32_e32 v78, 0x1100, v220
	v_mul_f32_e32 v79, v226, v79
	v_add_u32_e32 v87, v222, v78
	v_cvt_pk_bf16_f32 v79, v79, s0
	ds_write_b16 v87, v79
	v_mul_f32_e32 v79, 0.5, v80
	v_rcp_f32_e32 v80, v84
	v_mul_f32_e64 v85, |v83|, -|v83|
	v_fmamk_f32 v84, v80, 0x3f87dc22, v206
	v_fmaak_f32 v84, v84, v80, 0x3fb5f0e3
	v_exp_f32_e32 v85, v85
	v_fmaak_f32 v84, v84, v80, 0xbe91a98e
	v_fmaak_f32 v84, v84, v80, 0x3e827906
	v_mul_f32_e32 v80, v80, v84
	v_fma_f32 v80, -v85, v80, 1.0
	v_fma_f32 v79, |v79|, v80, v79
	v_mul_f32_e32 v80, 0x3f596d27, v81
	v_fma_f32 v83, |v80|, s98, 1.0
	v_mul_f32_e32 v79, v227, v79
	v_cvt_pk_bf16_f32 v79, v79, s0
	ds_write_b16 v87, v79 offset:272
	v_mul_f32_e32 v79, 0.5, v81
	v_rcp_f32_e32 v81, v83
	v_mul_f32_e64 v84, |v80|, -|v80|
	v_fmamk_f32 v83, v81, 0x3f87dc22, v206
	v_fmaak_f32 v83, v83, v81, 0x3fb5f0e3
	v_exp_f32_e32 v84, v84
	v_fmaak_f32 v83, v83, v81, 0xbe91a98e
	v_fmaak_f32 v83, v83, v81, 0x3e827906
	v_mul_f32_e32 v81, v81, v83
	v_fma_f32 v80, -v84, v81, 1.0
	v_fma_f32 v79, |v79|, v80, v79
	v_mul_f32_e32 v80, 0x3f596d27, v82
	v_fma_f32 v81, |v80|, s98, 1.0
	v_mul_f32_e32 v79, v224, v79
	v_cvt_pk_bf16_f32 v79, v79, s0
	ds_write_b16 v87, v79 offset:544
	v_mul_f32_e32 v79, 0.5, v82
	v_rcp_f32_e32 v81, v81
	v_mul_f32_e64 v83, |v80|, -|v80|
	v_fmamk_f32 v82, v81, 0x3f87dc22, v206
	v_fmaak_f32 v82, v82, v81, 0x3fb5f0e3
	v_exp_f32_e32 v83, v83
	v_fmaak_f32 v82, v82, v81, 0xbe91a98e
	v_fmaak_f32 v82, v82, v81, 0x3e827906
	v_mul_f32_e32 v81, v81, v82
	v_fma_f32 v80, -v83, v81, 1.0
	v_fma_f32 v79, |v79|, v80, v79
	v_mul_f32_e32 v79, v225, v79
	v_cvt_pk_bf16_f32 v79, v79, s0
	ds_write_b16 v87, v79 offset:816
	v_mul_f32_e32 v79, v215, v140
	v_fmac_f32_e32 v79, v217, v192
	v_fmac_f32_e32 v79, v216, v193
	v_add_f32_e32 v80, v218, v79
	v_mul_f32_e32 v84, 0x3f596d27, v80
	v_mul_f32_e32 v79, v217, v193
	v_fma_f32 v85, |v84|, s98, 1.0
	v_fmac_f32_e32 v79, v215, v192
	v_fmac_f32_e32 v79, v216, v190
	v_add_f32_e32 v81, v218, v79
	v_mul_f32_e32 v79, v217, v190
	v_fmac_f32_e32 v79, v215, v193
	v_fmac_f32_e32 v79, v216, v191
	v_add_f32_e32 v82, v218, v79
	v_mul_f32_e32 v79, v217, v191
	v_fmac_f32_e32 v79, v215, v190
	v_fmac_f32_e32 v79, v216, v138
	v_rcp_f32_e32 v85, v85
	v_mul_f32_e64 v87, |v84|, -|v84|
	v_fmamk_f32 v86, v85, 0x3f87dc22, v206
	v_fmaak_f32 v86, v86, v85, 0x3fb5f0e3
	v_exp_f32_e32 v87, v87
	v_fmaak_f32 v86, v86, v85, 0xbe91a98e
	v_fmaak_f32 v86, v86, v85, 0x3e827906
	v_mul_f32_e32 v85, v85, v86
	v_fma_f32 v84, -v87, v85, 1.0
	v_mul_f32_e32 v80, 0.5, v80
	v_fma_f32 v80, |v80|, v84, v80
	v_mul_f32_e32 v84, 0x3f596d27, v81
	v_fma_f32 v85, |v84|, s98, 1.0
	v_add_f32_e32 v83, v218, v79
	v_add_u32_e32 v79, 0x2200, v220
	v_mul_f32_e32 v80, v202, v80
	v_add_u32_e32 v88, v222, v79
	v_cvt_pk_bf16_f32 v80, v80, s0
	ds_write_b16 v88, v80
	v_mul_f32_e32 v80, 0.5, v81
	v_rcp_f32_e32 v81, v85
	v_mul_f32_e64 v86, |v84|, -|v84|
	v_fmamk_f32 v85, v81, 0x3f87dc22, v206
	v_fmaak_f32 v85, v85, v81, 0x3fb5f0e3
	v_exp_f32_e32 v86, v86
	v_fmaak_f32 v85, v85, v81, 0xbe91a98e
	v_fmaak_f32 v85, v85, v81, 0x3e827906
	v_mul_f32_e32 v81, v81, v85
	v_fma_f32 v81, -v86, v81, 1.0
	v_fma_f32 v80, |v80|, v81, v80
	v_mul_f32_e32 v81, 0x3f596d27, v82
	v_fma_f32 v84, |v81|, s98, 1.0
	v_mul_f32_e32 v80, v203, v80
	v_cvt_pk_bf16_f32 v80, v80, s0
	ds_write_b16 v88, v80 offset:272
	v_mul_f32_e32 v80, 0.5, v82
	v_rcp_f32_e32 v82, v84
	v_mul_f32_e64 v85, |v81|, -|v81|
	v_fmamk_f32 v84, v82, 0x3f87dc22, v206
	v_fmaak_f32 v84, v84, v82, 0x3fb5f0e3
	v_exp_f32_e32 v85, v85
	v_fmaak_f32 v84, v84, v82, 0xbe91a98e
	v_fmaak_f32 v84, v84, v82, 0x3e827906
	v_mul_f32_e32 v82, v82, v84
	v_fma_f32 v81, -v85, v82, 1.0
	v_fma_f32 v80, |v80|, v81, v80
	v_mul_f32_e32 v81, 0x3f596d27, v83
	v_fma_f32 v82, |v81|, s98, 1.0
	v_mul_f32_e32 v80, v200, v80
	v_cvt_pk_bf16_f32 v80, v80, s0
	ds_write_b16 v88, v80 offset:544
	v_mul_f32_e32 v80, 0.5, v83
	v_rcp_f32_e32 v82, v82
	v_mul_f32_e64 v84, |v81|, -|v81|
	v_fmamk_f32 v83, v82, 0x3f87dc22, v206
	v_fmaak_f32 v83, v83, v82, 0x3fb5f0e3
	v_exp_f32_e32 v84, v84
	v_fmaak_f32 v83, v83, v82, 0xbe91a98e
	v_fmaak_f32 v83, v83, v82, 0x3e827906
	v_mul_f32_e32 v82, v82, v83
	v_fma_f32 v81, -v84, v82, 1.0
	v_fma_f32 v80, |v80|, v81, v80
	v_mul_f32_e32 v80, v201, v80
	v_cvt_pk_bf16_f32 v80, v80, s0
	ds_write_b16 v88, v80 offset:816
	v_mul_f32_e32 v80, v215, v132
	v_fmac_f32_e32 v80, v217, v188
	v_fmac_f32_e32 v80, v216, v189
	v_add_f32_e32 v81, v218, v80
	v_mul_f32_e32 v80, v217, v189
	v_fmac_f32_e32 v80, v215, v188
	v_mul_f32_e32 v85, 0x3f596d27, v81
	v_fmac_f32_e32 v80, v216, v186
	v_fma_f32 v86, |v85|, s98, 1.0
	v_add_f32_e32 v82, v218, v80
	v_mul_f32_e32 v80, v217, v186
	v_fmac_f32_e32 v80, v215, v189
	v_fmac_f32_e32 v80, v216, v187
	v_add_f32_e32 v83, v218, v80
	v_mul_f32_e32 v80, v217, v187
	v_fmac_f32_e32 v80, v215, v186
	s_waitcnt lgkmcnt(14)
; __device__ __forceinline__ u16 f2bf(float f) { return (u16)(pack2(f, f) & 0xffffu); }
; __device__ __forceinline__ float erf_f32(float x) {
;   const float ax = fabsf(x);
;   const float t = __frcp_rn(fmaf(0.3275911f, ax, 1.0f));
;   float poly = fmaf(1.061405429f, t, -1.453152027f);
;   poly = fmaf(poly, t, 1.421413741f);
;   poly = fmaf(poly, t, -0.284496736f);
;   poly = fmaf(poly, t, 0.254829592f);
;   const float y = 1.0f - poly * t * __expf(-ax * ax);
;   return copysignf(y, x);
; }
; __device__ __forceinline__ float gelu_exact(float x) { return 0.5f * x * (1.0f + erf_f32(x * 0.70710678118654752f)); }
; template <int EPI>
; __device__ __forceinline__ void phase_gemm(const Params& p, const GemmDesc& d, char* shmc) {
;     ...
; #pragma unroll
;       for (int n = 0; n < 2; ++n) {
;         const int col = ewc * 32 + n * 16 + efr;
;         const int ch = ch0 + col;
;         const float w0 = cw[n][0], w1 = cw[n][1], w2 = cw[n][2], cb = cw[n][3];
; #pragma unroll
;         for (int ai = 0; ai < 2; ++ai)
; #pragma unroll
;           for (int m = 0; m < 4; ++m) {
;             const int s = ai * 32 + ewr * 16 + m * 4 + efq;
;             const f32x4 g = acc[ai][0][m][n];
;             const f32x4 v = acc[ai][1][m][n];
;             const float c0 = w0 * gp[ai][m][n] + w1 * g[0] + w2 * g[1] + cb;
;             const float c1 = w0 * g[0] + w1 * g[1] + w2 * g[2] + cb;
;             const float c2 = w0 * g[1] + w1 * g[2] + w2 * g[3] + cb;
;             const float c3 = w0 * g[2] + w1 * g[3] + w2 * gn[ai][m][n] + cb;
;             u16* sp = stg + (s * 4) * 136 + col;
;             sp[0] = f2bf(gelu_exact(c0) * v[0]);
;             sp[136] = f2bf(gelu_exact(c1) * v[1]);
;             sp[272] = f2bf(gelu_exact(c2) * v[2]);
;             sp[408] = f2bf(gelu_exact(c3) * v[3]);
;             if (s == 0) {
;               edge[0 * DFF + ch] = c0; edge[1 * DFF + ch] = g[0]; edge[2 * DFF + ch] = v[0];
;             }
;             if (s == 63) {
;               edge[3 * DFF + ch] = c3; edge[4 * DFF + ch] = g[3]; edge[5 * DFF + ch] = v[3];
;             }
;           }
	v_fmac_f32_e32 v80, v216, v130
	v_rcp_f32_e32 v86, v86
	v_mul_f32_e64 v88, |v85|, -|v85|
	v_fmamk_f32 v87, v86, 0x3f87dc22, v206
	v_fmaak_f32 v87, v87, v86, 0x3fb5f0e3
	v_exp_f32_e32 v88, v88
	v_fmaak_f32 v87, v87, v86, 0xbe91a98e
	v_fmaak_f32 v87, v87, v86, 0x3e827906
	v_mul_f32_e32 v86, v86, v87
	v_fma_f32 v85, -v88, v86, 1.0
	v_mul_f32_e32 v81, 0.5, v81
	v_fma_f32 v81, |v81|, v85, v81
	v_mul_f32_e32 v85, 0x3f596d27, v82
	v_fma_f32 v86, |v85|, s98, 1.0
	v_add_f32_e32 v84, v218, v80
	v_add_u32_e32 v80, 0x3300, v220
	v_mul_f32_e32 v81, v194, v81
	v_add_u32_e32 v89, v222, v80
	v_cvt_pk_bf16_f32 v81, v81, s0
	ds_write_b16 v89, v81
	v_mul_f32_e32 v81, 0.5, v82
	v_rcp_f32_e32 v82, v86
	v_mul_f32_e64 v87, |v85|, -|v85|
	v_fmamk_f32 v86, v82, 0x3f87dc22, v206
	v_fmaak_f32 v86, v86, v82, 0x3fb5f0e3
	v_exp_f32_e32 v87, v87
	v_fmaak_f32 v86, v86, v82, 0xbe91a98e
	v_fmaak_f32 v86, v86, v82, 0x3e827906
	v_mul_f32_e32 v82, v82, v86
	v_fma_f32 v82, -v87, v82, 1.0
	v_fma_f32 v81, |v81|, v82, v81
	v_mul_f32_e32 v82, 0x3f596d27, v83
	v_fma_f32 v85, |v82|, s98, 1.0
	v_mul_f32_e32 v81, v195, v81
	v_cvt_pk_bf16_f32 v81, v81, s0
	ds_write_b16 v89, v81 offset:272
	v_mul_f32_e32 v81, 0.5, v83
	v_rcp_f32_e32 v83, v85
	v_mul_f32_e64 v86, |v82|, -|v82|
	v_fmamk_f32 v85, v83, 0x3f87dc22, v206
	v_fmaak_f32 v85, v85, v83, 0x3fb5f0e3
	v_exp_f32_e32 v86, v86
	v_fmaak_f32 v85, v85, v83, 0xbe91a98e
	v_fmaak_f32 v85, v85, v83, 0x3e827906
	v_mul_f32_e32 v83, v83, v85
	v_fma_f32 v82, -v86, v83, 1.0
	v_fma_f32 v81, |v81|, v82, v81
	v_mul_f32_e32 v82, 0x3f596d27, v84
	v_fma_f32 v83, |v82|, s98, 1.0
	v_mul_f32_e32 v81, v96, v81
	v_cvt_pk_bf16_f32 v81, v81, s0
	ds_write_b16 v89, v81 offset:544
	v_mul_f32_e32 v81, 0.5, v84
	v_rcp_f32_e32 v83, v83
	v_mul_f32_e64 v85, |v82|, -|v82|
	v_fmamk_f32 v84, v83, 0x3f87dc22, v206
	v_fmaak_f32 v84, v84, v83, 0x3fb5f0e3
	v_exp_f32_e32 v85, v85
	v_fmaak_f32 v84, v84, v83, 0xbe91a98e
	v_fmaak_f32 v84, v84, v83, 0x3e827906
	v_mul_f32_e32 v83, v83, v84
	v_fma_f32 v82, -v85, v83, 1.0
	v_fma_f32 v81, |v81|, v82, v81
	v_mul_f32_e32 v81, v97, v81
	v_cvt_pk_bf16_f32 v81, v81, s0
	ds_write_b16 v89, v81 offset:816
	v_mul_f32_e32 v81, v215, v124
	v_fmac_f32_e32 v81, v217, v184
	v_fmac_f32_e32 v81, v216, v185
	v_add_f32_e32 v82, v218, v81
	v_mul_f32_e32 v86, 0x3f596d27, v82
	v_mul_f32_e32 v81, v217, v185
	v_fma_f32 v87, |v86|, s98, 1.0
	v_fmac_f32_e32 v81, v215, v184
	v_fmac_f32_e32 v81, v216, v182
	v_add_f32_e32 v83, v218, v81
	v_mul_f32_e32 v81, v217, v182
	v_fmac_f32_e32 v81, v215, v185
	v_fmac_f32_e32 v81, v216, v183
	v_add_f32_e32 v84, v218, v81
	v_mul_f32_e32 v81, v217, v183
	v_fmac_f32_e32 v81, v215, v182
	v_fmac_f32_e32 v81, v216, v122
	v_rcp_f32_e32 v87, v87
	v_mul_f32_e64 v89, |v86|, -|v86|
	v_fmamk_f32 v88, v87, 0x3f87dc22, v206
	v_fmaak_f32 v88, v88, v87, 0x3fb5f0e3
	v_exp_f32_e32 v89, v89
	v_fmaak_f32 v88, v88, v87, 0xbe91a98e
	v_fmaak_f32 v88, v88, v87, 0x3e827906
	v_mul_f32_e32 v87, v87, v88
	v_fma_f32 v86, -v89, v87, 1.0
	v_mul_f32_e32 v82, 0.5, v82
	v_fma_f32 v82, |v82|, v86, v82
	v_mul_f32_e32 v86, 0x3f596d27, v83
	v_fma_f32 v87, |v86|, s98, 1.0
	v_pk_mul_f32 v[90:91], v[90:91], v[42:43]
	v_add_f32_e32 v85, v218, v81
	v_add_u32_e32 v81, 0x8800, v220
	v_mul_f32_e32 v82, v90, v82
	v_add_u32_e32 v96, v222, v81
	v_cvt_pk_bf16_f32 v82, v82, s0
	ds_write_b16 v96, v82
	v_mul_f32_e32 v82, 0.5, v83
	v_rcp_f32_e32 v83, v87
	v_mul_f32_e64 v88, |v86|, -|v86|
	v_fmamk_f32 v87, v83, 0x3f87dc22, v206
	v_fmaak_f32 v87, v87, v83, 0x3fb5f0e3
	v_exp_f32_e32 v88, v88
	v_fmaak_f32 v87, v87, v83, 0xbe91a98e
	v_fmaak_f32 v87, v87, v83, 0x3e827906
	v_mul_f32_e32 v83, v83, v87
	v_fma_f32 v83, -v88, v83, 1.0
	v_fma_f32 v82, |v82|, v83, v82
	v_mul_f32_e32 v83, 0x3f596d27, v84
	v_fma_f32 v86, |v83|, s98, 1.0
	v_mul_f32_e32 v82, v91, v82
	v_cvt_pk_bf16_f32 v82, v82, s0
	ds_write_b16 v96, v82 offset:272
	v_mul_f32_e32 v82, 0.5, v84
	v_rcp_f32_e32 v84, v86
	v_mul_f32_e64 v87, |v83|, -|v83|
	v_fmamk_f32 v86, v84, 0x3f87dc22, v206
	v_fmaak_f32 v86, v86, v84, 0x3fb5f0e3
	v_exp_f32_e32 v87, v87
	v_fmaak_f32 v86, v86, v84, 0xbe91a98e
	v_fmaak_f32 v86, v86, v84, 0x3e827906
	v_mul_f32_e32 v84, v84, v86
	v_fma_f32 v83, -v87, v84, 1.0
	v_fma_f32 v82, |v82|, v83, v82
	v_mul_f32_e32 v83, 0x3f596d27, v85
	v_fma_f32 v84, |v83|, s98, 1.0
	v_pk_mul_f32 v[92:93], v[92:93], v[44:45]
	s_nop 0
	v_mul_f32_e32 v82, v92, v82
	v_cvt_pk_bf16_f32 v82, v82, s0
	ds_write_b16 v96, v82 offset:544
	v_mul_f32_e32 v82, 0.5, v85
	v_rcp_f32_e32 v84, v84
	v_mul_f32_e64 v86, |v83|, -|v83|
	v_fmamk_f32 v85, v84, 0x3f87dc22, v206
	v_fmaak_f32 v85, v85, v84, 0x3fb5f0e3
	v_exp_f32_e32 v86, v86
	v_fmaak_f32 v85, v85, v84, 0xbe91a98e
	v_fmaak_f32 v85, v85, v84, 0x3e827906
	v_mul_f32_e32 v84, v84, v85
	v_fma_f32 v83, -v86, v84, 1.0
	v_fma_f32 v82, |v82|, v83, v82
	v_mul_f32_e32 v82, v93, v82
	v_cvt_pk_bf16_f32 v82, v82, s0
	ds_write_b16 v96, v82 offset:816
	v_mul_f32_e32 v82, v215, v116
	v_fmac_f32_e32 v82, v217, v180
	v_fmac_f32_e32 v82, v216, v181
	v_add_f32_e32 v83, v218, v82
	v_mul_f32_e32 v87, 0x3f596d27, v83
	v_fma_f32 v88, |v87|, s98, 1.0
	v_mul_f32_e32 v82, v217, v181
	v_fmac_f32_e32 v82, v215, v180
	v_fmac_f32_e32 v82, v216, v178
	v_rcp_f32_e32 v88, v88
	v_mul_f32_e64 v90, |v87|, -|v87|
	v_fmamk_f32 v89, v88, 0x3f87dc22, v206
	v_fmaak_f32 v89, v89, v88, 0x3fb5f0e3
	v_exp_f32_e32 v90, v90
	v_fmaak_f32 v89, v89, v88, 0xbe91a98e
	v_fmaak_f32 v89, v89, v88, 0x3e827906
	v_mul_f32_e32 v88, v88, v89
	v_fma_f32 v87, -v90, v88, 1.0
	v_mul_f32_e32 v83, 0.5, v83
	v_add_f32_e32 v84, v218, v82
	v_mul_f32_e32 v82, v217, v178
	v_fma_f32 v83, |v83|, v87, v83
	v_fmac_f32_e32 v82, v215, v181
	v_mul_f32_e32 v76, v76, v83
; __device__ __forceinline__ u16 f2bf(float f) { return (u16)(pack2(f, f) & 0xffffu); }
; __device__ __forceinline__ float erf_f32(float x) {
;   const float ax = fabsf(x);
;   const float t = __frcp_rn(fmaf(0.3275911f, ax, 1.0f));
;   float poly = fmaf(1.061405429f, t, -1.453152027f);
;   poly = fmaf(poly, t, 1.421413741f);
;   poly = fmaf(poly, t, -0.284496736f);
;   poly = fmaf(poly, t, 0.254829592f);
;   const float y = 1.0f - poly * t * __expf(-ax * ax);
;   return copysignf(y, x);
; }
; __device__ __forceinline__ float gelu_exact(float x) { return 0.5f * x * (1.0f + erf_f32(x * 0.70710678118654752f)); }
; template <int EPI>
; __device__ __forceinline__ void phase_gemm(const Params& p, const GemmDesc& d, char* shmc) {
;     ...
; #pragma unroll
;       for (int n = 0; n < 2; ++n) {
;         const int col = ewc * 32 + n * 16 + efr;
;         const int ch = ch0 + col;
;         const float w0 = cw[n][0], w1 = cw[n][1], w2 = cw[n][2], cb = cw[n][3];
; #pragma unroll
;         for (int ai = 0; ai < 2; ++ai)
; #pragma unroll
;           for (int m = 0; m < 4; ++m) {
;             const int s = ai * 32 + ewr * 16 + m * 4 + efq;
;             const f32x4 g = acc[ai][0][m][n];
;             const f32x4 v = acc[ai][1][m][n];
;             const float c0 = w0 * gp[ai][m][n] + w1 * g[0] + w2 * g[1] + cb;
;             const float c1 = w0 * g[0] + w1 * g[1] + w2 * g[2] + cb;
;             const float c2 = w0 * g[1] + w1 * g[2] + w2 * g[3] + cb;
;             const float c3 = w0 * g[2] + w1 * g[3] + w2 * gn[ai][m][n] + cb;
;             u16* sp = stg + (s * 4) * 136 + col;
;             sp[0] = f2bf(gelu_exact(c0) * v[0]);
;             sp[136] = f2bf(gelu_exact(c1) * v[1]);
;             sp[272] = f2bf(gelu_exact(c2) * v[2]);
;             sp[408] = f2bf(gelu_exact(c3) * v[3]);
;             if (s == 0) {
;               edge[0 * DFF + ch] = c0; edge[1 * DFF + ch] = g[0]; edge[2 * DFF + ch] = v[0];
;             }
;             if (s == 63) {
;               edge[3 * DFF + ch] = c3; edge[4 * DFF + ch] = g[3]; edge[5 * DFF + ch] = v[3];
;             }
;           }
	v_mul_f32_e32 v83, 0x3f596d27, v84
	v_fmac_f32_e32 v82, v216, v179
	v_fma_f32 v87, |v83|, s98, 1.0
	v_add_f32_e32 v85, v218, v82
	v_mul_f32_e32 v82, v217, v179
	v_fmac_f32_e32 v82, v215, v178
	v_fmac_f32_e32 v82, v216, v114
	v_add_f32_e32 v86, v218, v82
	v_add_u32_e32 v82, 0x9900, v220
	v_add_u32_e32 v91, v222, v82
	v_cvt_pk_bf16_f32 v76, v76, s0
	ds_write_b16 v91, v76
	v_mul_f32_e32 v76, 0.5, v84
	v_rcp_f32_e32 v84, v87
	v_mul_f32_e64 v88, |v83|, -|v83|
	v_fmamk_f32 v87, v84, 0x3f87dc22, v206
	v_fmaak_f32 v87, v87, v84, 0x3fb5f0e3
	v_exp_f32_e32 v88, v88
	v_fmaak_f32 v87, v87, v84, 0xbe91a98e
	v_fmaak_f32 v87, v87, v84, 0x3e827906
	v_mul_f32_e32 v84, v84, v87
	v_fma_f32 v83, -v88, v84, 1.0
	v_fma_f32 v76, |v76|, v83, v76
	v_mul_f32_e32 v76, v77, v76
	v_mul_f32_e32 v77, 0x3f596d27, v85
	v_fma_f32 v83, |v77|, s98, 1.0
	v_cvt_pk_bf16_f32 v76, v76, s0
	ds_write_b16 v91, v76 offset:272
	v_mul_f32_e32 v76, 0.5, v85
	v_rcp_f32_e32 v83, v83
	v_mul_f32_e64 v85, |v77|, -|v77|
	v_fmamk_f32 v84, v83, 0x3f87dc22, v206
	v_fmaak_f32 v84, v84, v83, 0x3fb5f0e3
	v_exp_f32_e32 v85, v85
	v_fmaak_f32 v84, v84, v83, 0xbe91a98e
	v_fmaak_f32 v84, v84, v83, 0x3e827906
	v_mul_f32_e32 v83, v83, v84
	v_fma_f32 v77, -v85, v83, 1.0
	v_fma_f32 v76, |v76|, v77, v76
	v_mul_f32_e32 v74, v74, v76
	v_mul_f32_e32 v76, 0x3f596d27, v86
	v_fma_f32 v77, |v76|, s98, 1.0
	v_cvt_pk_bf16_f32 v74, v74, s0
	ds_write_b16 v91, v74 offset:544
	v_mul_f32_e32 v74, 0.5, v86
	v_rcp_f32_e32 v77, v77
	v_mul_f32_e64 v84, |v76|, -|v76|
	v_fmamk_f32 v83, v77, 0x3f87dc22, v206
	v_fmaak_f32 v83, v83, v77, 0x3fb5f0e3
	v_exp_f32_e32 v84, v84
	v_fmaak_f32 v83, v83, v77, 0xbe91a98e
	v_fmaak_f32 v83, v83, v77, 0x3e827906
	v_mul_f32_e32 v77, v77, v83
	v_fma_f32 v76, -v84, v77, 1.0
	v_fma_f32 v74, |v74|, v76, v74
	v_mul_f32_e32 v74, v75, v74
	v_cvt_pk_bf16_f32 v74, v74, s0
	ds_write_b16 v91, v74 offset:816
	v_mul_f32_e32 v74, v215, v108
	v_fmac_f32_e32 v74, v217, v160
	v_fmac_f32_e32 v74, v216, v161
	v_add_f32_e32 v75, v218, v74
	v_mul_f32_e32 v84, 0x3f596d27, v75
	v_fma_f32 v85, |v84|, s98, 1.0
	v_mul_f32_e32 v74, v217, v161
	v_fmac_f32_e32 v74, v215, v160
	v_fmac_f32_e32 v74, v216, v156
	v_rcp_f32_e32 v85, v85
	v_mul_f32_e64 v87, |v84|, -|v84|
	v_fmamk_f32 v86, v85, 0x3f87dc22, v206
	v_fmaak_f32 v86, v86, v85, 0x3fb5f0e3
	v_exp_f32_e32 v87, v87
	v_fmaak_f32 v86, v86, v85, 0xbe91a98e
	v_fmaak_f32 v86, v86, v85, 0x3e827906
	v_mul_f32_e32 v85, v85, v86
	v_fma_f32 v84, -v87, v85, 1.0
	v_mul_f32_e32 v75, 0.5, v75
	v_add_f32_e32 v76, v218, v74
	v_mul_f32_e32 v74, v217, v156
	v_fma_f32 v75, |v75|, v84, v75
	v_fmac_f32_e32 v74, v215, v161
	v_mul_f32_e32 v72, v72, v75
	v_mul_f32_e32 v75, 0x3f596d27, v76
	v_fmac_f32_e32 v74, v216, v157
	v_fma_f32 v84, |v75|, s98, 1.0
	v_add_f32_e32 v77, v218, v74
	v_mul_f32_e32 v74, v217, v157
	v_fmac_f32_e32 v74, v215, v156
	v_fmac_f32_e32 v74, v216, v106
	v_add_f32_e32 v83, v218, v74
	v_add_u32_e32 v74, 0xaa00, v220
	v_add_u32_e32 v88, v222, v74
	v_cvt_pk_bf16_f32 v72, v72, s0
	ds_write_b16 v88, v72
	v_mul_f32_e32 v72, 0.5, v76
	v_rcp_f32_e32 v76, v84
	v_mul_f32_e64 v85, |v75|, -|v75|
	v_fmamk_f32 v84, v76, 0x3f87dc22, v206
	v_fmaak_f32 v84, v84, v76, 0x3fb5f0e3
	v_exp_f32_e32 v85, v85
	v_fmaak_f32 v84, v84, v76, 0xbe91a98e
	v_fmaak_f32 v84, v84, v76, 0x3e827906
	v_mul_f32_e32 v76, v76, v84
	v_fma_f32 v75, -v85, v76, 1.0
	v_fma_f32 v72, |v72|, v75, v72
	v_mul_f32_e32 v72, v73, v72
	v_mul_f32_e32 v73, 0x3f596d27, v77
	v_fma_f32 v75, |v73|, s98, 1.0
	v_cvt_pk_bf16_f32 v72, v72, s0
	ds_write_b16 v88, v72 offset:272
	v_mul_f32_e32 v72, 0.5, v77
	v_rcp_f32_e32 v75, v75
	v_mul_f32_e64 v77, |v73|, -|v73|
	v_fmamk_f32 v76, v75, 0x3f87dc22, v206
	v_fmaak_f32 v76, v76, v75, 0x3fb5f0e3
	v_exp_f32_e32 v77, v77
	v_fmaak_f32 v76, v76, v75, 0xbe91a98e
	v_fmaak_f32 v76, v76, v75, 0x3e827906
	v_mul_f32_e32 v75, v75, v76
	v_fma_f32 v73, -v77, v75, 1.0
	v_fma_f32 v72, |v72|, v73, v72
	v_mul_f32_e32 v70, v70, v72
	v_mul_f32_e32 v72, 0x3f596d27, v83
	v_fma_f32 v73, |v72|, s98, 1.0
	v_cvt_pk_bf16_f32 v70, v70, s0
	ds_write_b16 v88, v70 offset:544
	v_mul_f32_e32 v70, 0.5, v83
	v_rcp_f32_e32 v73, v73
	v_mul_f32_e64 v76, |v72|, -|v72|
	v_fmamk_f32 v75, v73, 0x3f87dc22, v206
	v_fmaak_f32 v75, v75, v73, 0x3fb5f0e3
	v_exp_f32_e32 v76, v76
	v_fmaak_f32 v75, v75, v73, 0xbe91a98e
	v_fmaak_f32 v75, v75, v73, 0x3e827906
	v_mul_f32_e32 v73, v73, v75
	v_fma_f32 v72, -v76, v73, 1.0
	v_fma_f32 v70, |v70|, v72, v70
	v_mul_f32_e32 v70, v71, v70
	v_cvt_pk_bf16_f32 v70, v70, s0
	ds_write_b16 v88, v70 offset:816
	s_waitcnt lgkmcnt(14)
; __device__ __forceinline__ u16 f2bf(float f) { return (u16)(pack2(f, f) & 0xffffu); }
; __device__ __forceinline__ float erf_f32(float x) {
;   const float ax = fabsf(x);
;   const float t = __frcp_rn(fmaf(0.3275911f, ax, 1.0f));
;   float poly = fmaf(1.061405429f, t, -1.453152027f);
;   poly = fmaf(poly, t, 1.421413741f);
;   poly = fmaf(poly, t, -0.284496736f);
;   poly = fmaf(poly, t, 0.254829592f);
;   const float y = 1.0f - poly * t * __expf(-ax * ax);
;   return copysignf(y, x);
; }
; __device__ __forceinline__ float gelu_exact(float x) { return 0.5f * x * (1.0f + erf_f32(x * 0.70710678118654752f)); }
; template <int EPI>
; __device__ __forceinline__ void phase_gemm(const Params& p, const GemmDesc& d, char* shmc) {
;     ...
; #pragma unroll
;       for (int n = 0; n < 2; ++n) {
;         const int col = ewc * 32 + n * 16 + efr;
;         const int ch = ch0 + col;
;         const float w0 = cw[n][0], w1 = cw[n][1], w2 = cw[n][2], cb = cw[n][3];
; #pragma unroll
;         for (int ai = 0; ai < 2; ++ai)
; #pragma unroll
;           for (int m = 0; m < 4; ++m) {
;             const int s = ai * 32 + ewr * 16 + m * 4 + efq;
;             const f32x4 g = acc[ai][0][m][n];
;             const f32x4 v = acc[ai][1][m][n];
;             const float c0 = w0 * gp[ai][m][n] + w1 * g[0] + w2 * g[1] + cb;
;             const float c1 = w0 * g[0] + w1 * g[1] + w2 * g[2] + cb;
;             const float c2 = w0 * g[1] + w1 * g[2] + w2 * g[3] + cb;
;             const float c3 = w0 * g[2] + w1 * g[3] + w2 * gn[ai][m][n] + cb;
;             u16* sp = stg + (s * 4) * 136 + col;
;             sp[0] = f2bf(gelu_exact(c0) * v[0]);
;             sp[136] = f2bf(gelu_exact(c1) * v[1]);
;             sp[272] = f2bf(gelu_exact(c2) * v[2]);
;             sp[408] = f2bf(gelu_exact(c3) * v[3]);
;             if (s == 0) {
;               edge[0 * DFF + ch] = c0; edge[1 * DFF + ch] = g[0]; edge[2 * DFF + ch] = v[0];
;             }
;             if (s == 63) {
;               edge[3 * DFF + ch] = c3; edge[4 * DFF + ch] = g[3]; edge[5 * DFF + ch] = v[3];
;             }
;           }
	v_mul_f32_e32 v70, v215, v221
	v_fmac_f32_e32 v70, v217, v154
	v_fmac_f32_e32 v70, v216, v155
	v_add_f32_e32 v72, v218, v70
	v_mul_f32_e32 v76, 0x3f596d27, v72
	v_fma_f32 v77, |v76|, s98, 1.0
	v_mul_f32_e32 v70, v217, v155
	v_fmac_f32_e32 v70, v215, v154
	v_fmac_f32_e32 v70, v216, v152
	v_rcp_f32_e32 v77, v77
	v_mul_f32_e64 v84, |v76|, -|v76|
	v_fmamk_f32 v83, v77, 0x3f87dc22, v206
	v_fmaak_f32 v83, v83, v77, 0x3fb5f0e3
	v_exp_f32_e32 v84, v84
	v_fmaak_f32 v83, v83, v77, 0xbe91a98e
	v_fmaak_f32 v83, v83, v77, 0x3e827906
	v_mul_f32_e32 v77, v77, v83
	v_fma_f32 v76, -v84, v77, 1.0
	v_mul_f32_e32 v72, 0.5, v72
	v_add_f32_e32 v73, v218, v70
	v_mul_f32_e32 v70, v217, v152
	v_fma_f32 v72, |v72|, v76, v72
	v_fmac_f32_e32 v70, v215, v155
	v_mul_f32_e32 v68, v68, v72
	v_mul_f32_e32 v72, 0x3f596d27, v73
	v_fmac_f32_e32 v70, v216, v153
	v_fma_f32 v76, |v72|, s98, 1.0
	v_add_f32_e32 v75, v218, v70
	v_mul_f32_e32 v70, v217, v153
	v_fmac_f32_e32 v70, v215, v152
	v_fmac_f32_e32 v70, v216, v219
	v_add_f32_e32 v71, v218, v70
	v_add_u32_e32 v70, 0xbb00, v220
	v_add_u32_e32 v85, v222, v70
	v_cvt_pk_bf16_f32 v68, v68, s0
	ds_write_b16 v85, v68
	v_mul_f32_e32 v68, 0.5, v73
	v_rcp_f32_e32 v73, v76
	v_mul_f32_e64 v77, |v72|, -|v72|
	v_fmamk_f32 v76, v73, 0x3f87dc22, v206
	v_fmaak_f32 v76, v76, v73, 0x3fb5f0e3
	v_exp_f32_e32 v77, v77
	v_fmaak_f32 v76, v76, v73, 0xbe91a98e
	v_fmaak_f32 v76, v76, v73, 0x3e827906
	v_mul_f32_e32 v73, v73, v76
	v_fma_f32 v72, -v77, v73, 1.0
	v_fma_f32 v68, |v68|, v72, v68
	v_mul_f32_e32 v68, v69, v68
	v_mul_f32_e32 v69, 0x3f596d27, v75
	v_fma_f32 v72, |v69|, s98, 1.0
	v_cvt_pk_bf16_f32 v68, v68, s0
	ds_write_b16 v85, v68 offset:272
	v_mul_f32_e32 v68, 0.5, v75
	v_rcp_f32_e32 v72, v72
	v_mul_f32_e64 v75, |v69|, -|v69|
	v_fmamk_f32 v73, v72, 0x3f87dc22, v206
	v_fmaak_f32 v73, v73, v72, 0x3fb5f0e3
	v_exp_f32_e32 v75, v75
	v_fmaak_f32 v73, v73, v72, 0xbe91a98e
	v_fmaak_f32 v73, v73, v72, 0x3e827906
	v_mul_f32_e32 v72, v72, v73
	v_fma_f32 v69, -v75, v72, 1.0
	v_fma_f32 v68, |v68|, v69, v68
	v_mul_f32_e32 v66, v66, v68
	v_mul_f32_e32 v68, 0x3f596d27, v71
	v_fma_f32 v69, |v68|, s98, 1.0
	v_cvt_pk_bf16_f32 v66, v66, s0
	ds_write_b16 v85, v66 offset:544
	v_mul_f32_e32 v66, 0.5, v71
	v_rcp_f32_e32 v69, v69
	v_mul_f32_e64 v73, |v68|, -|v68|
	v_fmamk_f32 v72, v69, 0x3f87dc22, v206
	v_fmaak_f32 v72, v72, v69, 0x3fb5f0e3
	v_exp_f32_e32 v73, v73
	v_fmaak_f32 v72, v72, v69, 0xbe91a98e
	v_fmaak_f32 v72, v72, v69, 0x3e827906
	v_mul_f32_e32 v69, v69, v72
	v_fma_f32 v68, -v73, v69, 1.0
	v_fma_f32 v66, |v66|, v68, v66
	v_mul_f32_e32 v66, v67, v66
	v_cvt_pk_bf16_f32 v66, v66, s0
	ds_write_b16 v85, v66 offset:816
	s_and_saveexec_b64 s[58:59], s[8:9]
	s_cbranch_execz .LBB0_1168
	v_add_co_u32_e32 v68, vcc, 0x10000, v94
	s_nop 1
	v_addc_co_u32_e32 v69, vcc, 0, v95, vcc
	global_store_dword v[68:69], v71, off offset:2048
	v_add_co_u32_e32 v68, vcc, 0x16000, v94
	s_nop 1
	v_addc_co_u32_e32 v69, vcc, 0, v95, vcc
	global_store_dword v[68:69], v153, off
	v_add_co_u32_e32 v68, vcc, 0x1b000, v94
	s_nop 1
	v_addc_co_u32_e32 v69, vcc, 0, v95, vcc
	global_store_dword v[68:69], v67, off offset:2048
.LBB0_1168:
	s_or_b64 exec, exec, s[58:59]
	v_pk_mul_f32 v[64:65], v[60:61], v[64:65]
	v_pk_mul_f32 v[60:61], v[58:59], v[62:63]
	v_mul_f32_e32 v62, v208, v213
	v_fmac_f32_e32 v62, v210, v146
	v_fmac_f32_e32 v62, v209, v147
	v_add_f32_e32 v63, v207, v62
	v_mul_f32_e32 v71, 0x3f596d27, v63
	v_fma_f32 v72, |v71|, s98, 1.0
	v_mul_f32_e32 v62, v210, v147
	v_fmac_f32_e32 v62, v208, v146
	v_fmac_f32_e32 v62, v209, v158
	v_rcp_f32_e32 v72, v72
	v_mul_f32_e64 v75, |v71|, -|v71|
	v_fmamk_f32 v73, v72, 0x3f87dc22, v206
	v_fmaak_f32 v73, v73, v72, 0x3fb5f0e3
	v_exp_f32_e32 v75, v75
	v_fmaak_f32 v73, v73, v72, 0xbe91a98e
	v_fmaak_f32 v73, v73, v72, 0x3e827906
	v_mul_f32_e32 v72, v72, v73
	v_add_f32_e32 v67, v207, v62
	v_mul_f32_e32 v62, v210, v158
	v_fma_f32 v71, -v75, v72, 1.0
	v_fmac_f32_e32 v62, v208, v147
	v_mul_f32_e32 v72, 0x3f596d27, v67
	v_fmac_f32_e32 v62, v209, v159
	v_fma_f32 v73, |v72|, s98, 1.0
	v_add_f32_e32 v68, v207, v62
	v_mul_f32_e32 v62, v210, v159
	v_mul_f32_e32 v76, 0.5, v63
	v_fmac_f32_e32 v62, v208, v158
	v_fma_f32 v71, |v76|, v71, v76
	v_or_b32_e32 v66, 16, v162
	v_fmac_f32_e32 v62, v209, v214
	v_add_f32_e32 v69, v207, v62
	v_lshlrev_b32_e32 v62, 1, v66
	v_mul_f32_e32 v71, v60, v71
	v_add3_u32 v66, s14, v220, v62
	v_cvt_pk_bf16_f32 v71, v71, s0
	ds_write_b16 v66, v71
	v_rcp_f32_e32 v71, v73
	v_mul_f32_e64 v75, |v72|, -|v72|
	v_fmamk_f32 v73, v71, 0x3f87dc22, v206
	v_fmaak_f32 v73, v73, v71, 0x3fb5f0e3
	v_exp_f32_e32 v75, v75
	v_fmaak_f32 v73, v73, v71, 0xbe91a98e
	v_fmaak_f32 v73, v73, v71, 0x3e827906
	v_mul_f32_e32 v71, v71, v73
	v_fma_f32 v71, -v75, v71, 1.0
	v_mul_f32_e32 v67, 0.5, v67
	v_fma_f32 v67, |v67|, v71, v67
	v_mul_f32_e32 v61, v61, v67
	v_mul_f32_e32 v67, 0x3f596d27, v68
	v_fma_f32 v71, |v67|, s98, 1.0
	v_cvt_pk_bf16_f32 v61, v61, s0
	ds_write_b16 v66, v61 offset:272
	v_mul_f32_e32 v61, 0.5, v68
	v_rcp_f32_e32 v68, v71
	v_mul_f32_e64 v72, |v67|, -|v67|
	v_fmamk_f32 v71, v68, 0x3f87dc22, v206
	v_fmaak_f32 v71, v71, v68, 0x3fb5f0e3
	v_exp_f32_e32 v72, v72
	v_fmaak_f32 v71, v71, v68, 0xbe91a98e
	v_fmaak_f32 v71, v71, v68, 0x3e827906
	v_mul_f32_e32 v68, v68, v71
	v_fma_f32 v67, -v72, v68, 1.0
	v_fma_f32 v61, |v61|, v67, v61
	v_mul_f32_e32 v61, v64, v61
	v_mul_f32_e32 v64, 0x3f596d27, v69
	v_fma_f32 v67, |v64|, s98, 1.0
	v_cvt_pk_bf16_f32 v61, v61, s0
	ds_write_b16 v66, v61 offset:544
	v_mul_f32_e32 v61, 0.5, v69
	v_rcp_f32_e32 v67, v67
	v_mul_f32_e64 v69, |v64|, -|v64|
	v_fmamk_f32 v68, v67, 0x3f87dc22, v206
	v_fmaak_f32 v68, v68, v67, 0x3fb5f0e3
	v_exp_f32_e32 v69, v69
	v_fmaak_f32 v68, v68, v67, 0xbe91a98e
	v_fmaak_f32 v68, v68, v67, 0x3e827906
	v_mul_f32_e32 v67, v67, v68
	v_fma_f32 v64, -v69, v67, 1.0
	s_ashr_i32 s55, s54, 31
	v_lshl_add_u64 v[58:59], v[162:163], 0, s[54:55]
	v_fma_f32 v61, |v61|, v64, v61
	v_lshl_add_u64 v[58:59], v[58:59], 2, s[56:57]
	v_mul_f32_e32 v61, v65, v61
	v_lshl_add_u64 v[58:59], v[58:59], 0, 64
	v_cvt_pk_bf16_f32 v61, v61, s0
	ds_write_b16 v66, v61 offset:816
	s_and_saveexec_b64 s[56:57], s[10:11]
	s_cbranch_execz .LBB0_1170
	v_add_co_u32_e32 v64, vcc, 0x5000, v58
	global_store_dword v[58:59], v63, off
	s_nop 0
	v_addc_co_u32_e32 v65, vcc, 0, v59, vcc
	global_store_dword v[64:65], v146, off offset:2048
	v_add_co_u32_e32 v64, vcc, 0xb000, v58
	s_nop 1
	v_addc_co_u32_e32 v65, vcc, 0, v59, vcc
	global_store_dword v[64:65], v60, off
; __device__ __forceinline__ u16 f2bf(float f) { return (u16)(pack2(f, f) & 0xffffu); }
; __device__ __forceinline__ float erf_f32(float x) {
;   const float ax = fabsf(x);
;   const float t = __frcp_rn(fmaf(0.3275911f, ax, 1.0f));
;   float poly = fmaf(1.061405429f, t, -1.453152027f);
;   poly = fmaf(poly, t, 1.421413741f);
;   poly = fmaf(poly, t, -0.284496736f);
;   poly = fmaf(poly, t, 0.254829592f);
;   const float y = 1.0f - poly * t * __expf(-ax * ax);
;   return copysignf(y, x);
; }
; __device__ __forceinline__ float gelu_exact(float x) { return 0.5f * x * (1.0f + erf_f32(x * 0.70710678118654752f)); }
; template <int EPI>
; __device__ __forceinline__ void phase_gemm(const Params& p, const GemmDesc& d, char* shmc) {
;     ...
; #pragma unroll
;       for (int n = 0; n < 2; ++n) {
;         const int col = ewc * 32 + n * 16 + efr;
;         const int ch = ch0 + col;
;         const float w0 = cw[n][0], w1 = cw[n][1], w2 = cw[n][2], cb = cw[n][3];
; #pragma unroll
;         for (int ai = 0; ai < 2; ++ai)
; #pragma unroll
;           for (int m = 0; m < 4; ++m) {
;             const int s = ai * 32 + ewr * 16 + m * 4 + efq;
;             const f32x4 g = acc[ai][0][m][n];
;             const f32x4 v = acc[ai][1][m][n];
;             const float c0 = w0 * gp[ai][m][n] + w1 * g[0] + w2 * g[1] + cb;
;             const float c1 = w0 * g[0] + w1 * g[1] + w2 * g[2] + cb;
;             const float c2 = w0 * g[1] + w1 * g[2] + w2 * g[3] + cb;
;             const float c3 = w0 * g[2] + w1 * g[3] + w2 * gn[ai][m][n] + cb;
;             u16* sp = stg + (s * 4) * 136 + col;
;             sp[0] = f2bf(gelu_exact(c0) * v[0]);
;             sp[136] = f2bf(gelu_exact(c1) * v[1]);
;             sp[272] = f2bf(gelu_exact(c2) * v[2]);
;             sp[408] = f2bf(gelu_exact(c3) * v[3]);
;             if (s == 0) {
;               edge[0 * DFF + ch] = c0; edge[1 * DFF + ch] = g[0]; edge[2 * DFF + ch] = v[0];
;             }
;             if (s == 63) {
;               edge[3 * DFF + ch] = c3; edge[4 * DFF + ch] = g[3]; edge[5 * DFF + ch] = v[3];
;             }
;           }
.LBB0_1170:
	s_or_b64 exec, exec, s[56:57]
	v_pk_mul_f32 v[48:49], v[4:5], v[48:49]
	v_pk_mul_f32 v[4:5], v[14:15], v[30:31]
	v_mul_f32_e32 v14, v208, v151
	v_fmac_f32_e32 v14, v210, v144
	v_fmac_f32_e32 v14, v209, v145
	v_add_f32_e32 v14, v207, v14
	v_pk_mul_f32 v[52:53], v[8:9], v[52:53]
	v_pk_mul_f32 v[8:9], v[18:19], v[34:35]
	v_mul_f32_e32 v18, 0x3f596d27, v14
	v_fma_f32 v19, |v18|, s98, 1.0
	v_pk_mul_f32 v[50:51], v[6:7], v[50:51]
	v_pk_mul_f32 v[6:7], v[20:21], v[36:37]
	v_pk_mul_f32 v[56:57], v[12:13], v[56:57]
	v_pk_mul_f32 v[12:13], v[22:23], v[38:39]
	v_pk_mul_f32 v[54:55], v[10:11], v[54:55]
	v_pk_mul_f32 v[10:11], v[24:25], v[40:41]
	v_rcp_f32_e32 v19, v19
	v_mul_f32_e64 v21, |v18|, -|v18|
	v_fmamk_f32 v20, v19, 0x3f87dc22, v206
	v_fmaak_f32 v20, v20, v19, 0x3fb5f0e3
	v_exp_f32_e32 v21, v21
	v_fmaak_f32 v20, v20, v19, 0xbe91a98e
	v_fmaak_f32 v20, v20, v19, 0x3e827906
	v_mul_f32_e32 v15, v210, v145
	v_mul_f32_e32 v19, v19, v20
	v_fmac_f32_e32 v15, v208, v144
	v_fma_f32 v18, -v21, v19, 1.0
	v_fmac_f32_e32 v15, v209, v142
	v_add_f32_e32 v15, v207, v15
	v_mul_f32_e32 v14, 0.5, v14
	v_fma_f32 v14, |v14|, v18, v14
	v_mul_f32_e32 v18, 0x3f596d27, v15
	v_fma_f32 v19, |v18|, s98, 1.0
	v_mul_f32_e32 v14, v54, v14
	v_add3_u32 v22, s14, v78, v62
	v_cvt_pk_bf16_f32 v14, v14, s0
	ds_write_b16 v22, v14
	v_mul_f32_e32 v14, 0.5, v15
	v_rcp_f32_e32 v15, v19
	v_mul_f32_e64 v20, |v18|, -|v18|
	v_fmamk_f32 v19, v15, 0x3f87dc22, v206
	v_fmaak_f32 v19, v19, v15, 0x3fb5f0e3
	v_exp_f32_e32 v20, v20
	v_fmaak_f32 v19, v19, v15, 0xbe91a98e
	v_fmaak_f32 v19, v19, v15, 0x3e827906
	v_pk_mul_f32 v[46:47], v[2:3], v[46:47]
	v_pk_mul_f32 v[2:3], v[16:17], v[32:33]
	v_mul_f32_e32 v16, v210, v142
	v_mul_f32_e32 v15, v15, v19
	v_fmac_f32_e32 v16, v208, v145
	v_fma_f32 v15, -v20, v15, 1.0
	v_fmac_f32_e32 v16, v209, v143
	v_add_f32_e32 v16, v207, v16
	v_fma_f32 v14, |v14|, v15, v14
	v_mul_f32_e32 v15, 0x3f596d27, v16
	v_fma_f32 v18, |v15|, s98, 1.0
	v_mul_f32_e32 v14, v55, v14
	v_cvt_pk_bf16_f32 v14, v14, s0
	ds_write_b16 v22, v14 offset:272
	v_mul_f32_e32 v14, 0.5, v16
	v_rcp_f32_e32 v16, v18
	v_mul_f32_e64 v19, |v15|, -|v15|
	v_fmamk_f32 v18, v16, 0x3f87dc22, v206
	v_fmaak_f32 v18, v18, v16, 0x3fb5f0e3
	v_exp_f32_e32 v19, v19
	v_fmaak_f32 v18, v18, v16, 0xbe91a98e
	v_fmaak_f32 v18, v18, v16, 0x3e827906
	v_mul_f32_e32 v17, v210, v143
	v_mul_f32_e32 v16, v16, v18
	v_fmac_f32_e32 v17, v208, v142
	v_fma_f32 v15, -v19, v16, 1.0
	v_fmac_f32_e32 v17, v209, v149
	v_add_f32_e32 v17, v207, v17
	v_fma_f32 v14, |v14|, v15, v14
	v_mul_f32_e32 v15, 0x3f596d27, v17
	v_fma_f32 v16, |v15|, s98, 1.0
	v_mul_f32_e32 v14, v56, v14
	v_cvt_pk_bf16_f32 v14, v14, s0
	ds_write_b16 v22, v14 offset:544
	v_mul_f32_e32 v14, 0.5, v17
	v_rcp_f32_e32 v16, v16
	v_mul_f32_e64 v18, |v15|, -|v15|
	v_fmamk_f32 v17, v16, 0x3f87dc22, v206
	v_fmaak_f32 v17, v17, v16, 0x3fb5f0e3
	v_exp_f32_e32 v18, v18
	v_fmaak_f32 v17, v17, v16, 0xbe91a98e
	v_fmaak_f32 v17, v17, v16, 0x3e827906
	v_mul_f32_e32 v16, v16, v17
	v_fma_f32 v15, -v18, v16, 1.0
	v_fma_f32 v14, |v14|, v15, v14
	v_mul_f32_e32 v14, v57, v14
	v_cvt_pk_bf16_f32 v14, v14, s0
	ds_write_b16 v22, v14 offset:816
	v_mul_f32_e32 v14, v208, v141
	v_fmac_f32_e32 v14, v210, v136
	v_fmac_f32_e32 v14, v209, v137
	v_add_f32_e32 v14, v207, v14
	v_mul_f32_e32 v18, 0x3f596d27, v14
	v_fma_f32 v19, |v18|, s98, 1.0
	v_mul_f32_e32 v15, v210, v137
	v_fmac_f32_e32 v15, v208, v136
	v_fmac_f32_e32 v15, v209, v134
	v_rcp_f32_e32 v19, v19
	v_mul_f32_e64 v21, |v18|, -|v18|
	v_fmamk_f32 v20, v19, 0x3f87dc22, v206
	v_fmaak_f32 v20, v20, v19, 0x3fb5f0e3
	v_exp_f32_e32 v21, v21
	v_fmaak_f32 v20, v20, v19, 0xbe91a98e
	v_fmaak_f32 v20, v20, v19, 0x3e827906
	v_mul_f32_e32 v19, v19, v20
	v_fma_f32 v18, -v21, v19, 1.0
	v_add_f32_e32 v15, v207, v15
	v_mul_f32_e32 v14, 0.5, v14
	v_fma_f32 v14, |v14|, v18, v14
	v_mul_f32_e32 v18, 0x3f596d27, v15
	v_fma_f32 v19, |v18|, s98, 1.0
	v_mul_f32_e32 v14, v50, v14
	v_add3_u32 v22, s14, v79, v62
	v_cvt_pk_bf16_f32 v14, v14, s0
	ds_write_b16 v22, v14
	v_mul_f32_e32 v14, 0.5, v15
	v_rcp_f32_e32 v15, v19
	v_mul_f32_e64 v20, |v18|, -|v18|
	v_fmamk_f32 v19, v15, 0x3f87dc22, v206
	v_fmaak_f32 v19, v19, v15, 0x3fb5f0e3
	v_exp_f32_e32 v20, v20
	v_fmaak_f32 v19, v19, v15, 0xbe91a98e
	v_fmaak_f32 v19, v19, v15, 0x3e827906
	v_mul_f32_e32 v16, v210, v134
	v_mul_f32_e32 v15, v15, v19
	v_fmac_f32_e32 v16, v208, v137
	v_fma_f32 v15, -v20, v15, 1.0
	v_fmac_f32_e32 v16, v209, v135
	v_add_f32_e32 v16, v207, v16
	v_fma_f32 v14, |v14|, v15, v14
	v_mul_f32_e32 v15, 0x3f596d27, v16
	v_fma_f32 v18, |v15|, s98, 1.0
	v_mul_f32_e32 v14, v51, v14
	v_cvt_pk_bf16_f32 v14, v14, s0
	ds_write_b16 v22, v14 offset:272
	v_mul_f32_e32 v14, 0.5, v16
	v_rcp_f32_e32 v16, v18
	v_mul_f32_e64 v19, |v15|, -|v15|
	v_fmamk_f32 v18, v16, 0x3f87dc22, v206
	v_fmaak_f32 v18, v18, v16, 0x3fb5f0e3
	v_exp_f32_e32 v19, v19
	v_fmaak_f32 v18, v18, v16, 0xbe91a98e
	v_fmaak_f32 v18, v18, v16, 0x3e827906
	v_mul_f32_e32 v17, v210, v135
	v_mul_f32_e32 v16, v16, v18
	v_fmac_f32_e32 v17, v208, v134
	v_fma_f32 v15, -v19, v16, 1.0
	v_fmac_f32_e32 v17, v209, v139
	v_add_f32_e32 v17, v207, v17
	v_fma_f32 v14, |v14|, v15, v14
	v_mul_f32_e32 v15, 0x3f596d27, v17
	v_fma_f32 v16, |v15|, s98, 1.0
	v_mul_f32_e32 v14, v52, v14
	v_cvt_pk_bf16_f32 v14, v14, s0
	ds_write_b16 v22, v14 offset:544
	v_mul_f32_e32 v14, 0.5, v17
	v_rcp_f32_e32 v16, v16
	v_mul_f32_e64 v18, |v15|, -|v15|
	v_fmamk_f32 v17, v16, 0x3f87dc22, v206
	v_fmaak_f32 v17, v17, v16, 0x3fb5f0e3
	v_exp_f32_e32 v18, v18
	v_fmaak_f32 v17, v17, v16, 0xbe91a98e
	v_fmaak_f32 v17, v17, v16, 0x3e827906
	v_mul_f32_e32 v16, v16, v17
	v_fma_f32 v15, -v18, v16, 1.0
; __device__ __forceinline__ u16 f2bf(float f) { return (u16)(pack2(f, f) & 0xffffu); }
; __device__ __forceinline__ float erf_f32(float x) {
;   const float ax = fabsf(x);
;   const float t = __frcp_rn(fmaf(0.3275911f, ax, 1.0f));
;   float poly = fmaf(1.061405429f, t, -1.453152027f);
;   poly = fmaf(poly, t, 1.421413741f);
;   poly = fmaf(poly, t, -0.284496736f);
;   poly = fmaf(poly, t, 0.254829592f);
;   const float y = 1.0f - poly * t * __expf(-ax * ax);
;   return copysignf(y, x);
; }
; __device__ __forceinline__ float gelu_exact(float x) { return 0.5f * x * (1.0f + erf_f32(x * 0.70710678118654752f)); }
; template <int EPI>
; __device__ __forceinline__ void phase_gemm(const Params& p, const GemmDesc& d, char* shmc) {
;     ...
; #pragma unroll
;       for (int n = 0; n < 2; ++n) {
;         const int col = ewc * 32 + n * 16 + efr;
;         const int ch = ch0 + col;
;         const float w0 = cw[n][0], w1 = cw[n][1], w2 = cw[n][2], cb = cw[n][3];
; #pragma unroll
;         for (int ai = 0; ai < 2; ++ai)
; #pragma unroll
;           for (int m = 0; m < 4; ++m) {
;             const int s = ai * 32 + ewr * 16 + m * 4 + efq;
;             const f32x4 g = acc[ai][0][m][n];
;             const f32x4 v = acc[ai][1][m][n];
;             const float c0 = w0 * gp[ai][m][n] + w1 * g[0] + w2 * g[1] + cb;
;             const float c1 = w0 * g[0] + w1 * g[1] + w2 * g[2] + cb;
;             const float c2 = w0 * g[1] + w1 * g[2] + w2 * g[3] + cb;
;             const float c3 = w0 * g[2] + w1 * g[3] + w2 * gn[ai][m][n] + cb;
;             u16* sp = stg + (s * 4) * 136 + col;
;             sp[0] = f2bf(gelu_exact(c0) * v[0]);
;             sp[136] = f2bf(gelu_exact(c1) * v[1]);
;             sp[272] = f2bf(gelu_exact(c2) * v[2]);
;             sp[408] = f2bf(gelu_exact(c3) * v[3]);
;             if (s == 0) {
;               edge[0 * DFF + ch] = c0; edge[1 * DFF + ch] = g[0]; edge[2 * DFF + ch] = v[0];
;             }
;             if (s == 63) {
;               edge[3 * DFF + ch] = c3; edge[4 * DFF + ch] = g[3]; edge[5 * DFF + ch] = v[3];
;             }
;           }
	v_fma_f32 v14, |v14|, v15, v14
	v_mul_f32_e32 v14, v53, v14
	v_cvt_pk_bf16_f32 v14, v14, s0
	ds_write_b16 v22, v14 offset:816
	v_mul_f32_e32 v14, v208, v133
	v_fmac_f32_e32 v14, v210, v128
	v_fmac_f32_e32 v14, v209, v129
	v_add_f32_e32 v14, v207, v14
	v_mul_f32_e32 v18, 0x3f596d27, v14
	v_fma_f32 v19, |v18|, s98, 1.0
	v_mul_f32_e32 v15, v210, v129
	v_fmac_f32_e32 v15, v208, v128
	v_fmac_f32_e32 v15, v209, v126
	v_rcp_f32_e32 v19, v19
	v_mul_f32_e64 v21, |v18|, -|v18|
	v_fmamk_f32 v20, v19, 0x3f87dc22, v206
	v_fmaak_f32 v20, v20, v19, 0x3fb5f0e3
	v_exp_f32_e32 v21, v21
	v_fmaak_f32 v20, v20, v19, 0xbe91a98e
	v_fmaak_f32 v20, v20, v19, 0x3e827906
	v_mul_f32_e32 v19, v19, v20
	v_fma_f32 v18, -v21, v19, 1.0
	v_add_f32_e32 v15, v207, v15
	v_mul_f32_e32 v14, 0.5, v14
	v_fma_f32 v14, |v14|, v18, v14
	v_mul_f32_e32 v18, 0x3f596d27, v15
	v_fma_f32 v19, |v18|, s98, 1.0
	v_mul_f32_e32 v14, v46, v14
	v_add3_u32 v22, s14, v80, v62
	v_cvt_pk_bf16_f32 v14, v14, s0
	ds_write_b16 v22, v14
	v_mul_f32_e32 v14, 0.5, v15
	v_rcp_f32_e32 v15, v19
	v_mul_f32_e64 v20, |v18|, -|v18|
	v_fmamk_f32 v19, v15, 0x3f87dc22, v206
	v_fmaak_f32 v19, v19, v15, 0x3fb5f0e3
	v_exp_f32_e32 v20, v20
	v_fmaak_f32 v19, v19, v15, 0xbe91a98e
	v_fmaak_f32 v19, v19, v15, 0x3e827906
	v_mul_f32_e32 v16, v210, v126
	v_mul_f32_e32 v15, v15, v19
	v_fmac_f32_e32 v16, v208, v129
	v_fma_f32 v15, -v20, v15, 1.0
	v_fmac_f32_e32 v16, v209, v127
	v_add_f32_e32 v16, v207, v16
	v_fma_f32 v14, |v14|, v15, v14
	v_mul_f32_e32 v15, 0x3f596d27, v16
	v_fma_f32 v18, |v15|, s98, 1.0
	v_mul_f32_e32 v14, v47, v14
	v_cvt_pk_bf16_f32 v14, v14, s0
	ds_write_b16 v22, v14 offset:272
	v_mul_f32_e32 v14, 0.5, v16
	v_rcp_f32_e32 v16, v18
	v_mul_f32_e64 v19, |v15|, -|v15|
	v_fmamk_f32 v18, v16, 0x3f87dc22, v206
	v_fmaak_f32 v18, v18, v16, 0x3fb5f0e3
	v_exp_f32_e32 v19, v19
	v_fmaak_f32 v18, v18, v16, 0xbe91a98e
	v_fmaak_f32 v18, v18, v16, 0x3e827906
	v_mul_f32_e32 v17, v210, v127
	v_mul_f32_e32 v16, v16, v18
	v_fmac_f32_e32 v17, v208, v126
	v_fma_f32 v15, -v19, v16, 1.0
	v_fmac_f32_e32 v17, v209, v131
	v_add_f32_e32 v17, v207, v17
	v_fma_f32 v14, |v14|, v15, v14
	v_mul_f32_e32 v15, 0x3f596d27, v17
	v_fma_f32 v16, |v15|, s98, 1.0
	v_mul_f32_e32 v14, v48, v14
	v_cvt_pk_bf16_f32 v14, v14, s0
	ds_write_b16 v22, v14 offset:544
	v_mul_f32_e32 v14, 0.5, v17
	v_rcp_f32_e32 v16, v16
	v_mul_f32_e64 v18, |v15|, -|v15|
	v_fmamk_f32 v17, v16, 0x3f87dc22, v206
	v_fmaak_f32 v17, v17, v16, 0x3fb5f0e3
	v_exp_f32_e32 v18, v18
	v_fmaak_f32 v17, v17, v16, 0xbe91a98e
	v_fmaak_f32 v17, v17, v16, 0x3e827906
	v_mul_f32_e32 v16, v16, v17
	v_fma_f32 v15, -v18, v16, 1.0
	v_fma_f32 v14, |v14|, v15, v14
	v_mul_f32_e32 v14, v49, v14
	v_cvt_pk_bf16_f32 v14, v14, s0
	ds_write_b16 v22, v14 offset:816
	v_mul_f32_e32 v14, v208, v125
	v_fmac_f32_e32 v14, v210, v120
	v_fmac_f32_e32 v14, v209, v121
	v_add_f32_e32 v14, v207, v14
	v_mul_f32_e32 v18, 0x3f596d27, v14
	v_fma_f32 v19, |v18|, s98, 1.0
	v_mul_f32_e32 v15, v210, v121
	v_fmac_f32_e32 v15, v208, v120
	v_fmac_f32_e32 v15, v209, v118
	v_rcp_f32_e32 v19, v19
	v_mul_f32_e64 v21, |v18|, -|v18|
	v_fmamk_f32 v20, v19, 0x3f87dc22, v206
	v_fmaak_f32 v20, v20, v19, 0x3fb5f0e3
	v_exp_f32_e32 v21, v21
	v_fmaak_f32 v20, v20, v19, 0xbe91a98e
	v_fmaak_f32 v20, v20, v19, 0x3e827906
	v_mul_f32_e32 v19, v19, v20
	v_fma_f32 v18, -v21, v19, 1.0
	v_add_f32_e32 v15, v207, v15
	v_mul_f32_e32 v14, 0.5, v14
	v_fma_f32 v14, |v14|, v18, v14
	v_mul_f32_e32 v18, 0x3f596d27, v15
	v_fma_f32 v19, |v18|, s98, 1.0
	v_pk_mul_f32 v[26:27], v[26:27], v[42:43]
	v_add3_u32 v22, s14, v81, v62
	v_mul_f32_e32 v14, v26, v14
	v_cvt_pk_bf16_f32 v14, v14, s0
	ds_write_b16 v22, v14
	v_mul_f32_e32 v14, 0.5, v15
	v_rcp_f32_e32 v15, v19
	v_mul_f32_e64 v20, |v18|, -|v18|
	v_fmamk_f32 v19, v15, 0x3f87dc22, v206
	v_fmaak_f32 v19, v19, v15, 0x3fb5f0e3
	v_exp_f32_e32 v20, v20
	v_fmaak_f32 v19, v19, v15, 0xbe91a98e
	v_fmaak_f32 v19, v19, v15, 0x3e827906
	v_mul_f32_e32 v16, v210, v118
	v_mul_f32_e32 v15, v15, v19
	v_fmac_f32_e32 v16, v208, v121
	v_fma_f32 v15, -v20, v15, 1.0
	v_fmac_f32_e32 v16, v209, v119
	v_add_f32_e32 v16, v207, v16
	v_fma_f32 v14, |v14|, v15, v14
	v_mul_f32_e32 v15, 0x3f596d27, v16
	v_fma_f32 v18, |v15|, s98, 1.0
	v_mul_f32_e32 v14, v27, v14
	v_cvt_pk_bf16_f32 v14, v14, s0
	ds_write_b16 v22, v14 offset:272
	v_mul_f32_e32 v14, 0.5, v16
	v_rcp_f32_e32 v16, v18
	v_mul_f32_e64 v19, |v15|, -|v15|
	v_fmamk_f32 v18, v16, 0x3f87dc22, v206
	v_fmaak_f32 v18, v18, v16, 0x3fb5f0e3
	v_exp_f32_e32 v19, v19
	v_fmaak_f32 v18, v18, v16, 0xbe91a98e
	v_fmaak_f32 v18, v18, v16, 0x3e827906
	v_mul_f32_e32 v17, v210, v119
	v_mul_f32_e32 v16, v16, v18
	v_fmac_f32_e32 v17, v208, v118
	v_fma_f32 v15, -v19, v16, 1.0
	v_fmac_f32_e32 v17, v209, v123
	v_add_f32_e32 v17, v207, v17
	v_fma_f32 v14, |v14|, v15, v14
	v_mul_f32_e32 v15, 0x3f596d27, v17
	v_fma_f32 v16, |v15|, s98, 1.0
	v_pk_mul_f32 v[28:29], v[28:29], v[44:45]
	s_nop 0
	v_mul_f32_e32 v14, v28, v14
	v_cvt_pk_bf16_f32 v14, v14, s0
	ds_write_b16 v22, v14 offset:544
	v_mul_f32_e32 v14, 0.5, v17
	v_rcp_f32_e32 v16, v16
	v_mul_f32_e64 v18, |v15|, -|v15|
	v_fmamk_f32 v17, v16, 0x3f87dc22, v206
	v_fmaak_f32 v17, v17, v16, 0x3fb5f0e3
	v_exp_f32_e32 v18, v18
	v_fmaak_f32 v17, v17, v16, 0xbe91a98e
	v_fmaak_f32 v17, v17, v16, 0x3e827906
	v_mul_f32_e32 v16, v16, v17
	v_fma_f32 v15, -v18, v16, 1.0
	v_fma_f32 v14, |v14|, v15, v14
	v_mul_f32_e32 v14, v29, v14
	v_cvt_pk_bf16_f32 v14, v14, s0
	ds_write_b16 v22, v14 offset:816
	v_mul_f32_e32 v14, v208, v117
	v_fmac_f32_e32 v14, v210, v112
	v_fmac_f32_e32 v14, v209, v113
	v_add_f32_e32 v14, v207, v14
	v_mul_f32_e32 v18, 0x3f596d27, v14
	v_fma_f32 v19, |v18|, s98, 1.0
; __device__ __forceinline__ u16 f2bf(float f) { return (u16)(pack2(f, f) & 0xffffu); }
; __device__ __forceinline__ float erf_f32(float x) {
;   const float ax = fabsf(x);
;   const float t = __frcp_rn(fmaf(0.3275911f, ax, 1.0f));
;   float poly = fmaf(1.061405429f, t, -1.453152027f);
;   poly = fmaf(poly, t, 1.421413741f);
;   poly = fmaf(poly, t, -0.284496736f);
;   poly = fmaf(poly, t, 0.254829592f);
;   const float y = 1.0f - poly * t * __expf(-ax * ax);
;   return copysignf(y, x);
; }
; __device__ __forceinline__ float gelu_exact(float x) { return 0.5f * x * (1.0f + erf_f32(x * 0.70710678118654752f)); }
; template <int EPI>
; __device__ __forceinline__ void phase_gemm(const Params& p, const GemmDesc& d, char* shmc) {
;     ...
; #pragma unroll
;       for (int n = 0; n < 2; ++n) {
;         const int col = ewc * 32 + n * 16 + efr;
;         const int ch = ch0 + col;
;         const float w0 = cw[n][0], w1 = cw[n][1], w2 = cw[n][2], cb = cw[n][3];
; #pragma unroll
;         for (int ai = 0; ai < 2; ++ai)
; #pragma unroll
;           for (int m = 0; m < 4; ++m) {
;             const int s = ai * 32 + ewr * 16 + m * 4 + efq;
;             const f32x4 g = acc[ai][0][m][n];
;             const f32x4 v = acc[ai][1][m][n];
;             const float c0 = w0 * gp[ai][m][n] + w1 * g[0] + w2 * g[1] + cb;
;             const float c1 = w0 * g[0] + w1 * g[1] + w2 * g[2] + cb;
;             const float c2 = w0 * g[1] + w1 * g[2] + w2 * g[3] + cb;
;             const float c3 = w0 * g[2] + w1 * g[3] + w2 * gn[ai][m][n] + cb;
;             u16* sp = stg + (s * 4) * 136 + col;
;             sp[0] = f2bf(gelu_exact(c0) * v[0]);
;             sp[136] = f2bf(gelu_exact(c1) * v[1]);
;             sp[272] = f2bf(gelu_exact(c2) * v[2]);
;             sp[408] = f2bf(gelu_exact(c3) * v[3]);
;             if (s == 0) {
;               edge[0 * DFF + ch] = c0; edge[1 * DFF + ch] = g[0]; edge[2 * DFF + ch] = v[0];
;             }
;             if (s == 63) {
;               edge[3 * DFF + ch] = c3; edge[4 * DFF + ch] = g[3]; edge[5 * DFF + ch] = v[3];
;             }
;           }
	v_mul_f32_e32 v15, v210, v113
	v_fmac_f32_e32 v15, v208, v112
	v_fmac_f32_e32 v15, v209, v110
	v_rcp_f32_e32 v19, v19
	v_mul_f32_e64 v21, |v18|, -|v18|
	v_fmamk_f32 v20, v19, 0x3f87dc22, v206
	v_fmaak_f32 v20, v20, v19, 0x3fb5f0e3
	v_exp_f32_e32 v21, v21
	v_fmaak_f32 v20, v20, v19, 0xbe91a98e
	v_fmaak_f32 v20, v20, v19, 0x3e827906
	v_mul_f32_e32 v19, v19, v20
	v_fma_f32 v18, -v21, v19, 1.0
	v_mul_f32_e32 v14, 0.5, v14
	v_add_f32_e32 v15, v207, v15
	v_fma_f32 v14, |v14|, v18, v14
	v_mul_f32_e32 v12, v12, v14
	v_mul_f32_e32 v14, 0x3f596d27, v15
	v_fma_f32 v18, |v14|, s98, 1.0
	v_add3_u32 v22, s14, v82, v62
	v_cvt_pk_bf16_f32 v12, v12, s0
	ds_write_b16 v22, v12
	v_mul_f32_e32 v12, 0.5, v15
	v_rcp_f32_e32 v15, v18
	v_mul_f32_e64 v19, |v14|, -|v14|
	v_fmamk_f32 v18, v15, 0x3f87dc22, v206
	v_fmaak_f32 v18, v18, v15, 0x3fb5f0e3
	v_exp_f32_e32 v19, v19
	v_fmaak_f32 v18, v18, v15, 0xbe91a98e
	v_fmaak_f32 v18, v18, v15, 0x3e827906
	v_mul_f32_e32 v15, v15, v18
	v_mul_f32_e32 v16, v210, v110
	v_fma_f32 v14, -v19, v15, 1.0
	v_fmac_f32_e32 v16, v208, v113
	v_fmac_f32_e32 v16, v209, v111
	v_add_f32_e32 v16, v207, v16
	v_fma_f32 v12, |v12|, v14, v12
	v_mul_f32_e32 v12, v13, v12
	v_mul_f32_e32 v13, 0x3f596d27, v16
	v_fma_f32 v14, |v13|, s98, 1.0
	v_cvt_pk_bf16_f32 v12, v12, s0
	ds_write_b16 v22, v12 offset:272
	v_mul_f32_e32 v12, 0.5, v16
	v_rcp_f32_e32 v14, v14
	v_mul_f32_e64 v16, |v13|, -|v13|
	v_fmamk_f32 v15, v14, 0x3f87dc22, v206
	v_fmaak_f32 v15, v15, v14, 0x3fb5f0e3
	v_exp_f32_e32 v16, v16
	v_fmaak_f32 v15, v15, v14, 0xbe91a98e
	v_fmaak_f32 v15, v15, v14, 0x3e827906
	v_mul_f32_e32 v14, v14, v15
	v_mul_f32_e32 v17, v210, v111
	v_fma_f32 v13, -v16, v14, 1.0
	v_fmac_f32_e32 v17, v208, v110
	v_fmac_f32_e32 v17, v209, v115
	v_add_f32_e32 v17, v207, v17
	v_fma_f32 v12, |v12|, v13, v12
	v_mul_f32_e32 v10, v10, v12
	v_mul_f32_e32 v12, 0x3f596d27, v17
	v_fma_f32 v13, |v12|, s98, 1.0
	v_cvt_pk_bf16_f32 v10, v10, s0
	ds_write_b16 v22, v10 offset:544
	v_mul_f32_e32 v10, 0.5, v17
	v_rcp_f32_e32 v13, v13
	v_mul_f32_e64 v15, |v12|, -|v12|
	v_fmamk_f32 v14, v13, 0x3f87dc22, v206
	v_fmaak_f32 v14, v14, v13, 0x3fb5f0e3
	v_exp_f32_e32 v15, v15
	v_fmaak_f32 v14, v14, v13, 0xbe91a98e
	v_fmaak_f32 v14, v14, v13, 0x3e827906
	v_mul_f32_e32 v13, v13, v14
	v_fma_f32 v12, -v15, v13, 1.0
	v_fma_f32 v10, |v10|, v12, v10
	v_mul_f32_e32 v10, v11, v10
	v_cvt_pk_bf16_f32 v10, v10, s0
	ds_write_b16 v22, v10 offset:816
	v_mul_f32_e32 v10, v208, v109
	v_fmac_f32_e32 v10, v210, v104
	v_fmac_f32_e32 v10, v209, v105
	v_add_f32_e32 v10, v207, v10
	v_mul_f32_e32 v14, 0x3f596d27, v10
	v_fma_f32 v15, |v14|, s98, 1.0
	v_mul_f32_e32 v11, v210, v105
	v_fmac_f32_e32 v11, v208, v104
	v_fmac_f32_e32 v11, v209, v102
	v_rcp_f32_e32 v15, v15
	v_mul_f32_e64 v17, |v14|, -|v14|
	v_fmamk_f32 v16, v15, 0x3f87dc22, v206
	v_fmaak_f32 v16, v16, v15, 0x3fb5f0e3
	v_exp_f32_e32 v17, v17
	v_fmaak_f32 v16, v16, v15, 0xbe91a98e
	v_fmaak_f32 v16, v16, v15, 0x3e827906
	v_mul_f32_e32 v15, v15, v16
	v_fma_f32 v14, -v17, v15, 1.0
	v_mul_f32_e32 v10, 0.5, v10
	v_add_f32_e32 v11, v207, v11
	v_fma_f32 v10, |v10|, v14, v10
	v_mul_f32_e32 v8, v8, v10
	v_mul_f32_e32 v10, 0x3f596d27, v11
	v_fma_f32 v14, |v10|, s98, 1.0
	v_add3_u32 v18, s14, v74, v62
	v_cvt_pk_bf16_f32 v8, v8, s0
	ds_write_b16 v18, v8
	v_mul_f32_e32 v8, 0.5, v11
	v_rcp_f32_e32 v11, v14
	v_mul_f32_e64 v15, |v10|, -|v10|
	v_fmamk_f32 v14, v11, 0x3f87dc22, v206
	v_fmaak_f32 v14, v14, v11, 0x3fb5f0e3
	v_exp_f32_e32 v15, v15
	v_fmaak_f32 v14, v14, v11, 0xbe91a98e
	v_fmaak_f32 v14, v14, v11, 0x3e827906
	v_mul_f32_e32 v11, v11, v14
	v_mul_f32_e32 v12, v210, v102
	v_fma_f32 v10, -v15, v11, 1.0
	v_fmac_f32_e32 v12, v208, v105
	v_fmac_f32_e32 v12, v209, v103
	v_add_f32_e32 v12, v207, v12
	v_fma_f32 v8, |v8|, v10, v8
	v_mul_f32_e32 v8, v9, v8
	v_mul_f32_e32 v9, 0x3f596d27, v12
	v_fma_f32 v10, |v9|, s98, 1.0
	v_cvt_pk_bf16_f32 v8, v8, s0
	ds_write_b16 v18, v8 offset:272
	v_mul_f32_e32 v8, 0.5, v12
	v_rcp_f32_e32 v10, v10
; __device__ __forceinline__ u16 f2bf(float f) { return (u16)(pack2(f, f) & 0xffffu); }
; __device__ __forceinline__ float erf_f32(float x) {
;   const float ax = fabsf(x);
;   const float t = __frcp_rn(fmaf(0.3275911f, ax, 1.0f));
;   float poly = fmaf(1.061405429f, t, -1.453152027f);
;   poly = fmaf(poly, t, 1.421413741f);
;   poly = fmaf(poly, t, -0.284496736f);
;   poly = fmaf(poly, t, 0.254829592f);
;   const float y = 1.0f - poly * t * __expf(-ax * ax);
;   return copysignf(y, x);
; }
; __device__ __forceinline__ float gelu_exact(float x) { return 0.5f * x * (1.0f + erf_f32(x * 0.70710678118654752f)); }
; template <int EPI>
; __device__ __forceinline__ void phase_gemm(const Params& p, const GemmDesc& d, char* shmc) {
;     ...
; #pragma unroll
;       for (int n = 0; n < 2; ++n) {
;         const int col = ewc * 32 + n * 16 + efr;
;         const int ch = ch0 + col;
;         const float w0 = cw[n][0], w1 = cw[n][1], w2 = cw[n][2], cb = cw[n][3];
; #pragma unroll
;         for (int ai = 0; ai < 2; ++ai)
; #pragma unroll
;           for (int m = 0; m < 4; ++m) {
;             const int s = ai * 32 + ewr * 16 + m * 4 + efq;
;             const f32x4 g = acc[ai][0][m][n];
;             const f32x4 v = acc[ai][1][m][n];
;             const float c0 = w0 * gp[ai][m][n] + w1 * g[0] + w2 * g[1] + cb;
;             const float c1 = w0 * g[0] + w1 * g[1] + w2 * g[2] + cb;
;             const float c2 = w0 * g[1] + w1 * g[2] + w2 * g[3] + cb;
;             const float c3 = w0 * g[2] + w1 * g[3] + w2 * gn[ai][m][n] + cb;
;             u16* sp = stg + (s * 4) * 136 + col;
;             sp[0] = f2bf(gelu_exact(c0) * v[0]);
;             sp[136] = f2bf(gelu_exact(c1) * v[1]);
;             sp[272] = f2bf(gelu_exact(c2) * v[2]);
;             sp[408] = f2bf(gelu_exact(c3) * v[3]);
;             if (s == 0) {
;               edge[0 * DFF + ch] = c0; edge[1 * DFF + ch] = g[0]; edge[2 * DFF + ch] = v[0];
;             }
;             if (s == 63) {
;               edge[3 * DFF + ch] = c3; edge[4 * DFF + ch] = g[3]; edge[5 * DFF + ch] = v[3];
;             }
;           }
	v_mul_f32_e64 v12, |v9|, -|v9|
	v_fmamk_f32 v11, v10, 0x3f87dc22, v206
	v_fmaak_f32 v11, v11, v10, 0x3fb5f0e3
	v_exp_f32_e32 v12, v12
	v_fmaak_f32 v11, v11, v10, 0xbe91a98e
	v_fmaak_f32 v11, v11, v10, 0x3e827906
	v_mul_f32_e32 v10, v10, v11
	v_mul_f32_e32 v13, v210, v103
	v_fma_f32 v9, -v12, v10, 1.0
	v_fmac_f32_e32 v13, v208, v102
	v_fmac_f32_e32 v13, v209, v107
	v_add_f32_e32 v13, v207, v13
	v_fma_f32 v8, |v8|, v9, v8
	v_mul_f32_e32 v6, v6, v8
	v_mul_f32_e32 v8, 0x3f596d27, v13
	v_fma_f32 v9, |v8|, s98, 1.0
	v_cvt_pk_bf16_f32 v6, v6, s0
	ds_write_b16 v18, v6 offset:544
	v_mul_f32_e32 v6, 0.5, v13
	v_rcp_f32_e32 v9, v9
	v_mul_f32_e64 v11, |v8|, -|v8|
	v_fmamk_f32 v10, v9, 0x3f87dc22, v206
	v_fmaak_f32 v10, v10, v9, 0x3fb5f0e3
	v_exp_f32_e32 v11, v11
	v_fmaak_f32 v10, v10, v9, 0xbe91a98e
	v_fmaak_f32 v10, v10, v9, 0x3e827906
	v_mul_f32_e32 v9, v9, v10
	v_fma_f32 v8, -v11, v9, 1.0
	v_fma_f32 v6, |v6|, v8, v6
	v_mul_f32_e32 v6, v7, v6
	v_cvt_pk_bf16_f32 v6, v6, s0
	ds_write_b16 v18, v6 offset:816
	v_mul_f32_e32 v6, v208, v212
	v_fmac_f32_e32 v6, v210, v98
	v_fmac_f32_e32 v6, v209, v99
	v_add_f32_e32 v7, v207, v6
	v_mul_f32_e32 v10, 0x3f596d27, v7
	v_fma_f32 v11, |v10|, s98, 1.0
	v_mul_f32_e32 v6, v210, v99
	v_fmac_f32_e32 v6, v208, v98
	v_fmac_f32_e32 v6, v209, v100
	v_rcp_f32_e32 v11, v11
	v_mul_f32_e64 v13, |v10|, -|v10|
	v_fmamk_f32 v12, v11, 0x3f87dc22, v206
	v_fmaak_f32 v12, v12, v11, 0x3fb5f0e3
	v_exp_f32_e32 v13, v13
	v_fmaak_f32 v12, v12, v11, 0xbe91a98e
	v_fmaak_f32 v12, v12, v11, 0x3e827906
	v_mul_f32_e32 v11, v11, v12
	v_fma_f32 v10, -v13, v11, 1.0
	v_mul_f32_e32 v7, 0.5, v7
	v_add_f32_e32 v8, v207, v6
	v_fma_f32 v7, |v7|, v10, v7
	v_mul_f32_e32 v4, v4, v7
	v_mul_f32_e32 v7, 0x3f596d27, v8
	v_fma_f32 v10, |v7|, s98, 1.0
	v_add3_u32 v14, s14, v70, v62
	v_cvt_pk_bf16_f32 v4, v4, s0
	ds_write_b16 v14, v4
	v_mul_f32_e32 v4, 0.5, v8
	v_rcp_f32_e32 v8, v10
	v_mul_f32_e64 v11, |v7|, -|v7|
	v_fmamk_f32 v10, v8, 0x3f87dc22, v206
	v_fmaak_f32 v10, v10, v8, 0x3fb5f0e3
	v_exp_f32_e32 v11, v11
	v_fmaak_f32 v10, v10, v8, 0xbe91a98e
	v_fmaak_f32 v10, v10, v8, 0x3e827906
	v_mul_f32_e32 v8, v8, v10
	v_mul_f32_e32 v6, v210, v100
	v_fma_f32 v7, -v11, v8, 1.0
	v_fmac_f32_e32 v6, v208, v99
	v_fmac_f32_e32 v6, v209, v101
	v_add_f32_e32 v9, v207, v6
	v_fma_f32 v4, |v4|, v7, v4
	v_mul_f32_e32 v4, v5, v4
	v_mul_f32_e32 v5, 0x3f596d27, v9
	v_fma_f32 v7, |v5|, s98, 1.0
	v_cvt_pk_bf16_f32 v4, v4, s0
	ds_write_b16 v14, v4 offset:272
	v_mul_f32_e32 v4, 0.5, v9
	v_rcp_f32_e32 v7, v7
	v_mul_f32_e64 v9, |v5|, -|v5|
	v_fmamk_f32 v8, v7, 0x3f87dc22, v206
	v_fmaak_f32 v8, v8, v7, 0x3fb5f0e3
	v_exp_f32_e32 v9, v9
	v_fmaak_f32 v8, v8, v7, 0xbe91a98e
	v_fmaak_f32 v8, v8, v7, 0x3e827906
	v_mul_f32_e32 v7, v7, v8
	v_mul_f32_e32 v6, v210, v101
	v_fma_f32 v5, -v9, v7, 1.0
	v_fmac_f32_e32 v6, v208, v100
	v_fmac_f32_e32 v6, v209, v211
	v_add_f32_e32 v6, v207, v6
	v_fma_f32 v4, |v4|, v5, v4
	v_mul_f32_e32 v2, v2, v4
	v_mul_f32_e32 v4, 0x3f596d27, v6
	v_fma_f32 v5, |v4|, s98, 1.0
	v_cvt_pk_bf16_f32 v2, v2, s0
	ds_write_b16 v14, v2 offset:544
	v_mul_f32_e32 v2, 0.5, v6
	v_rcp_f32_e32 v5, v5
	v_mul_f32_e64 v8, |v4|, -|v4|
	v_fmamk_f32 v7, v5, 0x3f87dc22, v206
	v_fmaak_f32 v7, v7, v5, 0x3fb5f0e3
	v_exp_f32_e32 v8, v8
	v_fmaak_f32 v7, v7, v5, 0xbe91a98e
	v_fmaak_f32 v7, v7, v5, 0x3e827906
	v_mul_f32_e32 v5, v5, v7
	v_fma_f32 v4, -v8, v5, 1.0
	v_fma_f32 v2, |v2|, v4, v2
	v_mul_f32_e32 v2, v3, v2
	v_cvt_pk_bf16_f32 v2, v2, s0
	ds_write_b16 v14, v2 offset:816
	s_and_saveexec_b64 s[10:11], s[8:9]
	s_cbranch_execz .LBB0_1146
	v_add_co_u32_e32 v4, vcc, 0x10000, v58
	s_nop 1
	v_addc_co_u32_e32 v5, vcc, 0, v59, vcc
	global_store_dword v[4:5], v6, off offset:2048
	v_add_co_u32_e32 v4, vcc, 0x16000, v58
	s_nop 1
	v_addc_co_u32_e32 v5, vcc, 0, v59, vcc
	global_store_dword v[4:5], v101, off
	v_add_co_u32_e32 v4, vcc, 0x1b000, v58
	s_nop 1
	v_addc_co_u32_e32 v5, vcc, 0, v59, vcc
	global_store_dword v[4:5], v3, off offset:2048
	s_branch .LBB0_1146

; #define WAIT_V(n) asm volatile("s_waitcnt vmcnt(" #n ")" ::: "memory")
; #define BAR __builtin_amdgcn_s_barrier()
; template <int EPI>
; __device__ __forceinline__ void phase_gemm(const Params& p, const GemmDesc& d, char* shmc) {
;     ...
;     f32x4 acc[2][2][4][2];
; #pragma unroll
;     for (int a = 0; a < 2; ++a)
; #pragma unroll
;       for (int b = 0; b < 2; ++b)
; #pragma unroll
;         for (int m = 0; m < 4; ++m)
; #pragma unroll
;           for (int n = 0; n < 2; ++n) acc[a][b][m][n] = f32x4{0.f, 0.f, 0.f, 0.f};
;     bf16x8 At[4][2], B0[2][2], B1[2][2];
;     if constexpr (EPI == EPI_UP || EPI == EPI_QKV) {
;       if (wid == 0)
;         __builtin_amdgcn_global_load_lds((const unsigned*)(p.rstd + brow + lane * 4), (unsigned*)(shmc + 143360), 16, 0, 0);
;     }
;     STAGE_B(SB(0, 0), 0, 0); STAGE_A(SA(0, 0), 0, 0);
;     STAGE_B(SB(0, 1), 1, 0); STAGE_A(SA(0, 1), 1, 0);
;     if (wr == 1) BAR;
;     WAIT_V(4); BAR;
;     STAGE_B(SB(1, 0), 0, 1); STAGE_A(SA(1, 0), 0, 1); STAGE_B(SB(1, 1), 1, 1);
;     WAIT_V(6); BAR;
.LBB0_1311:
	s_or_b64 exec, exec, s[44:45]
	v_mov_b32_e32 v141, v131
	s_waitcnt lgkmcnt(0)
	v_lshl_add_u64 v[2:3], s[42:43], 0, v[140:141]
	v_mov_b32_e32 v143, v131
	s_mov_b32 m0, s53
	v_lshl_add_u64 v[4:5], s[42:43], 0, v[142:143]
	v_lshl_add_u64 v[2:3], v[2:3], 0, s[8:9]
	v_lshl_add_u64 v[6:7], s[38:39], 0, v[140:141]
	v_mov_b32_e32 v10, 0
	v_mov_b32_e32 v11, 0
	v_mov_b32_e32 v12, 0
	v_mov_b32_e32 v13, 0
	v_mov_b32_e32 v14, 0
	v_mov_b32_e32 v15, 0
	v_mov_b32_e32 v16, 0
	v_mov_b32_e32 v17, 0
	v_mov_b32_e32 v18, 0
	v_mov_b32_e32 v19, 0
	v_mov_b32_e32 v20, 0
	v_mov_b32_e32 v21, 0
	v_mov_b32_e32 v22, 0
	v_mov_b32_e32 v23, 0
	v_mov_b32_e32 v24, 0
	v_mov_b32_e32 v25, 0
	v_mov_b32_e32 v26, 0
	v_mov_b32_e32 v27, 0
	v_mov_b32_e32 v28, 0
	v_mov_b32_e32 v29, 0
	v_mov_b32_e32 v30, 0
	v_mov_b32_e32 v31, 0
	v_mov_b32_e32 v32, 0
	v_mov_b32_e32 v33, 0
	v_mov_b32_e32 v34, 0
	v_mov_b32_e32 v35, 0
	v_mov_b32_e32 v36, 0
	v_mov_b32_e32 v37, 0
	v_mov_b32_e32 v38, 0
	v_mov_b32_e32 v39, 0
	v_mov_b32_e32 v40, 0
	v_mov_b32_e32 v41, 0
	v_mov_b32_e32 v42, 0
	v_mov_b32_e32 v43, 0
	v_mov_b32_e32 v44, 0
	v_mov_b32_e32 v45, 0
	v_mov_b32_e32 v46, 0
	v_mov_b32_e32 v47, 0
	v_mov_b32_e32 v48, 0
	v_mov_b32_e32 v49, 0
	v_mov_b32_e32 v50, 0
	v_mov_b32_e32 v51, 0
	v_mov_b32_e32 v52, 0
	v_mov_b32_e32 v53, 0
	v_mov_b32_e32 v54, 0
	v_mov_b32_e32 v55, 0
	v_mov_b32_e32 v56, 0
	v_mov_b32_e32 v57, 0
	v_mov_b32_e32 v70, 0
	v_mov_b32_e32 v71, 0
	v_mov_b32_e32 v72, 0
	v_mov_b32_e32 v73, 0
	v_mov_b32_e32 v86, 0
	v_mov_b32_e32 v87, 0
	v_mov_b32_e32 v88, 0
	v_mov_b32_e32 v89, 0
	v_mov_b32_e32 v98, 0
	v_mov_b32_e32 v99, 0
	v_mov_b32_e32 v100, 0
	v_mov_b32_e32 v101, 0
	v_mov_b32_e32 v102, 0
	v_mov_b32_e32 v103, 0
	v_mov_b32_e32 v104, 0
	v_mov_b32_e32 v105, 0
	v_mov_b32_e32 v106, 0
	v_mov_b32_e32 v107, 0
	v_mov_b32_e32 v108, 0
	v_mov_b32_e32 v109, 0
	v_mov_b32_e32 v110, 0
	v_mov_b32_e32 v111, 0
	v_mov_b32_e32 v112, 0
	v_mov_b32_e32 v113, 0
	v_mov_b32_e32 v114, 0
	v_mov_b32_e32 v115, 0
	v_mov_b32_e32 v116, 0
	v_mov_b32_e32 v117, 0
	v_mov_b32_e32 v118, 0
	v_mov_b32_e32 v119, 0
	v_mov_b32_e32 v120, 0
	v_mov_b32_e32 v121, 0
	v_mov_b32_e32 v122, 0
	v_mov_b32_e32 v123, 0
	v_mov_b32_e32 v124, 0
	v_mov_b32_e32 v125, 0
	v_mov_b32_e32 v126, 0
	v_mov_b32_e32 v127, 0
	v_mov_b32_e32 v128, 0
	v_mov_b32_e32 v129, 0
	v_mov_b32_e32 v58, 0
	v_mov_b32_e32 v59, 0
	v_mov_b32_e32 v60, 0
	v_mov_b32_e32 v61, 0
	v_mov_b32_e32 v62, 0
	v_mov_b32_e32 v63, 0
	v_mov_b32_e32 v64, 0
	v_mov_b32_e32 v65, 0
	v_mov_b32_e32 v66, 0
	v_mov_b32_e32 v67, 0
	v_mov_b32_e32 v68, 0
	v_mov_b32_e32 v69, 0
	v_mov_b32_e32 v74, 0
	v_mov_b32_e32 v75, 0
	v_mov_b32_e32 v76, 0
	v_mov_b32_e32 v77, 0
	v_mov_b32_e32 v78, 0
	v_mov_b32_e32 v79, 0
	v_mov_b32_e32 v80, 0
	v_mov_b32_e32 v81, 0
	v_mov_b32_e32 v82, 0
	v_mov_b32_e32 v83, 0
	v_mov_b32_e32 v84, 0
	v_mov_b32_e32 v85, 0
	v_mov_b32_e32 v90, 0
	v_mov_b32_e32 v91, 0
	v_mov_b32_e32 v92, 0
	v_mov_b32_e32 v93, 0
	v_mov_b32_e32 v94, 0
	v_mov_b32_e32 v95, 0
	v_mov_b32_e32 v96, 0
	v_mov_b32_e32 v97, 0
	s_waitcnt vmcnt(2)
	s_barrier
	global_load_lds_dwordx4 v[2:3], off
	v_lshl_add_u64 v[2:3], v[4:5], 0, s[8:9]
	s_mov_b32 m0, s54
	v_lshl_add_u64 v[8:9], s[38:39], 0, v[142:143]
	global_load_lds_dwordx4 v[2:3], off
	v_lshl_add_u64 v[2:3], v[6:7], 0, s[8:9]
	s_mov_b32 m0, s55
	s_add_u32 s42, s42, 0x160080
	global_load_lds_dwordx4 v[2:3], off
	v_lshl_add_u64 v[2:3], v[8:9], 0, s[8:9]
	s_mov_b32 m0, s56
	s_addc_u32 s43, s43, 0
	global_load_lds_dwordx4 v[2:3], off
	s_mov_b32 m0, s57
	s_add_i32 s64, s64, s65
	global_load_lds_dwordx4 v140, s[42:43]
	s_mov_b32 m0, s58
	v_lshl_add_u64 v[144:145], v[132:133], 0, s[40:41]
	global_load_lds_dwordx4 v142, s[42:43]
	s_waitcnt vmcnt(6)
	v_lshl_add_u64 v[146:147], v[134:135], 0, s[40:41]
	v_mad_i64_i32 v[148:149], s[40:41], s64, v154, v[136:137]
	v_mad_i64_i32 v[150:151], s[40:41], s64, v154, v[138:139]
	v_mov_b32_e32 v2, 0
	s_mov_b32 s42, -2
	s_mov_b64 s[40:41], 0
	v_mov_b32_e32 v3, v2
	v_mov_b32_e32 v4, v2
	v_mov_b32_e32 v5, v2
	v_mov_b32_e32 v6, v2
	v_mov_b32_e32 v7, v2
	v_mov_b32_e32 v8, v2
	v_mov_b32_e32 v9, v2
	s_barrier

; __global__ void __launch_bounds__(NTHREADS, 2) fwd_megakernel(Params p) {
;   extern __shared__ __attribute__((aligned(16))) char shm[];
;   cg::grid_group grid = cg::this_grid();
	.amdhsa_kernel _Z14fwd_megakernel6Params
		.amdhsa_group_segment_fixed_size 0
		.amdhsa_private_segment_fixed_size 0
		.amdhsa_kernarg_size 488
		.amdhsa_user_sgpr_count 2
		.amdhsa_user_sgpr_dispatch_ptr 0
		.amdhsa_user_sgpr_queue_ptr 0
		.amdhsa_user_sgpr_kernarg_segment_ptr 1
		.amdhsa_user_sgpr_dispatch_id 0
		.amdhsa_user_sgpr_kernarg_preload_length 0
		.amdhsa_user_sgpr_kernarg_preload_offset 0
		.amdhsa_user_sgpr_private_segment_size 0
		.amdhsa_uses_dynamic_stack 0
		.amdhsa_enable_private_segment 0
		.amdhsa_system_sgpr_workgroup_id_x 1
		.amdhsa_system_sgpr_workgroup_id_y 0
		.amdhsa_system_sgpr_workgroup_id_z 0
		.amdhsa_system_sgpr_workgroup_info 0
		.amdhsa_system_vgpr_workitem_id 2
		.amdhsa_next_free_vgpr 247
		.amdhsa_next_free_sgpr 102
		.amdhsa_accum_offset 248
		.amdhsa_reserve_vcc 1
		.amdhsa_float_round_mode_32 0
		.amdhsa_float_round_mode_16_64 0
		.amdhsa_float_denorm_mode_32 3
		.amdhsa_float_denorm_mode_16_64 3
		.amdhsa_dx10_clamp 1
		.amdhsa_ieee_mode 1
		.amdhsa_fp16_overflow 0
		.amdhsa_tg_split 0
		.amdhsa_exception_fp_ieee_invalid_op 0
		.amdhsa_exception_fp_denorm_src 0
		.amdhsa_exception_fp_ieee_div_zero 0
		.amdhsa_exception_fp_ieee_overflow 0
		.amdhsa_exception_fp_ieee_underflow 0
		.amdhsa_exception_fp_ieee_inexact 0
		.amdhsa_exception_int_div_zero 0
	.end_amdhsa_kernel

; __global__ void __launch_bounds__(NTHREADS, 2) fwd_megakernel(Params p) {
;   extern __shared__ __attribute__((aligned(16))) char shm[];
;   cg::grid_group grid = cg::this_grid();
amdhsa.kernels:
  - .agpr_count:     0
    .args:
      - .offset:         0
        .size:           232
        .value_kind:     by_value
      - .offset:         232
        .size:           4
        .value_kind:     hidden_block_count_x
      - .offset:         236
        .size:           4
        .value_kind:     hidden_block_count_y
      - .offset:         240
        .size:           4
        .value_kind:     hidden_block_count_z
      - .offset:         244
        .size:           2
        .value_kind:     hidden_group_size_x
      - .offset:         246
        .size:           2
        .value_kind:     hidden_group_size_y
      - .offset:         248
        .size:           2
        .value_kind:     hidden_group_size_z
      - .offset:         250
        .size:           2
        .value_kind:     hidden_remainder_x
      - .offset:         252
        .size:           2
        .value_kind:     hidden_remainder_y
      - .offset:         254
        .size:           2
        .value_kind:     hidden_remainder_z
      - .offset:         272
        .size:           8
        .value_kind:     hidden_global_offset_x
      - .offset:         280
        .size:           8
        .value_kind:     hidden_global_offset_y
      - .offset:         288
        .size:           8
        .value_kind:     hidden_global_offset_z
      - .offset:         296
        .size:           2
        .value_kind:     hidden_grid_dims
      - .offset:         320
        .size:           8
        .value_kind:     hidden_multigrid_sync_arg
      - .offset:         352
        .size:           4
        .value_kind:     hidden_dynamic_lds_size
    .group_segment_fixed_size: 0
    .kernarg_segment_align: 8
    .kernarg_segment_size: 488
    .language:       OpenCL C
    .language_version:
      - 2
      - 0
    .max_flat_workgroup_size: 512
    .name:           _Z14fwd_megakernel6Params
    .private_segment_fixed_size: 0
    .sgpr_count:     108
    .sgpr_spill_count: 34
    .symbol:         _Z14fwd_megakernel6Params.kd
    .uniform_work_group_size: 1
    .uses_dynamic_stack: false
    .vgpr_count:     247
    .vgpr_spill_count: 0
    .wavefront_size: 64
